# LayerNorm phases: all row loads issued up front with counted per-row vmcnt waits; gain/bias staged in LDS instead of serialized global loads
# baseline (speedup 1.0000x reference)
.LBB0_1958:
	s_andn2_b64 vcc, exec, s[8:9]
	s_cbranch_vccnz .LBB0_2034
	s_mov_b32 s0, s80
	s_mov_b32 s2, -1
	s_mov_b64 s[8:9], s[96:97]
	v_mbcnt_lo_u32_b32 v0, s2, 0
	v_mbcnt_hi_u32_b32 v0, s2, v0
	s_add_i32 s2, s0, s67
	s_mov_b64 s[12:13], s[96:97]
	s_mov_b64 s[16:17], s[96:97]
	s_mov_b64 s[20:21], s[96:97]
	s_mov_b64 s[18:19], s[96:97]
	s_cmpk_gt_i32 s2, 0x7ff
	s_cbranch_scc1 .LBB0_1978
	s_load_dwordx2 s[20:21], s[20:21], 0x110
	s_nop 0
	s_load_dwordx2 s[8:9], s[8:9], 0x110
	s_nop 0
	s_load_dwordx2 s[22:23], s[12:13], 0x10
	s_nop 0
	s_load_dwordx2 s[16:17], s[16:17], 0x18
	s_nop 0
	s_load_dwordx2 s[18:19], s[18:19], 0x110
	s_waitcnt lgkmcnt(0)
	s_add_u32 s12, s20, 0x900000
	s_addc_u32 s13, s21, 0
	s_lshl_b32 s10, s48, 12
	s_lshl_b64 s[26:27], s[10:11], 2
	s_add_u32 s16, s16, s26
	s_addc_u32 s17, s17, s27
	s_add_u32 s22, s22, s26
	s_addc_u32 s23, s23, s27
	s_lshl_b32 s36, s2, 3
	v_lshlrev_b32_e32 v2, 3, v0
	s_cmp_lg_u64 s[20:21], 0
	v_ashrrev_i32_e32 v3, 31, v2
	s_cselect_b64 s[2:3], -1, 0
	v_cmp_eq_u32_e32 vcc, 0, v0
	v_lshlrev_b64 v[4:5], 2, v[2:3]
	s_and_b64 s[42:43], vcc, s[2:3]
	s_lshl_b32 s100, s80, 10
	v_lshl_add_u32 v194, v0, 4, s100
	global_load_dwordx4 v[196:199], v194, s[22:23]
	global_load_dwordx4 v[200:203], v194, s[16:17]
	v_lshlrev_b32_e32 v195, 5, v0
	s_waitcnt vmcnt(0)
	ds_write_b128 v194, v[196:199]
	ds_write_b128 v194, v[200:203] offset:8192
	s_waitcnt lgkmcnt(0)
	s_barrier
	v_lshl_add_u64 v[116:117], s[22:23], 0, v[4:5]
	v_lshl_add_u64 v[118:119], s[16:17], 0, v[4:5]
	s_mov_b64 s[2:3], 0x1000
	v_ashrrev_i32_e32 v1, 31, v0
	v_lshl_add_u64 v[120:121], v[116:117], 0, s[2:3]
	v_lshl_add_u64 v[122:123], v[118:119], 0, s[2:3]
	s_mov_b64 s[2:3], 0x1800
	s_lshl_b32 s0, s0, 4
	s_ashr_i32 s37, s36, 31
	v_lshl_add_u64 v[124:125], v[116:117], 0, s[2:3]
	v_lshl_add_u64 v[126:127], v[118:119], 0, s[2:3]
	s_add_i32 s44, s88, s0
	s_lshl_b64 s[46:47], s[36:37], 12
	v_lshl_add_u64 v[128:129], v[2:3], 1, s[18:19]
	v_lshl_add_u64 v[130:131], v[0:1], 4, s[8:9]
	s_branch .LBB0_1962
.LBB0_1961:
	s_or_b64 exec, exec, s[8:9]
	s_nop 0
	ds_read_b128 v[36:39], v195 offset:16
	ds_read_b128 v[40:43], v195 offset:0
	ds_read_b128 v[44:47], v195 offset:8192
	ds_read_b128 v[48:51], v195 offset:8208
	v_pk_mul_f32 v[24:25], v[24:25], v[34:35] op_sel_hi:[1,0]
	v_pk_mul_f32 v[28:29], v[30:31], v[34:35] op_sel_hi:[1,0]
	v_pk_mul_f32 v[26:27], v[26:27], v[34:35] op_sel_hi:[1,0]
	v_pk_mul_f32 v[30:31], v[32:33], v[34:35] op_sel_hi:[1,0]
	s_mov_b32 s0, 0x16b07000
	v_add_co_u32_e32 v32, vcc, s0, v112
	v_pk_mul_f32 v[12:13], v[12:13], v[34:35] op_sel_hi:[1,0]
	s_nop 0
	v_addc_co_u32_e32 v33, vcc, 0, v113, vcc
	v_pk_mul_f32 v[20:21], v[20:21], v[34:35] op_sel_hi:[1,0]
	v_pk_mul_f32 v[14:15], v[14:15], v[34:35] op_sel_hi:[1,0]
	v_pk_mul_f32 v[22:23], v[22:23], v[34:35] op_sel_hi:[1,0]
	v_pk_mul_f32 v[4:5], v[4:5], v[34:35] op_sel_hi:[1,0]
	v_pk_mul_f32 v[16:17], v[16:17], v[34:35] op_sel_hi:[1,0]
	v_pk_mul_f32 v[6:7], v[6:7], v[34:35] op_sel_hi:[1,0]
	v_pk_mul_f32 v[18:19], v[18:19], v[34:35] op_sel_hi:[1,0]
	v_pk_mul_f32 v[0:1], v[0:1], v[34:35] op_sel_hi:[1,0]
	v_pk_mul_f32 v[8:9], v[8:9], v[34:35] op_sel_hi:[1,0]
	v_pk_mul_f32 v[2:3], v[2:3], v[34:35] op_sel_hi:[1,0]
	v_pk_mul_f32 v[10:11], v[10:11], v[34:35] op_sel_hi:[1,0]
	v_readlane_b32 s2, v253, 6
	s_add_i32 s36, s36, s64
	s_add_i32 s44, s44, s86
	v_readlane_b32 s3, v253, 7
	s_cmpk_lt_i32 s36, 0x4000
	s_waitcnt lgkmcnt(1)
	v_pk_fma_f32 v[24:25], v[24:25], v[40:41], v[44:45]
	s_waitcnt lgkmcnt(0)
	v_pk_fma_f32 v[28:29], v[28:29], v[36:37], v[48:49]
	v_pk_fma_f32 v[26:27], v[26:27], v[42:43], v[46:47]
	v_pk_fma_f32 v[30:31], v[30:31], v[38:39], v[50:51]
	v_cvt_pk_bf16_f32 v24, v24, v25
	v_cvt_pk_bf16_f32 v25, v26, v27
	v_cvt_pk_bf16_f32 v26, v28, v29
	v_cvt_pk_bf16_f32 v27, v30, v31
	global_store_dwordx4 v[32:33], v[24:27], off
	s_nop 0
	ds_read_b128 v[24:27], v195 offset:2064
	s_nop 0
	ds_read_b128 v[28:31], v195 offset:2048
	ds_read_b128 v[36:39], v195 offset:10240
	ds_read_b128 v[40:43], v195 offset:10256
	v_lshl_add_u64 v[128:129], v[128:129], 0, s[2:3]
	v_lshl_add_u64 v[130:131], v[130:131], 0, s[2:3]
	s_waitcnt lgkmcnt(1)
	v_pk_fma_f32 v[12:13], v[12:13], v[28:29], v[36:37]
	s_waitcnt lgkmcnt(0)
	v_pk_fma_f32 v[20:21], v[20:21], v[24:25], v[40:41]
	v_pk_fma_f32 v[14:15], v[14:15], v[30:31], v[38:39]
	v_pk_fma_f32 v[22:23], v[22:23], v[26:27], v[42:43]
	v_cvt_pk_bf16_f32 v12, v12, v13
	v_cvt_pk_bf16_f32 v13, v14, v15
	v_cvt_pk_bf16_f32 v14, v20, v21
	v_cvt_pk_bf16_f32 v15, v22, v23
	global_store_dwordx4 v[32:33], v[12:15], off offset:1024
	s_nop 0
	ds_read_b128 v[12:15], v195 offset:4112
	s_nop 0
	ds_read_b128 v[20:23], v195 offset:4096
	ds_read_b128 v[24:27], v195 offset:12288
	ds_read_b128 v[28:31], v195 offset:12304
	s_waitcnt lgkmcnt(1)
	v_pk_fma_f32 v[4:5], v[4:5], v[20:21], v[24:25]
	s_waitcnt lgkmcnt(0)
	v_pk_fma_f32 v[12:13], v[16:17], v[12:13], v[28:29]
	v_pk_fma_f32 v[6:7], v[6:7], v[22:23], v[26:27]
	v_pk_fma_f32 v[14:15], v[18:19], v[14:15], v[30:31]
	v_cvt_pk_bf16_f32 v4, v4, v5
	v_cvt_pk_bf16_f32 v5, v6, v7
	v_cvt_pk_bf16_f32 v6, v12, v13
	v_cvt_pk_bf16_f32 v7, v14, v15
	global_store_dwordx4 v[32:33], v[4:7], off offset:2048
	s_nop 0
	ds_read_b128 v[4:7], v195 offset:6160
	s_nop 0
	ds_read_b128 v[12:15], v195 offset:6144
	ds_read_b128 v[16:19], v195 offset:14336
	ds_read_b128 v[20:23], v195 offset:14352
	s_waitcnt lgkmcnt(1)
	v_pk_fma_f32 v[0:1], v[0:1], v[12:13], v[16:17]
	s_waitcnt lgkmcnt(0)
	v_pk_fma_f32 v[4:5], v[8:9], v[4:5], v[20:21]
	v_pk_fma_f32 v[2:3], v[2:3], v[14:15], v[18:19]
	v_pk_fma_f32 v[6:7], v[10:11], v[6:7], v[22:23]
	v_cvt_pk_bf16_f32 v0, v0, v1
	v_cvt_pk_bf16_f32 v1, v2, v3
	v_cvt_pk_bf16_f32 v2, v4, v5
	v_cvt_pk_bf16_f32 v3, v6, v7
	global_store_dwordx4 v[32:33], v[0:3], off offset:3072
	s_cbranch_scc0 .LBB0_1978
.LBB0_1962:
	s_nop 0
	v_lshl_add_u64 v[0:1], v[130:131], 0, s[46:47]
	v_add_co_u32_e32 v2, vcc, 0x12b00000, v0
	s_nop 1
	v_addc_co_u32_e32 v3, vcc, 0, v1, vcc
	global_load_dwordx4 v[132:135], v[2:3], off
	global_load_dwordx4 v[136:139], v[2:3], off offset:1024
	global_load_dwordx4 v[140:143], v[2:3], off offset:2048
	global_load_dwordx4 v[112:115], v[2:3], off offset:3072
	v_add_co_u32_e32 v4, vcc, 0x12b01000, v0
	s_nop 1
	v_addc_co_u32_e32 v5, vcc, 0, v1, vcc
	v_add_co_u32_e32 v2, vcc, 0x12b02000, v0
	s_nop 1
	v_addc_co_u32_e32 v3, vcc, 0, v1, vcc
	global_load_dwordx4 v[108:111], v[4:5], off
	global_load_dwordx4 v[104:107], v[4:5], off offset:1024
	global_load_dwordx4 v[100:103], v[4:5], off offset:2048
	global_load_dwordx4 v[96:99], v[4:5], off offset:3072
	v_add_co_u32_e32 v4, vcc, 0x12b03000, v0
	s_nop 1
	v_addc_co_u32_e32 v5, vcc, 0, v1, vcc
	global_load_dwordx4 v[92:95], v[2:3], off
	global_load_dwordx4 v[88:91], v[2:3], off offset:1024
	global_load_dwordx4 v[84:87], v[2:3], off offset:2048
	global_load_dwordx4 v[80:83], v[2:3], off offset:3072
	v_add_co_u32_e32 v2, vcc, 0x12b04000, v0
	s_nop 1
	v_addc_co_u32_e32 v3, vcc, 0, v1, vcc
	global_load_dwordx4 v[76:79], v[4:5], off
	global_load_dwordx4 v[72:75], v[4:5], off offset:1024
	global_load_dwordx4 v[68:71], v[4:5], off offset:2048
	global_load_dwordx4 v[64:67], v[4:5], off offset:3072
	v_add_co_u32_e32 v4, vcc, 0x12b05000, v0
	s_nop 1
	v_addc_co_u32_e32 v5, vcc, 0, v1, vcc
	global_load_dwordx4 v[60:63], v[2:3], off
	global_load_dwordx4 v[56:59], v[2:3], off offset:1024
	global_load_dwordx4 v[52:55], v[2:3], off offset:2048
	global_load_dwordx4 v[48:51], v[2:3], off offset:3072
	v_add_co_u32_e32 v2, vcc, 0x12b06000, v0
	s_nop 1
	v_addc_co_u32_e32 v3, vcc, 0, v1, vcc
	v_add_co_u32_e32 v0, vcc, 0x12b07000, v0
	s_nop 1
	v_addc_co_u32_e32 v1, vcc, 0, v1, vcc
	global_load_dwordx4 v[44:47], v[4:5], off
	global_load_dwordx4 v[40:43], v[4:5], off offset:1024
	global_load_dwordx4 v[36:39], v[4:5], off offset:2048
	global_load_dwordx4 v[32:35], v[4:5], off offset:3072
	global_load_dwordx4 v[28:31], v[2:3], off
	global_load_dwordx4 v[24:27], v[2:3], off offset:1024
	global_load_dwordx4 v[20:23], v[2:3], off offset:2048
	global_load_dwordx4 v[16:19], v[2:3], off offset:3072
	global_load_dwordx4 v[12:15], v[0:1], off
	global_load_dwordx4 v[8:11], v[0:1], off offset:1024
	global_load_dwordx4 v[4:7], v[0:1], off offset:2048
	global_load_dwordx4 v[0:3], v[0:1], off offset:3072
	s_waitcnt vmcnt(28)
	v_cvt_f32_f16_e32 v148, v134
	v_cvt_f32_f16_sdwa v149, v134 dst_sel:DWORD dst_unused:UNUSED_PAD src0_sel:WORD_1
	v_cvt_f32_f16_e32 v134, v132
	v_cvt_f32_f16_e32 v144, v135
	v_cvt_f32_f16_sdwa v145, v135 dst_sel:DWORD dst_unused:UNUSED_PAD src0_sel:WORD_1
	v_cvt_f32_f16_sdwa v135, v132 dst_sel:DWORD dst_unused:UNUSED_PAD src0_sel:WORD_1
	v_cvt_f32_f16_e32 v146, v133
	v_cvt_f32_f16_sdwa v147, v133 dst_sel:DWORD dst_unused:UNUSED_PAD src0_sel:WORD_1
	v_cvt_f32_f16_e32 v152, v136
	v_cvt_f32_f16_sdwa v153, v136 dst_sel:DWORD dst_unused:UNUSED_PAD src0_sel:WORD_1
	v_add_f32_e32 v136, 0, v134
	v_add_f32_e32 v136, v136, v135
	v_add_f32_e32 v136, v136, v146
	v_add_f32_e32 v136, v136, v147
	v_add_f32_e32 v136, v136, v148
	v_add_f32_e32 v136, v136, v149
	v_cvt_f32_f16_e32 v150, v137
	v_add_f32_e32 v136, v136, v144
	v_cvt_f32_f16_e32 v132, v139
	v_cvt_f32_f16_sdwa v133, v139 dst_sel:DWORD dst_unused:UNUSED_PAD src0_sel:WORD_1
	v_cvt_f32_f16_sdwa v151, v137 dst_sel:DWORD dst_unused:UNUSED_PAD src0_sel:WORD_1
	v_add_f32_e32 v139, v136, v145
	v_cvt_f32_f16_e32 v136, v138
	v_cvt_f32_f16_sdwa v137, v138 dst_sel:DWORD dst_unused:UNUSED_PAD src0_sel:WORD_1
	v_add_f32_e32 v138, v139, v152
	v_add_f32_e32 v138, v138, v153
	v_add_f32_e32 v138, v138, v150
	v_add_f32_e32 v138, v138, v151
	v_add_f32_e32 v138, v138, v136
	v_add_f32_e32 v138, v138, v137
	v_cvt_f32_f16_e32 v166, v140
	v_add_f32_e32 v138, v138, v132
	v_cvt_f32_f16_sdwa v167, v140 dst_sel:DWORD dst_unused:UNUSED_PAD src0_sel:WORD_1
	v_add_f32_e32 v154, v138, v133
	v_cvt_f32_f16_e32 v138, v141
	v_cvt_f32_f16_sdwa v139, v141 dst_sel:DWORD dst_unused:UNUSED_PAD src0_sel:WORD_1
	v_cvt_f32_f16_e32 v140, v142
	v_cvt_f32_f16_sdwa v141, v142 dst_sel:DWORD dst_unused:UNUSED_PAD src0_sel:WORD_1
	v_add_f32_e32 v142, v154, v166
	v_add_f32_e32 v142, v142, v167
	v_cvt_f32_f16_e32 v164, v143
	v_add_f32_e32 v142, v142, v138
	v_cvt_f32_f16_sdwa v165, v143 dst_sel:DWORD dst_unused:UNUSED_PAD src0_sel:WORD_1
	v_add_f32_e32 v142, v142, v139
	v_add_f32_e32 v142, v142, v140
	v_cvt_f32_f16_e32 v172, v112
	v_add_f32_e32 v142, v142, v141
	v_cvt_f32_f16_sdwa v173, v112 dst_sel:DWORD dst_unused:UNUSED_PAD src0_sel:WORD_1
	v_add_f32_e32 v142, v142, v164
	v_cvt_f32_f16_e32 v170, v113
	v_add_f32_e32 v142, v142, v165
	v_cvt_f32_f16_sdwa v171, v113 dst_sel:DWORD dst_unused:UNUSED_PAD src0_sel:WORD_1
	v_cvt_f32_f16_e32 v174, v114
	v_add_f32_e32 v112, v142, v172
	v_cvt_f32_f16_sdwa v175, v114 dst_sel:DWORD dst_unused:UNUSED_PAD src0_sel:WORD_1
	v_add_f32_e32 v112, v112, v173
	v_cvt_f32_f16_e32 v168, v115
	v_add_f32_e32 v112, v112, v170
	v_cvt_f32_f16_sdwa v169, v115 dst_sel:DWORD dst_unused:UNUSED_PAD src0_sel:WORD_1
	v_add_f32_e32 v112, v112, v171
	v_add_f32_e32 v112, v112, v174
	v_add_f32_e32 v112, v112, v175
	v_add_f32_e32 v112, v112, v168
	v_add_f32_e32 v112, v112, v169
	s_nop 1
	v_add_f32_dpp v112, v112, v112 quad_perm:[1,0,3,2] row_mask:0xf bank_mask:0xf bound_ctrl:1
	s_nop 1
	v_add_f32_dpp v112, v112, v112 quad_perm:[2,3,0,1] row_mask:0xf bank_mask:0xf bound_ctrl:1
	s_nop 1
	v_add_f32_dpp v112, v112, v112 row_half_mirror row_mask:0xf bank_mask:0xf bound_ctrl:1
	s_nop 1
	v_add_f32_dpp v112, v112, v112 row_mirror row_mask:0xf bank_mask:0xf bound_ctrl:1
	s_nop 0
	v_readlane_b32 s0, v112, 16
	v_readlane_b32 s7, v112, 48
	v_readlane_b32 s2, v112, 0
	v_readlane_b32 s3, v112, 32
	v_mov_b32_e32 v112, s0
	v_mov_b32_e32 v113, s7
	v_pk_add_f32 v[112:113], s[2:3], v[112:113]
	s_nop 0
	v_add_f32_e32 v112, v112, v113
	v_mul_f32_e32 v162, 0x3a000000, v112
	v_pk_add_f32 v[158:159], v[134:135], v[162:163] op_sel_hi:[1,0] neg_lo:[0,1] neg_hi:[0,1]
	v_pk_add_f32 v[112:113], v[146:147], v[162:163] op_sel_hi:[1,0] neg_lo:[0,1] neg_hi:[0,1]
	v_pk_mul_f32 v[176:177], v[158:159], v[158:159]
	v_pk_mul_f32 v[146:147], v[112:113], v[112:113]
	v_pk_add_f32 v[160:161], v[148:149], v[162:163] op_sel_hi:[1,0] neg_lo:[0,1] neg_hi:[0,1]
	v_pk_add_f32 v[156:157], v[144:145], v[162:163] op_sel_hi:[1,0] neg_lo:[0,1] neg_hi:[0,1]
	v_pk_add_f32 v[152:153], v[152:153], v[162:163] op_sel_hi:[1,0] neg_lo:[0,1] neg_hi:[0,1]
	v_pk_add_f32 v[148:149], v[150:151], v[162:163] op_sel_hi:[1,0] neg_lo:[0,1] neg_hi:[0,1]
	v_pk_add_f32 v[154:155], v[136:137], v[162:163] op_sel_hi:[1,0] neg_lo:[0,1] neg_hi:[0,1]
	v_pk_add_f32 v[150:151], v[132:133], v[162:163] op_sel_hi:[1,0] neg_lo:[0,1] neg_hi:[0,1]
	v_pk_add_f32 v[142:143], v[166:167], v[162:163] op_sel_hi:[1,0] neg_lo:[0,1] neg_hi:[0,1]
	v_pk_add_f32 v[138:139], v[138:139], v[162:163] op_sel_hi:[1,0] neg_lo:[0,1] neg_hi:[0,1]
	v_pk_add_f32 v[144:145], v[140:141], v[162:163] op_sel_hi:[1,0] neg_lo:[0,1] neg_hi:[0,1]
	v_pk_add_f32 v[140:141], v[164:165], v[162:163] op_sel_hi:[1,0] neg_lo:[0,1] neg_hi:[0,1]
	v_pk_add_f32 v[132:133], v[172:173], v[162:163] op_sel_hi:[1,0] neg_lo:[0,1] neg_hi:[0,1]
	v_pk_add_f32 v[114:115], v[170:171], v[162:163] op_sel_hi:[1,0] neg_lo:[0,1] neg_hi:[0,1]
	v_pk_add_f32 v[136:137], v[174:175], v[162:163] op_sel_hi:[1,0] neg_lo:[0,1] neg_hi:[0,1]
	v_pk_add_f32 v[134:135], v[168:169], v[162:163] op_sel_hi:[1,0] neg_lo:[0,1] neg_hi:[0,1]
	v_add_f32_e32 v163, v176, v177
	v_add_f32_e32 v146, v146, v163
	v_pk_mul_f32 v[178:179], v[160:161], v[160:161]
	v_add_f32_e32 v146, v147, v146
	v_add_f32_e32 v146, v178, v146
	v_pk_mul_f32 v[180:181], v[156:157], v[156:157]
	v_add_f32_e32 v146, v179, v146
	v_add_f32_e32 v146, v180, v146
	v_pk_mul_f32 v[182:183], v[152:153], v[152:153]
	v_add_f32_e32 v146, v181, v146
	v_add_f32_e32 v146, v182, v146
	v_pk_mul_f32 v[184:185], v[148:149], v[148:149]
	v_add_f32_e32 v146, v183, v146
	v_add_f32_e32 v146, v184, v146
	v_pk_mul_f32 v[186:187], v[154:155], v[154:155]
	v_add_f32_e32 v146, v185, v146
	v_add_f32_e32 v146, v186, v146
	v_pk_mul_f32 v[188:189], v[150:151], v[150:151]
	v_add_f32_e32 v146, v187, v146
	v_add_f32_e32 v146, v188, v146
	v_pk_mul_f32 v[166:167], v[142:143], v[142:143]
	v_add_f32_e32 v146, v189, v146
	v_add_f32_e32 v146, v166, v146
	v_pk_mul_f32 v[190:191], v[138:139], v[138:139]
	v_add_f32_e32 v146, v167, v146
	v_add_f32_e32 v146, v190, v146
	v_pk_mul_f32 v[192:193], v[144:145], v[144:145]
	v_add_f32_e32 v146, v191, v146
	v_add_f32_e32 v146, v192, v146
	v_pk_mul_f32 v[164:165], v[140:141], v[140:141]
	v_add_f32_e32 v146, v193, v146
	v_add_f32_e32 v146, v164, v146
	v_pk_mul_f32 v[172:173], v[132:133], v[132:133]
	v_add_f32_e32 v146, v165, v146
	v_add_f32_e32 v146, v172, v146
	v_pk_mul_f32 v[170:171], v[114:115], v[114:115]
	v_add_f32_e32 v146, v173, v146
	v_add_f32_e32 v146, v170, v146
	v_pk_mul_f32 v[174:175], v[136:137], v[136:137]
	v_add_f32_e32 v146, v171, v146
	v_add_f32_e32 v146, v174, v146
	v_pk_mul_f32 v[168:169], v[134:135], v[134:135]
	v_add_f32_e32 v146, v175, v146
	v_add_f32_e32 v146, v168, v146
	v_add_f32_e32 v146, v169, v146
	s_nop 1
	v_add_f32_dpp v146, v146, v146 quad_perm:[1,0,3,2] row_mask:0xf bank_mask:0xf bound_ctrl:1
	s_nop 1
	v_add_f32_dpp v146, v146, v146 quad_perm:[2,3,0,1] row_mask:0xf bank_mask:0xf bound_ctrl:1
	s_nop 1
	v_add_f32_dpp v146, v146, v146 row_half_mirror row_mask:0xf bank_mask:0xf bound_ctrl:1
	s_nop 1
	v_add_f32_dpp v146, v146, v146 row_mirror row_mask:0xf bank_mask:0xf bound_ctrl:1
	s_nop 0
	v_readlane_b32 s2, v146, 16
	v_readlane_b32 s0, v146, 0
	s_nop 0
	v_mov_b32_e32 v147, s2
	v_readlane_b32 s2, v146, 48
	v_add_f32_e32 v147, s0, v147
	v_readlane_b32 s0, v146, 32
	v_mov_b32_e32 v146, s2
	s_nop 0
	v_add_f32_e32 v146, s0, v146
	v_add_f32_e32 v146, v147, v146
	v_fmamk_f32 v146, v146, 0x3a000000, v245
	v_mul_f32_e32 v147, 0x4f800000, v146
	v_cmp_gt_f32_e32 vcc, s87, v146
	s_nop 1
	v_cndmask_b32_e32 v146, v146, v147, vcc
	v_sqrt_f32_e32 v147, v146
	s_nop 0
	v_add_u32_e32 v163, -1, v147
	v_fma_f32 v164, -v163, v147, v146
	v_cmp_ge_f32_e64 s[40:41], 0, v164
	v_add_u32_e32 v164, 1, v147
	s_nop 0
	v_cndmask_b32_e64 v163, v147, v163, s[40:41]
	v_fma_f32 v147, -v164, v147, v146
	v_cmp_lt_f32_e64 s[40:41], 0, v147
	s_nop 1
	v_cndmask_b32_e64 v147, v163, v164, s[40:41]
	v_mul_f32_e32 v163, 0x37800000, v147
	v_cndmask_b32_e32 v147, v147, v163, vcc
	v_cmp_class_f32_e32 vcc, v146, v243
	s_nop 1
	v_cndmask_b32_e32 v146, v147, v146, vcc
	v_div_scale_f32 v147, s[2:3], v146, v146, 1.0
	v_rcp_f32_e32 v163, v147
	s_nop 0
	v_fma_f32 v164, -v147, v163, 1.0
	v_fmac_f32_e32 v163, v164, v163
	v_div_scale_f32 v164, vcc, 1.0, v146, 1.0
	v_mul_f32_e32 v165, v164, v163
	v_fma_f32 v166, -v147, v165, v164
	v_fmac_f32_e32 v165, v166, v163
	v_fma_f32 v147, -v147, v165, v164
	v_div_fmas_f32 v147, v147, v163, v165
	v_div_fixup_f32 v146, v147, v146, 1.0
	s_and_saveexec_b64 s[8:9], s[42:43]
	s_cbranch_execz .LBB0_1964
	s_ashr_i32 s45, s44, 31
	s_lshl_b64 s[2:3], s[44:45], 2
	s_add_u32 s2, s12, s2
	v_mov_b32_e32 v163, v146
	s_addc_u32 s3, s13, s3
	global_store_dwordx2 v225, v[162:163], s[2:3]
.LBB0_1964:
	s_or_b64 exec, exec, s[8:9]
	s_nop 0
	ds_read_b128 v[162:165], v195 offset:16
	ds_read_b128 v[166:169], v195 offset:0
	ds_read_b128 v[170:173], v195 offset:8208
	ds_read_b128 v[174:177], v195 offset:8192
	v_pk_mul_f32 v[112:113], v[112:113], v[146:147] op_sel_hi:[1,0]
	v_pk_mul_f32 v[160:161], v[160:161], v[146:147] op_sel_hi:[1,0]
	v_pk_mul_f32 v[156:157], v[156:157], v[146:147] op_sel_hi:[1,0]
	v_pk_mul_f32 v[158:159], v[158:159], v[146:147] op_sel_hi:[1,0]
	s_mov_b32 s0, 0x16b00000
	v_pk_mul_f32 v[152:153], v[152:153], v[146:147] op_sel_hi:[1,0]
	v_pk_mul_f32 v[154:155], v[154:155], v[146:147] op_sel_hi:[1,0]
	v_pk_mul_f32 v[148:149], v[148:149], v[146:147] op_sel_hi:[1,0]
	v_pk_mul_f32 v[150:151], v[150:151], v[146:147] op_sel_hi:[1,0]
	v_pk_mul_f32 v[142:143], v[142:143], v[146:147] op_sel_hi:[1,0]
	v_pk_mul_f32 v[144:145], v[144:145], v[146:147] op_sel_hi:[1,0]
	v_pk_mul_f32 v[138:139], v[138:139], v[146:147] op_sel_hi:[1,0]
	v_pk_mul_f32 v[140:141], v[140:141], v[146:147] op_sel_hi:[1,0]
	v_pk_mul_f32 v[132:133], v[132:133], v[146:147] op_sel_hi:[1,0]
	v_pk_mul_f32 v[136:137], v[136:137], v[146:147] op_sel_hi:[1,0]
	v_pk_mul_f32 v[114:115], v[114:115], v[146:147] op_sel_hi:[1,0]
	v_pk_mul_f32 v[134:135], v[134:135], v[146:147] op_sel_hi:[1,0]
	s_waitcnt lgkmcnt(1)
	v_pk_fma_f32 v[160:161], v[160:161], v[162:163], v[170:171]
	s_waitcnt lgkmcnt(0)
	v_pk_fma_f32 v[112:113], v[112:113], v[168:169], v[176:177]
	v_pk_fma_f32 v[162:163], v[156:157], v[164:165], v[172:173]
	v_cvt_pk_bf16_f32 v157, v112, v113
	v_lshl_add_u64 v[112:113], v[128:129], 0, s[46:47]
	v_pk_fma_f32 v[158:159], v[158:159], v[166:167], v[174:175]
	v_add_co_u32_e32 v172, vcc, s0, v112
	v_cvt_pk_bf16_f32 v156, v158, v159
	v_cvt_pk_bf16_f32 v158, v160, v161
	v_cvt_pk_bf16_f32 v159, v162, v163
	v_addc_co_u32_e32 v173, vcc, 0, v113, vcc
	global_store_dwordx4 v[172:173], v[156:159], off
	s_nop 0
	ds_read_b128 v[156:159], v195 offset:2064
	s_nop 0
	ds_read_b128 v[160:163], v195 offset:2048
	ds_read_b128 v[164:167], v195 offset:10256
	ds_read_b128 v[168:171], v195 offset:10240
	s_waitcnt lgkmcnt(1)
	v_pk_fma_f32 v[154:155], v[154:155], v[156:157], v[164:165]
	s_waitcnt lgkmcnt(0)
	v_pk_fma_f32 v[152:153], v[152:153], v[160:161], v[168:169]
	v_pk_fma_f32 v[156:157], v[148:149], v[162:163], v[170:171]
	v_pk_fma_f32 v[158:159], v[150:151], v[158:159], v[166:167]
	v_cvt_pk_bf16_f32 v148, v152, v153
	v_cvt_pk_bf16_f32 v149, v156, v157
	v_cvt_pk_bf16_f32 v150, v154, v155
	v_cvt_pk_bf16_f32 v151, v158, v159
	global_store_dwordx4 v[172:173], v[148:151], off offset:1024
	s_nop 0
	ds_read_b128 v[148:151], v195 offset:4112
	s_nop 0
	ds_read_b128 v[152:155], v195 offset:4096
	ds_read_b128 v[156:159], v195 offset:12304
	ds_read_b128 v[160:163], v195 offset:12288
	s_waitcnt lgkmcnt(1)
	v_pk_fma_f32 v[144:145], v[144:145], v[148:149], v[156:157]
	s_waitcnt lgkmcnt(0)
	v_pk_fma_f32 v[142:143], v[142:143], v[152:153], v[160:161]
	v_pk_fma_f32 v[148:149], v[138:139], v[154:155], v[162:163]
	v_pk_fma_f32 v[150:151], v[140:141], v[150:151], v[158:159]
	v_cvt_pk_bf16_f32 v138, v142, v143
	v_cvt_pk_bf16_f32 v139, v148, v149
	v_cvt_pk_bf16_f32 v140, v144, v145
	v_cvt_pk_bf16_f32 v141, v150, v151
	global_store_dwordx4 v[172:173], v[138:141], off offset:2048
	s_nop 0
	ds_read_b128 v[138:141], v195 offset:6160
	s_nop 0
	ds_read_b128 v[142:145], v195 offset:6144
	ds_read_b128 v[148:151], v195 offset:14352
	ds_read_b128 v[152:155], v195 offset:14336
	s_waitcnt vmcnt(28)
	v_cvt_f32_f16_e32 v156, v97
	v_cvt_f32_f16_sdwa v157, v97 dst_sel:DWORD dst_unused:UNUSED_PAD src0_sel:WORD_1
	s_waitcnt lgkmcnt(1)
	v_pk_fma_f32 v[136:137], v[136:137], v[138:139], v[148:149]
	s_waitcnt lgkmcnt(0)
	v_pk_fma_f32 v[132:133], v[132:133], v[142:143], v[152:153]
	v_pk_fma_f32 v[114:115], v[114:115], v[144:145], v[154:155]
	v_pk_fma_f32 v[138:139], v[134:135], v[140:141], v[150:151]
	v_cvt_pk_bf16_f32 v132, v132, v133
	v_cvt_pk_bf16_f32 v133, v114, v115
	v_cvt_pk_bf16_f32 v134, v136, v137
	v_cvt_pk_bf16_f32 v135, v138, v139
	global_store_dwordx4 v[172:173], v[132:135], off offset:3072
	v_cvt_f32_f16_sdwa v115, v111 dst_sel:DWORD dst_unused:UNUSED_PAD src0_sel:WORD_1
	v_cvt_f32_f16_e32 v114, v111
	v_cvt_f32_f16_sdwa v133, v109 dst_sel:DWORD dst_unused:UNUSED_PAD src0_sel:WORD_1
	v_cvt_f32_f16_e32 v132, v109
	v_cvt_f32_f16_sdwa v109, v108 dst_sel:DWORD dst_unused:UNUSED_PAD src0_sel:WORD_1
	v_cvt_f32_f16_e32 v108, v108
	v_cvt_f32_f16_sdwa v111, v110 dst_sel:DWORD dst_unused:UNUSED_PAD src0_sel:WORD_1
	v_cvt_f32_f16_e32 v110, v110
	v_cvt_f32_f16_sdwa v137, v105 dst_sel:DWORD dst_unused:UNUSED_PAD src0_sel:WORD_1
	v_add_f32_e32 v134, 0, v108
	v_add_f32_e32 v134, v134, v109
	v_add_f32_e32 v134, v134, v132
	v_add_f32_e32 v134, v134, v133
	v_add_f32_e32 v134, v134, v110
	v_cvt_f32_f16_e32 v136, v105
	v_cvt_f32_f16_sdwa v105, v104 dst_sel:DWORD dst_unused:UNUSED_PAD src0_sel:WORD_1
	v_cvt_f32_f16_e32 v104, v104
	v_add_f32_e32 v134, v134, v111
	v_add_f32_e32 v134, v134, v114
	v_add_f32_e32 v138, v134, v115
	v_cvt_f32_f16_sdwa v135, v107 dst_sel:DWORD dst_unused:UNUSED_PAD src0_sel:WORD_1
	v_cvt_f32_f16_e32 v134, v107
	v_cvt_f32_f16_sdwa v107, v106 dst_sel:DWORD dst_unused:UNUSED_PAD src0_sel:WORD_1
	v_cvt_f32_f16_e32 v106, v106
	v_add_f32_e32 v138, v138, v104
	v_add_f32_e32 v138, v138, v105
	v_add_f32_e32 v138, v138, v136
	v_add_f32_e32 v138, v138, v137
	v_add_f32_e32 v138, v138, v106
	v_cvt_f32_f16_sdwa v151, v101 dst_sel:DWORD dst_unused:UNUSED_PAD src0_sel:WORD_1
	v_cvt_f32_f16_e32 v150, v101
	v_cvt_f32_f16_sdwa v101, v100 dst_sel:DWORD dst_unused:UNUSED_PAD src0_sel:WORD_1
	v_cvt_f32_f16_e32 v100, v100
	v_add_f32_e32 v138, v138, v107
	v_add_f32_e32 v138, v138, v134
	v_add_f32_e32 v138, v138, v135
	v_cvt_f32_f16_sdwa v149, v103 dst_sel:DWORD dst_unused:UNUSED_PAD src0_sel:WORD_1
	v_cvt_f32_f16_e32 v148, v103
	v_cvt_f32_f16_sdwa v103, v102 dst_sel:DWORD dst_unused:UNUSED_PAD src0_sel:WORD_1
	v_cvt_f32_f16_e32 v102, v102
	v_add_f32_e32 v138, v138, v100
	v_add_f32_e32 v138, v138, v101
	v_add_f32_e32 v138, v138, v150
	v_add_f32_e32 v138, v138, v151
	v_add_f32_e32 v138, v138, v102
	v_cvt_f32_f16_sdwa v155, v98 dst_sel:DWORD dst_unused:UNUSED_PAD src0_sel:WORD_1
	v_cvt_f32_f16_e32 v154, v98
	v_cvt_f32_f16_e32 v98, v96
	v_add_f32_e32 v138, v138, v103
	v_cvt_f32_f16_sdwa v153, v99 dst_sel:DWORD dst_unused:UNUSED_PAD src0_sel:WORD_1
	v_cvt_f32_f16_e32 v152, v99
	v_cvt_f32_f16_sdwa v99, v96 dst_sel:DWORD dst_unused:UNUSED_PAD src0_sel:WORD_1
	v_add_f32_e32 v138, v138, v148
	v_add_f32_e32 v138, v138, v149
	v_add_f32_e32 v96, v138, v98
	v_add_f32_e32 v96, v96, v99
	v_add_f32_e32 v96, v96, v156
	v_add_f32_e32 v96, v96, v157
	v_add_f32_e32 v96, v96, v154
	v_add_f32_e32 v96, v96, v155
	v_add_f32_e32 v96, v96, v152
	v_add_f32_e32 v96, v96, v153
	s_nop 1
	v_add_f32_dpp v96, v96, v96 quad_perm:[1,0,3,2] row_mask:0xf bank_mask:0xf bound_ctrl:1
	s_nop 1
	v_add_f32_dpp v96, v96, v96 quad_perm:[2,3,0,1] row_mask:0xf bank_mask:0xf bound_ctrl:1
	s_nop 1
	v_add_f32_dpp v96, v96, v96 row_half_mirror row_mask:0xf bank_mask:0xf bound_ctrl:1
	s_nop 1
	v_add_f32_dpp v96, v96, v96 row_mirror row_mask:0xf bank_mask:0xf bound_ctrl:1
	s_nop 0
	v_readlane_b32 s0, v96, 16
	v_readlane_b32 s7, v96, 48
	v_readlane_b32 s2, v96, 0
	v_readlane_b32 s3, v96, 32
	v_mov_b32_e32 v96, s0
	v_mov_b32_e32 v97, s7
	v_pk_add_f32 v[96:97], s[2:3], v[96:97]
	s_nop 0
	v_add_f32_e32 v96, v96, v97
	v_mul_f32_e32 v146, 0x3a000000, v96
	v_pk_add_f32 v[140:141], v[108:109], v[146:147] op_sel_hi:[1,0] neg_lo:[0,1] neg_hi:[0,1]
	v_pk_add_f32 v[138:139], v[132:133], v[146:147] op_sel_hi:[1,0] neg_lo:[0,1] neg_hi:[0,1]
	v_pk_mul_f32 v[158:159], v[140:141], v[140:141]
	v_pk_mul_f32 v[160:161], v[138:139], v[138:139]
	v_pk_add_f32 v[144:145], v[110:111], v[146:147] op_sel_hi:[1,0] neg_lo:[0,1] neg_hi:[0,1]
	v_pk_add_f32 v[142:143], v[114:115], v[146:147] op_sel_hi:[1,0] neg_lo:[0,1] neg_hi:[0,1]
	v_pk_add_f32 v[132:133], v[104:105], v[146:147] op_sel_hi:[1,0] neg_lo:[0,1] neg_hi:[0,1]
	v_pk_add_f32 v[114:115], v[136:137], v[146:147] op_sel_hi:[1,0] neg_lo:[0,1] neg_hi:[0,1]
	v_pk_add_f32 v[136:137], v[106:107], v[146:147] op_sel_hi:[1,0] neg_lo:[0,1] neg_hi:[0,1]
	v_pk_add_f32 v[134:135], v[134:135], v[146:147] op_sel_hi:[1,0] neg_lo:[0,1] neg_hi:[0,1]
	v_pk_add_f32 v[100:101], v[100:101], v[146:147] op_sel_hi:[1,0] neg_lo:[0,1] neg_hi:[0,1]
	v_pk_add_f32 v[96:97], v[150:151], v[146:147] op_sel_hi:[1,0] neg_lo:[0,1] neg_hi:[0,1]
	v_pk_add_f32 v[108:109], v[102:103], v[146:147] op_sel_hi:[1,0] neg_lo:[0,1] neg_hi:[0,1]
	v_pk_add_f32 v[104:105], v[148:149], v[146:147] op_sel_hi:[1,0] neg_lo:[0,1] neg_hi:[0,1]
	v_pk_add_f32 v[98:99], v[98:99], v[146:147] op_sel_hi:[1,0] neg_lo:[0,1] neg_hi:[0,1]
	v_pk_add_f32 v[102:103], v[156:157], v[146:147] op_sel_hi:[1,0] neg_lo:[0,1] neg_hi:[0,1]
	v_pk_add_f32 v[106:107], v[154:155], v[146:147] op_sel_hi:[1,0] neg_lo:[0,1] neg_hi:[0,1]
	v_pk_add_f32 v[110:111], v[152:153], v[146:147] op_sel_hi:[1,0] neg_lo:[0,1] neg_hi:[0,1]
	v_add_f32_e32 v147, v158, v159
	v_add_f32_e32 v147, v160, v147
	v_pk_mul_f32 v[162:163], v[144:145], v[144:145]
	v_add_f32_e32 v147, v161, v147
	v_add_f32_e32 v147, v162, v147
	v_pk_mul_f32 v[164:165], v[142:143], v[142:143]
	v_add_f32_e32 v147, v163, v147
	v_add_f32_e32 v147, v164, v147
	v_pk_mul_f32 v[166:167], v[132:133], v[132:133]
	v_add_f32_e32 v147, v165, v147
	v_add_f32_e32 v147, v166, v147
	v_pk_mul_f32 v[168:169], v[114:115], v[114:115]
	v_add_f32_e32 v147, v167, v147
	v_add_f32_e32 v147, v168, v147
	v_pk_mul_f32 v[170:171], v[136:137], v[136:137]
	v_add_f32_e32 v147, v169, v147
	v_add_f32_e32 v147, v170, v147
	v_pk_mul_f32 v[172:173], v[134:135], v[134:135]
	v_add_f32_e32 v147, v171, v147
	v_add_f32_e32 v147, v172, v147
	v_pk_mul_f32 v[174:175], v[100:101], v[100:101]
	v_add_f32_e32 v147, v173, v147
	v_add_f32_e32 v147, v174, v147
	v_pk_mul_f32 v[150:151], v[96:97], v[96:97]
	v_add_f32_e32 v147, v175, v147
	v_add_f32_e32 v147, v150, v147
	v_pk_mul_f32 v[176:177], v[108:109], v[108:109]
	v_add_f32_e32 v147, v151, v147
	v_add_f32_e32 v147, v176, v147
	v_pk_mul_f32 v[148:149], v[104:105], v[104:105]
	v_add_f32_e32 v147, v177, v147
	v_add_f32_e32 v147, v148, v147
	v_pk_mul_f32 v[178:179], v[98:99], v[98:99]
	v_add_f32_e32 v147, v149, v147
	v_add_f32_e32 v147, v178, v147
	v_pk_mul_f32 v[156:157], v[102:103], v[102:103]
	v_add_f32_e32 v147, v179, v147
	v_add_f32_e32 v147, v156, v147
	v_pk_mul_f32 v[154:155], v[106:107], v[106:107]
	v_add_f32_e32 v147, v157, v147
	v_add_f32_e32 v147, v154, v147
	v_pk_mul_f32 v[152:153], v[110:111], v[110:111]
	v_add_f32_e32 v147, v155, v147
	v_add_f32_e32 v147, v152, v147
	v_add_f32_e32 v147, v153, v147
	s_nop 1
	v_add_f32_dpp v147, v147, v147 quad_perm:[1,0,3,2] row_mask:0xf bank_mask:0xf bound_ctrl:1
	s_nop 1
	v_add_f32_dpp v147, v147, v147 quad_perm:[2,3,0,1] row_mask:0xf bank_mask:0xf bound_ctrl:1
	s_nop 1
	v_add_f32_dpp v147, v147, v147 row_half_mirror row_mask:0xf bank_mask:0xf bound_ctrl:1
	s_nop 1
	v_add_f32_dpp v147, v147, v147 row_mirror row_mask:0xf bank_mask:0xf bound_ctrl:1
	s_nop 0
	v_readlane_b32 s2, v147, 16
	v_readlane_b32 s0, v147, 0
	s_nop 0
	v_mov_b32_e32 v148, s2
	v_readlane_b32 s2, v147, 48
	v_add_f32_e32 v148, s0, v148
	v_readlane_b32 s0, v147, 32
	v_mov_b32_e32 v147, s2
	s_nop 0
	v_add_f32_e32 v147, s0, v147
	v_add_f32_e32 v147, v148, v147
	v_fmamk_f32 v147, v147, 0x3a000000, v245
	v_cmp_gt_f32_e32 vcc, s87, v147
	v_mul_f32_e32 v148, 0x4f800000, v147
	s_nop 0
	v_cndmask_b32_e32 v147, v147, v148, vcc
	v_sqrt_f32_e32 v148, v147
	s_nop 0
	v_add_u32_e32 v149, -1, v148
	v_fma_f32 v150, -v149, v148, v147
	v_cmp_ge_f32_e64 s[40:41], 0, v150
	v_add_u32_e32 v150, 1, v148
	s_nop 0
	v_cndmask_b32_e64 v149, v148, v149, s[40:41]
	v_fma_f32 v148, -v150, v148, v147
	v_cmp_lt_f32_e64 s[40:41], 0, v148
	s_nop 1
	v_cndmask_b32_e64 v148, v149, v150, s[40:41]
	v_mul_f32_e32 v149, 0x37800000, v148
	v_cndmask_b32_e32 v148, v148, v149, vcc
	v_cmp_class_f32_e32 vcc, v147, v243
	s_nop 1
	v_cndmask_b32_e32 v147, v148, v147, vcc
	v_div_scale_f32 v148, s[2:3], v147, v147, 1.0
	v_rcp_f32_e32 v149, v148
	s_nop 0
	v_fma_f32 v150, -v148, v149, 1.0
	v_fmac_f32_e32 v149, v150, v149
	v_div_scale_f32 v150, vcc, 1.0, v147, 1.0
	v_mul_f32_e32 v151, v150, v149
	v_fma_f32 v152, -v148, v151, v150
	v_fmac_f32_e32 v151, v152, v149
	v_fma_f32 v148, -v148, v151, v150
	v_div_fmas_f32 v148, v148, v149, v151
	v_div_fixup_f32 v148, v148, v147, 1.0
	s_and_saveexec_b64 s[8:9], s[42:43]
	s_cbranch_execz .LBB0_1966
	s_ashr_i32 s45, s44, 31
	s_lshl_b64 s[2:3], s[44:45], 2
	s_add_u32 s2, s12, s2
	v_mov_b32_e32 v147, v148
	s_addc_u32 s3, s13, s3
	global_store_dwordx2 v225, v[146:147], s[2:3] offset:8
.LBB0_1966:
	s_or_b64 exec, exec, s[8:9]
	s_nop 0
	ds_read_b128 v[150:153], v195 offset:16
	ds_read_b128 v[154:157], v195 offset:0
	ds_read_b128 v[158:161], v195 offset:8208
	ds_read_b128 v[162:165], v195 offset:8192
	v_pk_mul_f32 v[140:141], v[140:141], v[148:149] op_sel_hi:[1,0]
	v_pk_mul_f32 v[144:145], v[144:145], v[148:149] op_sel_hi:[1,0]
	v_pk_mul_f32 v[138:139], v[138:139], v[148:149] op_sel_hi:[1,0]
	v_pk_mul_f32 v[142:143], v[142:143], v[148:149] op_sel_hi:[1,0]
	s_mov_b32 s0, 0x16b01000
	v_pk_mul_f32 v[132:133], v[132:133], v[148:149] op_sel_hi:[1,0]
	v_pk_mul_f32 v[136:137], v[136:137], v[148:149] op_sel_hi:[1,0]
	v_pk_mul_f32 v[114:115], v[114:115], v[148:149] op_sel_hi:[1,0]
	v_pk_mul_f32 v[134:135], v[134:135], v[148:149] op_sel_hi:[1,0]
	v_pk_mul_f32 v[100:101], v[100:101], v[148:149] op_sel_hi:[1,0]
	v_pk_mul_f32 v[108:109], v[108:109], v[148:149] op_sel_hi:[1,0]
	v_pk_mul_f32 v[96:97], v[96:97], v[148:149] op_sel_hi:[1,0]
	v_pk_mul_f32 v[104:105], v[104:105], v[148:149] op_sel_hi:[1,0]
	s_waitcnt lgkmcnt(1)
	v_pk_fma_f32 v[144:145], v[144:145], v[150:151], v[158:159]
	s_waitcnt lgkmcnt(0)
	v_pk_fma_f32 v[140:141], v[140:141], v[154:155], v[162:163]
	v_pk_fma_f32 v[146:147], v[138:139], v[156:157], v[164:165]
	v_pk_fma_f32 v[142:143], v[142:143], v[152:153], v[160:161]
	v_add_co_u32_e32 v158, vcc, s0, v112
	v_cvt_pk_bf16_f32 v138, v140, v141
	v_cvt_pk_bf16_f32 v139, v146, v147
	v_cvt_pk_bf16_f32 v140, v144, v145
	v_cvt_pk_bf16_f32 v141, v142, v143
	v_addc_co_u32_e32 v159, vcc, 0, v113, vcc
	global_store_dwordx4 v[158:159], v[138:141], off
	s_nop 0
	ds_read_b128 v[138:141], v195 offset:2064
	s_nop 0
	ds_read_b128 v[142:145], v195 offset:2048
	ds_read_b128 v[150:153], v195 offset:10256
	ds_read_b128 v[154:157], v195 offset:10240
	s_waitcnt lgkmcnt(1)
	v_pk_fma_f32 v[136:137], v[136:137], v[138:139], v[150:151]
	s_waitcnt lgkmcnt(0)
	v_pk_fma_f32 v[132:133], v[132:133], v[142:143], v[154:155]
	v_pk_fma_f32 v[114:115], v[114:115], v[144:145], v[156:157]
	v_pk_fma_f32 v[138:139], v[134:135], v[140:141], v[152:153]
	v_cvt_pk_bf16_f32 v132, v132, v133
	v_cvt_pk_bf16_f32 v133, v114, v115
	v_cvt_pk_bf16_f32 v134, v136, v137
	v_cvt_pk_bf16_f32 v135, v138, v139
	global_store_dwordx4 v[158:159], v[132:135], off offset:1024
	s_nop 0
	ds_read_b128 v[132:135], v195 offset:4112
	s_nop 0
	ds_read_b128 v[136:139], v195 offset:4096
	ds_read_b128 v[140:143], v195 offset:12304
	ds_read_b128 v[144:147], v195 offset:12288
	s_waitcnt lgkmcnt(1)
	v_pk_fma_f32 v[108:109], v[108:109], v[132:133], v[140:141]
	s_waitcnt lgkmcnt(0)
	v_pk_fma_f32 v[100:101], v[100:101], v[136:137], v[144:145]
	v_pk_fma_f32 v[96:97], v[96:97], v[138:139], v[146:147]
	v_pk_fma_f32 v[104:105], v[104:105], v[134:135], v[142:143]
	v_cvt_pk_bf16_f32 v132, v100, v101
	v_cvt_pk_bf16_f32 v133, v96, v97
	v_cvt_pk_bf16_f32 v134, v108, v109
	v_cvt_pk_bf16_f32 v135, v104, v105
	global_store_dwordx4 v[158:159], v[132:135], off offset:2048
	s_nop 0
	ds_read_b128 v[132:135], v195 offset:6160
	s_nop 0
	ds_read_b128 v[136:139], v195 offset:6144
	ds_read_b128 v[140:143], v195 offset:14352
	ds_read_b128 v[144:147], v195 offset:14336
	v_pk_mul_f32 v[96:97], v[98:99], v[148:149] op_sel_hi:[1,0]
	v_pk_mul_f32 v[98:99], v[106:107], v[148:149] op_sel_hi:[1,0]
	v_pk_mul_f32 v[100:101], v[102:103], v[148:149] op_sel_hi:[1,0]
	v_pk_mul_f32 v[102:103], v[110:111], v[148:149] op_sel_hi:[1,0]
	s_waitcnt lgkmcnt(1)
	v_pk_fma_f32 v[98:99], v[98:99], v[132:133], v[140:141]
	s_waitcnt lgkmcnt(0)
	v_pk_fma_f32 v[96:97], v[96:97], v[136:137], v[144:145]
	v_pk_fma_f32 v[100:101], v[100:101], v[138:139], v[146:147]
	v_pk_fma_f32 v[102:103], v[102:103], v[134:135], v[142:143]
	v_cvt_pk_bf16_f32 v96, v96, v97
	v_cvt_pk_bf16_f32 v97, v100, v101
	v_cvt_pk_bf16_f32 v98, v98, v99
	v_cvt_pk_bf16_f32 v99, v102, v103
	global_store_dwordx4 v[158:159], v[96:99], off offset:3072
	s_waitcnt vmcnt(30)
	v_cvt_f32_f16_sdwa v103, v89 dst_sel:DWORD dst_unused:UNUSED_PAD src0_sel:WORD_1
	v_cvt_f32_f16_e32 v102, v89
	v_cvt_f32_f16_sdwa v99, v93 dst_sel:DWORD dst_unused:UNUSED_PAD src0_sel:WORD_1
	v_cvt_f32_f16_e32 v98, v93
	v_cvt_f32_f16_sdwa v93, v92 dst_sel:DWORD dst_unused:UNUSED_PAD src0_sel:WORD_1
	v_cvt_f32_f16_e32 v92, v92
	v_cvt_f32_f16_sdwa v97, v95 dst_sel:DWORD dst_unused:UNUSED_PAD src0_sel:WORD_1
	v_cvt_f32_f16_e32 v96, v95
	v_cvt_f32_f16_sdwa v95, v94 dst_sel:DWORD dst_unused:UNUSED_PAD src0_sel:WORD_1
	v_cvt_f32_f16_e32 v94, v94
	v_add_f32_e32 v100, 0, v92
	v_add_f32_e32 v100, v100, v93
	v_add_f32_e32 v100, v100, v98
	v_add_f32_e32 v100, v100, v99
	v_add_f32_e32 v100, v100, v94
	v_cvt_f32_f16_sdwa v89, v88 dst_sel:DWORD dst_unused:UNUSED_PAD src0_sel:WORD_1
	v_cvt_f32_f16_e32 v88, v88
	v_add_f32_e32 v100, v100, v95
	v_add_f32_e32 v100, v100, v96
	v_add_f32_e32 v104, v100, v97
	v_cvt_f32_f16_sdwa v101, v91 dst_sel:DWORD dst_unused:UNUSED_PAD src0_sel:WORD_1
	v_cvt_f32_f16_e32 v100, v91
	v_cvt_f32_f16_sdwa v91, v90 dst_sel:DWORD dst_unused:UNUSED_PAD src0_sel:WORD_1
	v_cvt_f32_f16_e32 v90, v90
	v_add_f32_e32 v104, v104, v88
	v_add_f32_e32 v104, v104, v89
	v_add_f32_e32 v104, v104, v102
	v_add_f32_e32 v104, v104, v103
	v_add_f32_e32 v104, v104, v90
	v_cvt_f32_f16_sdwa v135, v85 dst_sel:DWORD dst_unused:UNUSED_PAD src0_sel:WORD_1
	v_cvt_f32_f16_e32 v134, v85
	v_cvt_f32_f16_sdwa v85, v84 dst_sel:DWORD dst_unused:UNUSED_PAD src0_sel:WORD_1
	v_cvt_f32_f16_e32 v84, v84
	v_add_f32_e32 v104, v104, v91
	v_add_f32_e32 v104, v104, v100
	v_add_f32_e32 v104, v104, v101
	v_cvt_f32_f16_sdwa v133, v87 dst_sel:DWORD dst_unused:UNUSED_PAD src0_sel:WORD_1
	v_cvt_f32_f16_e32 v132, v87
	v_cvt_f32_f16_sdwa v87, v86 dst_sel:DWORD dst_unused:UNUSED_PAD src0_sel:WORD_1
	v_cvt_f32_f16_e32 v86, v86
	v_add_f32_e32 v104, v104, v84
	v_add_f32_e32 v104, v104, v85
	v_add_f32_e32 v104, v104, v134
	v_add_f32_e32 v104, v104, v135
	v_add_f32_e32 v104, v104, v86
	v_cvt_f32_f16_sdwa v139, v82 dst_sel:DWORD dst_unused:UNUSED_PAD src0_sel:WORD_1
	v_cvt_f32_f16_e32 v138, v82
	v_cvt_f32_f16_e32 v82, v80
	v_add_f32_e32 v104, v104, v87
	v_cvt_f32_f16_sdwa v137, v83 dst_sel:DWORD dst_unused:UNUSED_PAD src0_sel:WORD_1
	v_cvt_f32_f16_e32 v136, v83
	v_cvt_f32_f16_sdwa v83, v80 dst_sel:DWORD dst_unused:UNUSED_PAD src0_sel:WORD_1
	v_add_f32_e32 v104, v104, v132
	v_cvt_f32_f16_e32 v140, v81
	v_add_f32_e32 v104, v104, v133
	v_cvt_f32_f16_sdwa v141, v81 dst_sel:DWORD dst_unused:UNUSED_PAD src0_sel:WORD_1
	v_add_f32_e32 v80, v104, v82
	v_add_f32_e32 v80, v80, v83
	v_add_f32_e32 v80, v80, v140
	v_add_f32_e32 v80, v80, v141
	v_add_f32_e32 v80, v80, v138
	v_add_f32_e32 v80, v80, v139
	v_add_f32_e32 v80, v80, v136
	v_add_f32_e32 v80, v80, v137
	s_nop 1
	v_add_f32_dpp v80, v80, v80 quad_perm:[1,0,3,2] row_mask:0xf bank_mask:0xf bound_ctrl:1
	s_nop 1
	v_add_f32_dpp v80, v80, v80 quad_perm:[2,3,0,1] row_mask:0xf bank_mask:0xf bound_ctrl:1
	s_nop 1
	v_add_f32_dpp v80, v80, v80 row_half_mirror row_mask:0xf bank_mask:0xf bound_ctrl:1
	s_nop 1
	v_add_f32_dpp v80, v80, v80 row_mirror row_mask:0xf bank_mask:0xf bound_ctrl:1
	s_nop 0
	v_readlane_b32 s0, v80, 16
	v_readlane_b32 s7, v80, 48
	v_readlane_b32 s2, v80, 0
	v_readlane_b32 s3, v80, 32
	v_mov_b32_e32 v80, s0
	v_mov_b32_e32 v81, s7
	v_pk_add_f32 v[80:81], s[2:3], v[80:81]
	s_nop 0
	v_add_f32_e32 v80, v80, v81
	v_mul_f32_e32 v114, 0x3a000000, v80
	v_pk_add_f32 v[106:107], v[92:93], v[114:115] op_sel_hi:[1,0] neg_lo:[0,1] neg_hi:[0,1]
	v_pk_add_f32 v[104:105], v[98:99], v[114:115] op_sel_hi:[1,0] neg_lo:[0,1] neg_hi:[0,1]
	v_pk_mul_f32 v[142:143], v[106:107], v[106:107]
	v_pk_mul_f32 v[144:145], v[104:105], v[104:105]
	v_pk_add_f32 v[110:111], v[94:95], v[114:115] op_sel_hi:[1,0] neg_lo:[0,1] neg_hi:[0,1]
	v_pk_add_f32 v[108:109], v[96:97], v[114:115] op_sel_hi:[1,0] neg_lo:[0,1] neg_hi:[0,1]
	v_pk_add_f32 v[98:99], v[88:89], v[114:115] op_sel_hi:[1,0] neg_lo:[0,1] neg_hi:[0,1]
	v_pk_add_f32 v[96:97], v[102:103], v[114:115] op_sel_hi:[1,0] neg_lo:[0,1] neg_hi:[0,1]
	v_pk_add_f32 v[102:103], v[90:91], v[114:115] op_sel_hi:[1,0] neg_lo:[0,1] neg_hi:[0,1]
	v_pk_add_f32 v[100:101], v[100:101], v[114:115] op_sel_hi:[1,0] neg_lo:[0,1] neg_hi:[0,1]
	v_pk_add_f32 v[84:85], v[84:85], v[114:115] op_sel_hi:[1,0] neg_lo:[0,1] neg_hi:[0,1]
	v_pk_add_f32 v[80:81], v[134:135], v[114:115] op_sel_hi:[1,0] neg_lo:[0,1] neg_hi:[0,1]
	v_pk_add_f32 v[92:93], v[86:87], v[114:115] op_sel_hi:[1,0] neg_lo:[0,1] neg_hi:[0,1]
	v_pk_add_f32 v[88:89], v[132:133], v[114:115] op_sel_hi:[1,0] neg_lo:[0,1] neg_hi:[0,1]
	v_pk_add_f32 v[82:83], v[82:83], v[114:115] op_sel_hi:[1,0] neg_lo:[0,1] neg_hi:[0,1]
	v_pk_add_f32 v[86:87], v[140:141], v[114:115] op_sel_hi:[1,0] neg_lo:[0,1] neg_hi:[0,1]
	v_pk_add_f32 v[90:91], v[138:139], v[114:115] op_sel_hi:[1,0] neg_lo:[0,1] neg_hi:[0,1]
	v_pk_add_f32 v[94:95], v[136:137], v[114:115] op_sel_hi:[1,0] neg_lo:[0,1] neg_hi:[0,1]
	v_add_f32_e32 v115, v142, v143
	v_add_f32_e32 v115, v144, v115
	v_pk_mul_f32 v[146:147], v[110:111], v[110:111]
	v_add_f32_e32 v115, v145, v115
	v_add_f32_e32 v115, v146, v115
	v_pk_mul_f32 v[148:149], v[108:109], v[108:109]
	v_add_f32_e32 v115, v147, v115
	v_add_f32_e32 v115, v148, v115
	v_pk_mul_f32 v[150:151], v[98:99], v[98:99]
	v_add_f32_e32 v115, v149, v115
	v_add_f32_e32 v115, v150, v115
	v_pk_mul_f32 v[152:153], v[96:97], v[96:97]
	v_add_f32_e32 v115, v151, v115
	v_add_f32_e32 v115, v152, v115
	v_pk_mul_f32 v[154:155], v[102:103], v[102:103]
	v_add_f32_e32 v115, v153, v115
	v_add_f32_e32 v115, v154, v115
	v_pk_mul_f32 v[156:157], v[100:101], v[100:101]
	v_add_f32_e32 v115, v155, v115
	v_add_f32_e32 v115, v156, v115
	v_pk_mul_f32 v[158:159], v[84:85], v[84:85]
	v_add_f32_e32 v115, v157, v115
	v_add_f32_e32 v115, v158, v115
	v_pk_mul_f32 v[134:135], v[80:81], v[80:81]
	v_add_f32_e32 v115, v159, v115
	v_add_f32_e32 v115, v134, v115
	v_pk_mul_f32 v[160:161], v[92:93], v[92:93]
	v_add_f32_e32 v115, v135, v115
	v_add_f32_e32 v115, v160, v115
	v_pk_mul_f32 v[132:133], v[88:89], v[88:89]
	v_add_f32_e32 v115, v161, v115
	v_add_f32_e32 v115, v132, v115
	v_pk_mul_f32 v[162:163], v[82:83], v[82:83]
	v_add_f32_e32 v115, v133, v115
	v_add_f32_e32 v115, v162, v115
	v_pk_mul_f32 v[140:141], v[86:87], v[86:87]
	v_add_f32_e32 v115, v163, v115
	v_add_f32_e32 v115, v140, v115
	v_pk_mul_f32 v[138:139], v[90:91], v[90:91]
	v_add_f32_e32 v115, v141, v115
	v_add_f32_e32 v115, v138, v115
	v_pk_mul_f32 v[136:137], v[94:95], v[94:95]
	v_add_f32_e32 v115, v139, v115
	v_add_f32_e32 v115, v136, v115
	v_add_f32_e32 v115, v137, v115
	s_nop 1
	v_add_f32_dpp v115, v115, v115 quad_perm:[1,0,3,2] row_mask:0xf bank_mask:0xf bound_ctrl:1
	s_nop 1
	v_add_f32_dpp v115, v115, v115 quad_perm:[2,3,0,1] row_mask:0xf bank_mask:0xf bound_ctrl:1
	s_nop 1
	v_add_f32_dpp v115, v115, v115 row_half_mirror row_mask:0xf bank_mask:0xf bound_ctrl:1
	s_nop 1
	v_add_f32_dpp v115, v115, v115 row_mirror row_mask:0xf bank_mask:0xf bound_ctrl:1
	s_nop 0
	v_readlane_b32 s2, v115, 16
	v_readlane_b32 s0, v115, 0
	s_nop 0
	v_mov_b32_e32 v132, s2
	v_readlane_b32 s2, v115, 48
	v_add_f32_e32 v132, s0, v132
	v_readlane_b32 s0, v115, 32
	v_mov_b32_e32 v115, s2
	s_nop 0
	v_add_f32_e32 v115, s0, v115
	v_add_f32_e32 v115, v132, v115
	v_fmamk_f32 v115, v115, 0x3a000000, v245
	v_cmp_gt_f32_e32 vcc, s87, v115
	v_mul_f32_e32 v132, 0x4f800000, v115
	s_nop 0
	v_cndmask_b32_e32 v115, v115, v132, vcc
	v_sqrt_f32_e32 v132, v115
	s_nop 0
	v_add_u32_e32 v133, -1, v132
	v_fma_f32 v134, -v133, v132, v115
	v_cmp_ge_f32_e64 s[40:41], 0, v134
	v_add_u32_e32 v134, 1, v132
	s_nop 0
	v_cndmask_b32_e64 v133, v132, v133, s[40:41]
	v_fma_f32 v132, -v134, v132, v115
	v_cmp_lt_f32_e64 s[40:41], 0, v132
	s_nop 1
	v_cndmask_b32_e64 v132, v133, v134, s[40:41]
	v_mul_f32_e32 v133, 0x37800000, v132
	v_cndmask_b32_e32 v132, v132, v133, vcc
	v_cmp_class_f32_e32 vcc, v115, v243
	s_nop 1
	v_cndmask_b32_e32 v115, v132, v115, vcc
	v_div_scale_f32 v132, s[2:3], v115, v115, 1.0
	v_rcp_f32_e32 v133, v132
	s_nop 0
	v_fma_f32 v134, -v132, v133, 1.0
	v_fmac_f32_e32 v133, v134, v133
	v_div_scale_f32 v134, vcc, 1.0, v115, 1.0
	v_mul_f32_e32 v135, v134, v133
	v_fma_f32 v136, -v132, v135, v134
	v_fmac_f32_e32 v135, v136, v133
	v_fma_f32 v132, -v132, v135, v134
	v_div_fmas_f32 v132, v132, v133, v135
	v_div_fixup_f32 v132, v132, v115, 1.0
	s_and_saveexec_b64 s[8:9], s[42:43]
	s_cbranch_execz .LBB0_1968
	s_ashr_i32 s45, s44, 31
	s_lshl_b64 s[2:3], s[44:45], 2
	s_add_u32 s2, s12, s2
	v_mov_b32_e32 v115, v132
	s_addc_u32 s3, s13, s3
	global_store_dwordx2 v225, v[114:115], s[2:3] offset:16
.LBB0_1968:
	s_or_b64 exec, exec, s[8:9]
	s_nop 0
	ds_read_b128 v[134:137], v195 offset:16
	ds_read_b128 v[138:141], v195 offset:0
	ds_read_b128 v[142:145], v195 offset:8208
	ds_read_b128 v[146:149], v195 offset:8192
	v_pk_mul_f32 v[104:105], v[104:105], v[132:133] op_sel_hi:[1,0]
	v_pk_mul_f32 v[106:107], v[106:107], v[132:133] op_sel_hi:[1,0]
	v_pk_mul_f32 v[110:111], v[110:111], v[132:133] op_sel_hi:[1,0]
	v_pk_mul_f32 v[108:109], v[108:109], v[132:133] op_sel_hi:[1,0]
	s_mov_b32 s0, 0x16b02000
	v_pk_mul_f32 v[98:99], v[98:99], v[132:133] op_sel_hi:[1,0]
	v_pk_mul_f32 v[102:103], v[102:103], v[132:133] op_sel_hi:[1,0]
	v_pk_mul_f32 v[96:97], v[96:97], v[132:133] op_sel_hi:[1,0]
	v_pk_mul_f32 v[100:101], v[100:101], v[132:133] op_sel_hi:[1,0]
	v_pk_mul_f32 v[84:85], v[84:85], v[132:133] op_sel_hi:[1,0]
	v_pk_mul_f32 v[92:93], v[92:93], v[132:133] op_sel_hi:[1,0]
	v_pk_mul_f32 v[80:81], v[80:81], v[132:133] op_sel_hi:[1,0]
	v_pk_mul_f32 v[88:89], v[88:89], v[132:133] op_sel_hi:[1,0]
	s_waitcnt lgkmcnt(1)
	v_pk_fma_f32 v[110:111], v[110:111], v[134:135], v[142:143]
	s_waitcnt lgkmcnt(0)
	v_pk_fma_f32 v[114:115], v[104:105], v[140:141], v[148:149]
	v_pk_fma_f32 v[106:107], v[106:107], v[138:139], v[146:147]
	v_pk_fma_f32 v[108:109], v[108:109], v[136:137], v[144:145]
	v_cvt_pk_bf16_f32 v105, v114, v115
	v_add_co_u32_e32 v114, vcc, s0, v112
	v_cvt_pk_bf16_f32 v104, v106, v107
	v_cvt_pk_bf16_f32 v106, v110, v111
	v_cvt_pk_bf16_f32 v107, v108, v109
	v_addc_co_u32_e32 v115, vcc, 0, v113, vcc
	global_store_dwordx4 v[114:115], v[104:107], off
	s_nop 0
	ds_read_b128 v[104:107], v195 offset:2064
	s_nop 0
	ds_read_b128 v[108:111], v195 offset:2048
	ds_read_b128 v[134:137], v195 offset:10256
	ds_read_b128 v[138:141], v195 offset:10240
	s_waitcnt lgkmcnt(1)
	v_pk_fma_f32 v[102:103], v[102:103], v[104:105], v[134:135]
	s_waitcnt lgkmcnt(0)
	v_pk_fma_f32 v[98:99], v[98:99], v[108:109], v[138:139]
	v_pk_fma_f32 v[104:105], v[96:97], v[110:111], v[140:141]
	v_pk_fma_f32 v[100:101], v[100:101], v[106:107], v[136:137]
	v_cvt_pk_bf16_f32 v96, v98, v99
	v_cvt_pk_bf16_f32 v97, v104, v105
	v_cvt_pk_bf16_f32 v98, v102, v103
	v_cvt_pk_bf16_f32 v99, v100, v101
	global_store_dwordx4 v[114:115], v[96:99], off offset:1024
	s_nop 0
	ds_read_b128 v[96:99], v195 offset:4112
	s_nop 0
	ds_read_b128 v[100:103], v195 offset:4096
	ds_read_b128 v[104:107], v195 offset:12304
	ds_read_b128 v[108:111], v195 offset:12288
	s_waitcnt lgkmcnt(1)
	v_pk_fma_f32 v[92:93], v[92:93], v[96:97], v[104:105]
	s_waitcnt lgkmcnt(0)
	v_pk_fma_f32 v[84:85], v[84:85], v[100:101], v[108:109]
	v_pk_fma_f32 v[80:81], v[80:81], v[102:103], v[110:111]
	v_pk_fma_f32 v[88:89], v[88:89], v[98:99], v[106:107]
	v_cvt_pk_bf16_f32 v96, v84, v85
	v_cvt_pk_bf16_f32 v97, v80, v81
	v_cvt_pk_bf16_f32 v98, v92, v93
	v_cvt_pk_bf16_f32 v99, v88, v89
	global_store_dwordx4 v[114:115], v[96:99], off offset:2048
	s_nop 0
	ds_read_b128 v[96:99], v195 offset:6160
	s_nop 0
	ds_read_b128 v[100:103], v195 offset:6144
	ds_read_b128 v[104:107], v195 offset:14352
	ds_read_b128 v[108:111], v195 offset:14336
	v_pk_mul_f32 v[80:81], v[82:83], v[132:133] op_sel_hi:[1,0]
	v_pk_mul_f32 v[82:83], v[90:91], v[132:133] op_sel_hi:[1,0]
	v_pk_mul_f32 v[84:85], v[86:87], v[132:133] op_sel_hi:[1,0]
	v_pk_mul_f32 v[86:87], v[94:95], v[132:133] op_sel_hi:[1,0]
	s_waitcnt lgkmcnt(1)
	v_pk_fma_f32 v[82:83], v[82:83], v[96:97], v[104:105]
	s_waitcnt lgkmcnt(0)
	v_pk_fma_f32 v[80:81], v[80:81], v[100:101], v[108:109]
	v_pk_fma_f32 v[84:85], v[84:85], v[102:103], v[110:111]
	v_pk_fma_f32 v[86:87], v[86:87], v[98:99], v[106:107]
	v_cvt_pk_bf16_f32 v80, v80, v81
	v_cvt_pk_bf16_f32 v81, v84, v85
	v_cvt_pk_bf16_f32 v82, v82, v83
	v_cvt_pk_bf16_f32 v83, v86, v87
	global_store_dwordx4 v[114:115], v[80:83], off offset:3072
	s_waitcnt vmcnt(31)
	v_cvt_f32_f16_sdwa v87, v73 dst_sel:DWORD dst_unused:UNUSED_PAD src0_sel:WORD_1
	v_cvt_f32_f16_e32 v86, v73
	v_cvt_f32_f16_sdwa v83, v77 dst_sel:DWORD dst_unused:UNUSED_PAD src0_sel:WORD_1
	v_cvt_f32_f16_e32 v82, v77
	v_cvt_f32_f16_sdwa v77, v76 dst_sel:DWORD dst_unused:UNUSED_PAD src0_sel:WORD_1
	v_cvt_f32_f16_e32 v76, v76
	v_cvt_f32_f16_sdwa v81, v79 dst_sel:DWORD dst_unused:UNUSED_PAD src0_sel:WORD_1
	v_cvt_f32_f16_e32 v80, v79
	v_cvt_f32_f16_sdwa v79, v78 dst_sel:DWORD dst_unused:UNUSED_PAD src0_sel:WORD_1
	v_cvt_f32_f16_e32 v78, v78
	v_add_f32_e32 v84, 0, v76
	v_add_f32_e32 v84, v84, v77
	v_add_f32_e32 v84, v84, v82
	v_add_f32_e32 v84, v84, v83
	v_add_f32_e32 v84, v84, v78
	v_cvt_f32_f16_sdwa v73, v72 dst_sel:DWORD dst_unused:UNUSED_PAD src0_sel:WORD_1
	v_cvt_f32_f16_e32 v72, v72
	v_add_f32_e32 v84, v84, v79
	v_add_f32_e32 v84, v84, v80
	v_add_f32_e32 v88, v84, v81
	v_cvt_f32_f16_sdwa v85, v75 dst_sel:DWORD dst_unused:UNUSED_PAD src0_sel:WORD_1
	v_cvt_f32_f16_e32 v84, v75
	v_cvt_f32_f16_sdwa v75, v74 dst_sel:DWORD dst_unused:UNUSED_PAD src0_sel:WORD_1
	v_cvt_f32_f16_e32 v74, v74
	v_add_f32_e32 v88, v88, v72
	v_add_f32_e32 v88, v88, v73
	v_add_f32_e32 v88, v88, v86
	v_add_f32_e32 v88, v88, v87
	v_add_f32_e32 v88, v88, v74
	v_cvt_f32_f16_sdwa v101, v69 dst_sel:DWORD dst_unused:UNUSED_PAD src0_sel:WORD_1
	v_cvt_f32_f16_e32 v100, v69
	v_cvt_f32_f16_sdwa v69, v68 dst_sel:DWORD dst_unused:UNUSED_PAD src0_sel:WORD_1
	v_cvt_f32_f16_e32 v68, v68
	v_add_f32_e32 v88, v88, v75
	v_add_f32_e32 v88, v88, v84
	v_add_f32_e32 v88, v88, v85
	v_cvt_f32_f16_sdwa v99, v71 dst_sel:DWORD dst_unused:UNUSED_PAD src0_sel:WORD_1
	v_cvt_f32_f16_e32 v98, v71
	v_cvt_f32_f16_sdwa v71, v70 dst_sel:DWORD dst_unused:UNUSED_PAD src0_sel:WORD_1
	v_cvt_f32_f16_e32 v70, v70
	v_add_f32_e32 v88, v88, v68
	v_add_f32_e32 v88, v88, v69
	v_add_f32_e32 v88, v88, v100
	v_add_f32_e32 v88, v88, v101
	v_add_f32_e32 v88, v88, v70
	v_cvt_f32_f16_sdwa v105, v66 dst_sel:DWORD dst_unused:UNUSED_PAD src0_sel:WORD_1
	v_cvt_f32_f16_e32 v104, v66
	v_cvt_f32_f16_e32 v66, v64
	v_add_f32_e32 v88, v88, v71
	v_cvt_f32_f16_sdwa v103, v67 dst_sel:DWORD dst_unused:UNUSED_PAD src0_sel:WORD_1
	v_cvt_f32_f16_e32 v102, v67
	v_cvt_f32_f16_sdwa v67, v64 dst_sel:DWORD dst_unused:UNUSED_PAD src0_sel:WORD_1
	v_add_f32_e32 v88, v88, v98
	v_cvt_f32_f16_e32 v106, v65
	v_add_f32_e32 v88, v88, v99
	v_cvt_f32_f16_sdwa v107, v65 dst_sel:DWORD dst_unused:UNUSED_PAD src0_sel:WORD_1
	v_add_f32_e32 v64, v88, v66
	v_add_f32_e32 v64, v64, v67
	v_add_f32_e32 v64, v64, v106
	v_add_f32_e32 v64, v64, v107
	v_add_f32_e32 v64, v64, v104
	v_add_f32_e32 v64, v64, v105
	v_add_f32_e32 v64, v64, v102
	v_add_f32_e32 v64, v64, v103
	s_nop 1
	v_add_f32_dpp v64, v64, v64 quad_perm:[1,0,3,2] row_mask:0xf bank_mask:0xf bound_ctrl:1
	s_nop 1
	v_add_f32_dpp v64, v64, v64 quad_perm:[2,3,0,1] row_mask:0xf bank_mask:0xf bound_ctrl:1
	s_nop 1
	v_add_f32_dpp v64, v64, v64 row_half_mirror row_mask:0xf bank_mask:0xf bound_ctrl:1
	s_nop 1
	v_add_f32_dpp v64, v64, v64 row_mirror row_mask:0xf bank_mask:0xf bound_ctrl:1
	s_nop 0
	v_readlane_b32 s0, v64, 16
	v_readlane_b32 s7, v64, 48
	v_readlane_b32 s2, v64, 0
	v_readlane_b32 s3, v64, 32
	v_mov_b32_e32 v64, s0
	v_mov_b32_e32 v65, s7
	v_pk_add_f32 v[64:65], s[2:3], v[64:65]
	s_nop 0
	v_add_f32_e32 v64, v64, v65
	v_mul_f32_e32 v96, 0x3a000000, v64
	v_pk_add_f32 v[90:91], v[76:77], v[96:97] op_sel_hi:[1,0] neg_lo:[0,1] neg_hi:[0,1]
	v_pk_add_f32 v[88:89], v[82:83], v[96:97] op_sel_hi:[1,0] neg_lo:[0,1] neg_hi:[0,1]
	v_pk_mul_f32 v[108:109], v[90:91], v[90:91]
	v_pk_mul_f32 v[110:111], v[88:89], v[88:89]
	v_pk_add_f32 v[94:95], v[78:79], v[96:97] op_sel_hi:[1,0] neg_lo:[0,1] neg_hi:[0,1]
	v_pk_add_f32 v[92:93], v[80:81], v[96:97] op_sel_hi:[1,0] neg_lo:[0,1] neg_hi:[0,1]
	v_pk_add_f32 v[82:83], v[72:73], v[96:97] op_sel_hi:[1,0] neg_lo:[0,1] neg_hi:[0,1]
	v_pk_add_f32 v[80:81], v[86:87], v[96:97] op_sel_hi:[1,0] neg_lo:[0,1] neg_hi:[0,1]
	v_pk_add_f32 v[86:87], v[74:75], v[96:97] op_sel_hi:[1,0] neg_lo:[0,1] neg_hi:[0,1]
	v_pk_add_f32 v[84:85], v[84:85], v[96:97] op_sel_hi:[1,0] neg_lo:[0,1] neg_hi:[0,1]
	v_pk_add_f32 v[68:69], v[68:69], v[96:97] op_sel_hi:[1,0] neg_lo:[0,1] neg_hi:[0,1]
	v_pk_add_f32 v[64:65], v[100:101], v[96:97] op_sel_hi:[1,0] neg_lo:[0,1] neg_hi:[0,1]
	v_pk_add_f32 v[76:77], v[70:71], v[96:97] op_sel_hi:[1,0] neg_lo:[0,1] neg_hi:[0,1]
	v_pk_add_f32 v[72:73], v[98:99], v[96:97] op_sel_hi:[1,0] neg_lo:[0,1] neg_hi:[0,1]
	v_pk_add_f32 v[66:67], v[66:67], v[96:97] op_sel_hi:[1,0] neg_lo:[0,1] neg_hi:[0,1]
	v_pk_add_f32 v[70:71], v[106:107], v[96:97] op_sel_hi:[1,0] neg_lo:[0,1] neg_hi:[0,1]
	v_pk_add_f32 v[74:75], v[104:105], v[96:97] op_sel_hi:[1,0] neg_lo:[0,1] neg_hi:[0,1]
	v_pk_add_f32 v[78:79], v[102:103], v[96:97] op_sel_hi:[1,0] neg_lo:[0,1] neg_hi:[0,1]
	v_add_f32_e32 v97, v108, v109
	v_add_f32_e32 v97, v110, v97
	v_pk_mul_f32 v[114:115], v[94:95], v[94:95]
	v_add_f32_e32 v97, v111, v97
	v_add_f32_e32 v97, v114, v97
	v_pk_mul_f32 v[132:133], v[92:93], v[92:93]
	v_add_f32_e32 v97, v115, v97
	v_add_f32_e32 v97, v132, v97
	v_pk_mul_f32 v[134:135], v[82:83], v[82:83]
	v_add_f32_e32 v97, v133, v97
	v_add_f32_e32 v97, v134, v97
	v_pk_mul_f32 v[136:137], v[80:81], v[80:81]
	v_add_f32_e32 v97, v135, v97
	v_add_f32_e32 v97, v136, v97
	v_pk_mul_f32 v[138:139], v[86:87], v[86:87]
	v_add_f32_e32 v97, v137, v97
	v_add_f32_e32 v97, v138, v97
	v_pk_mul_f32 v[140:141], v[84:85], v[84:85]
	v_add_f32_e32 v97, v139, v97
	v_add_f32_e32 v97, v140, v97
	v_pk_mul_f32 v[142:143], v[68:69], v[68:69]
	v_add_f32_e32 v97, v141, v97
	v_add_f32_e32 v97, v142, v97
	v_pk_mul_f32 v[100:101], v[64:65], v[64:65]
	v_add_f32_e32 v97, v143, v97
	v_add_f32_e32 v97, v100, v97
	v_pk_mul_f32 v[144:145], v[76:77], v[76:77]
	v_add_f32_e32 v97, v101, v97
	v_add_f32_e32 v97, v144, v97
	v_pk_mul_f32 v[98:99], v[72:73], v[72:73]
	v_add_f32_e32 v97, v145, v97
	v_add_f32_e32 v97, v98, v97
	v_pk_mul_f32 v[146:147], v[66:67], v[66:67]
	v_add_f32_e32 v97, v99, v97
	v_add_f32_e32 v97, v146, v97
	v_pk_mul_f32 v[106:107], v[70:71], v[70:71]
	v_add_f32_e32 v97, v147, v97
	v_add_f32_e32 v97, v106, v97
	v_pk_mul_f32 v[104:105], v[74:75], v[74:75]
	v_add_f32_e32 v97, v107, v97
	v_add_f32_e32 v97, v104, v97
	v_pk_mul_f32 v[102:103], v[78:79], v[78:79]
	v_add_f32_e32 v97, v105, v97
	v_add_f32_e32 v97, v102, v97
	v_add_f32_e32 v97, v103, v97
	s_nop 1
	v_add_f32_dpp v97, v97, v97 quad_perm:[1,0,3,2] row_mask:0xf bank_mask:0xf bound_ctrl:1
	s_nop 1
	v_add_f32_dpp v97, v97, v97 quad_perm:[2,3,0,1] row_mask:0xf bank_mask:0xf bound_ctrl:1
	s_nop 1
	v_add_f32_dpp v97, v97, v97 row_half_mirror row_mask:0xf bank_mask:0xf bound_ctrl:1
	s_nop 1
	v_add_f32_dpp v97, v97, v97 row_mirror row_mask:0xf bank_mask:0xf bound_ctrl:1
	s_nop 0
	v_readlane_b32 s2, v97, 16
	v_readlane_b32 s0, v97, 0
	s_nop 0
	v_mov_b32_e32 v98, s2
	v_readlane_b32 s2, v97, 48
	v_add_f32_e32 v98, s0, v98
	v_readlane_b32 s0, v97, 32
	v_mov_b32_e32 v97, s2
	s_nop 0
	v_add_f32_e32 v97, s0, v97
	v_add_f32_e32 v97, v98, v97
	v_fmamk_f32 v97, v97, 0x3a000000, v245
	v_cmp_gt_f32_e32 vcc, s87, v97
	v_mul_f32_e32 v98, 0x4f800000, v97
	s_nop 0
	v_cndmask_b32_e32 v97, v97, v98, vcc
	v_sqrt_f32_e32 v98, v97
	s_nop 0
	v_add_u32_e32 v99, -1, v98
	v_fma_f32 v100, -v99, v98, v97
	v_cmp_ge_f32_e64 s[40:41], 0, v100
	v_add_u32_e32 v100, 1, v98
	s_nop 0
	v_cndmask_b32_e64 v99, v98, v99, s[40:41]
	v_fma_f32 v98, -v100, v98, v97
	v_cmp_lt_f32_e64 s[40:41], 0, v98
	s_nop 1
	v_cndmask_b32_e64 v98, v99, v100, s[40:41]
	v_mul_f32_e32 v99, 0x37800000, v98
	v_cndmask_b32_e32 v98, v98, v99, vcc
	v_cmp_class_f32_e32 vcc, v97, v243
	s_nop 1
	v_cndmask_b32_e32 v97, v98, v97, vcc
	v_div_scale_f32 v98, s[2:3], v97, v97, 1.0
	v_rcp_f32_e32 v99, v98
	s_nop 0
	v_fma_f32 v100, -v98, v99, 1.0
	v_fmac_f32_e32 v99, v100, v99
	v_div_scale_f32 v100, vcc, 1.0, v97, 1.0
	v_mul_f32_e32 v101, v100, v99
	v_fma_f32 v102, -v98, v101, v100
	v_fmac_f32_e32 v101, v102, v99
	v_fma_f32 v98, -v98, v101, v100
	v_div_fmas_f32 v98, v98, v99, v101
	v_div_fixup_f32 v98, v98, v97, 1.0
	s_and_saveexec_b64 s[8:9], s[42:43]
	s_cbranch_execz .LBB0_1970
	s_ashr_i32 s45, s44, 31
	s_lshl_b64 s[2:3], s[44:45], 2
	s_add_u32 s2, s12, s2
	v_mov_b32_e32 v97, v98
	s_addc_u32 s3, s13, s3
	global_store_dwordx2 v225, v[96:97], s[2:3] offset:24
.LBB0_1970:
	s_or_b64 exec, exec, s[8:9]
	s_nop 0
	ds_read_b128 v[100:103], v195 offset:16
	ds_read_b128 v[104:107], v195 offset:0
	ds_read_b128 v[108:111], v195 offset:8208
	ds_read_b128 v[132:135], v195 offset:8192
	v_pk_mul_f32 v[88:89], v[88:89], v[98:99] op_sel_hi:[1,0]
	v_pk_mul_f32 v[90:91], v[90:91], v[98:99] op_sel_hi:[1,0]
	v_pk_mul_f32 v[94:95], v[94:95], v[98:99] op_sel_hi:[1,0]
	v_pk_mul_f32 v[92:93], v[92:93], v[98:99] op_sel_hi:[1,0]
	s_mov_b32 s0, 0x16b03000
	v_pk_mul_f32 v[82:83], v[82:83], v[98:99] op_sel_hi:[1,0]
	v_pk_mul_f32 v[86:87], v[86:87], v[98:99] op_sel_hi:[1,0]
	v_pk_mul_f32 v[80:81], v[80:81], v[98:99] op_sel_hi:[1,0]
	v_pk_mul_f32 v[84:85], v[84:85], v[98:99] op_sel_hi:[1,0]
	v_pk_mul_f32 v[68:69], v[68:69], v[98:99] op_sel_hi:[1,0]
	v_pk_mul_f32 v[76:77], v[76:77], v[98:99] op_sel_hi:[1,0]
	v_pk_mul_f32 v[64:65], v[64:65], v[98:99] op_sel_hi:[1,0]
	v_pk_mul_f32 v[72:73], v[72:73], v[98:99] op_sel_hi:[1,0]
	s_waitcnt lgkmcnt(1)
	v_pk_fma_f32 v[94:95], v[94:95], v[100:101], v[108:109]
	s_waitcnt lgkmcnt(0)
	v_pk_fma_f32 v[96:97], v[88:89], v[106:107], v[134:135]
	v_pk_fma_f32 v[90:91], v[90:91], v[104:105], v[132:133]
	v_pk_fma_f32 v[92:93], v[92:93], v[102:103], v[110:111]
	v_cvt_pk_bf16_f32 v89, v96, v97
	v_add_co_u32_e32 v96, vcc, s0, v112
	v_cvt_pk_bf16_f32 v88, v90, v91
	v_cvt_pk_bf16_f32 v90, v94, v95
	v_cvt_pk_bf16_f32 v91, v92, v93
	v_addc_co_u32_e32 v97, vcc, 0, v113, vcc
	global_store_dwordx4 v[96:97], v[88:91], off
	s_nop 0
	ds_read_b128 v[88:91], v195 offset:2064
	s_nop 0
	ds_read_b128 v[92:95], v195 offset:2048
	ds_read_b128 v[100:103], v195 offset:10256
	ds_read_b128 v[104:107], v195 offset:10240
	s_waitcnt lgkmcnt(1)
	v_pk_fma_f32 v[86:87], v[86:87], v[88:89], v[100:101]
	s_waitcnt lgkmcnt(0)
	v_pk_fma_f32 v[82:83], v[82:83], v[92:93], v[104:105]
	v_pk_fma_f32 v[88:89], v[80:81], v[94:95], v[106:107]
	v_pk_fma_f32 v[84:85], v[84:85], v[90:91], v[102:103]
	v_cvt_pk_bf16_f32 v80, v82, v83
	v_cvt_pk_bf16_f32 v81, v88, v89
	v_cvt_pk_bf16_f32 v82, v86, v87
	v_cvt_pk_bf16_f32 v83, v84, v85
	global_store_dwordx4 v[96:97], v[80:83], off offset:1024
	s_nop 0
	ds_read_b128 v[80:83], v195 offset:4112
	s_nop 0
	ds_read_b128 v[84:87], v195 offset:4096
	ds_read_b128 v[88:91], v195 offset:12304
	ds_read_b128 v[92:95], v195 offset:12288
	s_waitcnt lgkmcnt(1)
	v_pk_fma_f32 v[76:77], v[76:77], v[80:81], v[88:89]
	s_waitcnt lgkmcnt(0)
	v_pk_fma_f32 v[68:69], v[68:69], v[84:85], v[92:93]
	v_pk_fma_f32 v[64:65], v[64:65], v[86:87], v[94:95]
	v_pk_fma_f32 v[72:73], v[72:73], v[82:83], v[90:91]
	v_cvt_pk_bf16_f32 v80, v68, v69
	v_cvt_pk_bf16_f32 v81, v64, v65
	v_cvt_pk_bf16_f32 v82, v76, v77
	v_cvt_pk_bf16_f32 v83, v72, v73
	global_store_dwordx4 v[96:97], v[80:83], off offset:2048
	s_nop 0
	ds_read_b128 v[80:83], v195 offset:6160
	s_nop 0
	ds_read_b128 v[84:87], v195 offset:6144
	ds_read_b128 v[88:91], v195 offset:14352
	ds_read_b128 v[92:95], v195 offset:14336
	v_pk_mul_f32 v[64:65], v[66:67], v[98:99] op_sel_hi:[1,0]
	v_pk_mul_f32 v[66:67], v[74:75], v[98:99] op_sel_hi:[1,0]
	v_pk_mul_f32 v[68:69], v[70:71], v[98:99] op_sel_hi:[1,0]
	v_pk_mul_f32 v[70:71], v[78:79], v[98:99] op_sel_hi:[1,0]
	s_waitcnt lgkmcnt(1)
	v_pk_fma_f32 v[66:67], v[66:67], v[80:81], v[88:89]
	s_waitcnt lgkmcnt(0)
	v_pk_fma_f32 v[64:65], v[64:65], v[84:85], v[92:93]
	v_pk_fma_f32 v[68:69], v[68:69], v[86:87], v[94:95]
	v_pk_fma_f32 v[70:71], v[70:71], v[82:83], v[90:91]
	v_cvt_pk_bf16_f32 v64, v64, v65
	v_cvt_pk_bf16_f32 v65, v68, v69
	v_cvt_pk_bf16_f32 v66, v66, v67
	v_cvt_pk_bf16_f32 v67, v70, v71
	global_store_dwordx4 v[96:97], v[64:67], off offset:3072
	s_waitcnt vmcnt(32)
	v_cvt_f32_f16_sdwa v71, v57 dst_sel:DWORD dst_unused:UNUSED_PAD src0_sel:WORD_1
	v_cvt_f32_f16_e32 v70, v57
	v_cvt_f32_f16_sdwa v67, v61 dst_sel:DWORD dst_unused:UNUSED_PAD src0_sel:WORD_1
	v_cvt_f32_f16_e32 v66, v61
	v_cvt_f32_f16_sdwa v61, v60 dst_sel:DWORD dst_unused:UNUSED_PAD src0_sel:WORD_1
	v_cvt_f32_f16_e32 v60, v60
	v_cvt_f32_f16_sdwa v65, v63 dst_sel:DWORD dst_unused:UNUSED_PAD src0_sel:WORD_1
	v_cvt_f32_f16_e32 v64, v63
	v_cvt_f32_f16_sdwa v63, v62 dst_sel:DWORD dst_unused:UNUSED_PAD src0_sel:WORD_1
	v_cvt_f32_f16_e32 v62, v62
	v_add_f32_e32 v68, 0, v60
	v_add_f32_e32 v68, v68, v61
	v_add_f32_e32 v68, v68, v66
	v_add_f32_e32 v68, v68, v67
	v_add_f32_e32 v68, v68, v62
	v_cvt_f32_f16_sdwa v57, v56 dst_sel:DWORD dst_unused:UNUSED_PAD src0_sel:WORD_1
	v_cvt_f32_f16_e32 v56, v56
	v_add_f32_e32 v68, v68, v63
	v_add_f32_e32 v68, v68, v64
	v_add_f32_e32 v72, v68, v65
	v_cvt_f32_f16_sdwa v69, v59 dst_sel:DWORD dst_unused:UNUSED_PAD src0_sel:WORD_1
	v_cvt_f32_f16_e32 v68, v59
	v_cvt_f32_f16_sdwa v59, v58 dst_sel:DWORD dst_unused:UNUSED_PAD src0_sel:WORD_1
	v_cvt_f32_f16_e32 v58, v58
	v_add_f32_e32 v72, v72, v56
	v_add_f32_e32 v72, v72, v57
	v_add_f32_e32 v72, v72, v70
	v_add_f32_e32 v72, v72, v71
	v_add_f32_e32 v72, v72, v58
	v_cvt_f32_f16_sdwa v85, v53 dst_sel:DWORD dst_unused:UNUSED_PAD src0_sel:WORD_1
	v_cvt_f32_f16_e32 v84, v53
	v_cvt_f32_f16_sdwa v53, v52 dst_sel:DWORD dst_unused:UNUSED_PAD src0_sel:WORD_1
	v_cvt_f32_f16_e32 v52, v52
	v_add_f32_e32 v72, v72, v59
	v_add_f32_e32 v72, v72, v68
	v_add_f32_e32 v72, v72, v69
	v_cvt_f32_f16_sdwa v83, v55 dst_sel:DWORD dst_unused:UNUSED_PAD src0_sel:WORD_1
	v_cvt_f32_f16_e32 v82, v55
	v_cvt_f32_f16_sdwa v55, v54 dst_sel:DWORD dst_unused:UNUSED_PAD src0_sel:WORD_1
	v_cvt_f32_f16_e32 v54, v54
	v_add_f32_e32 v72, v72, v52
	v_add_f32_e32 v72, v72, v53
	v_add_f32_e32 v72, v72, v84
	v_add_f32_e32 v72, v72, v85
	v_add_f32_e32 v72, v72, v54
	v_cvt_f32_f16_sdwa v89, v50 dst_sel:DWORD dst_unused:UNUSED_PAD src0_sel:WORD_1
	v_cvt_f32_f16_e32 v88, v50
	v_cvt_f32_f16_e32 v50, v48
	v_add_f32_e32 v72, v72, v55
	v_cvt_f32_f16_sdwa v87, v51 dst_sel:DWORD dst_unused:UNUSED_PAD src0_sel:WORD_1
	v_cvt_f32_f16_e32 v86, v51
	v_cvt_f32_f16_sdwa v51, v48 dst_sel:DWORD dst_unused:UNUSED_PAD src0_sel:WORD_1
	v_add_f32_e32 v72, v72, v82
	v_cvt_f32_f16_e32 v90, v49
	v_add_f32_e32 v72, v72, v83
	v_cvt_f32_f16_sdwa v91, v49 dst_sel:DWORD dst_unused:UNUSED_PAD src0_sel:WORD_1
	v_add_f32_e32 v48, v72, v50
	v_add_f32_e32 v48, v48, v51
	v_add_f32_e32 v48, v48, v90
	v_add_f32_e32 v48, v48, v91
	v_add_f32_e32 v48, v48, v88
	v_add_f32_e32 v48, v48, v89
	v_add_f32_e32 v48, v48, v86
	v_add_f32_e32 v48, v48, v87
	s_nop 1
	v_add_f32_dpp v48, v48, v48 quad_perm:[1,0,3,2] row_mask:0xf bank_mask:0xf bound_ctrl:1
	s_nop 1
	v_add_f32_dpp v48, v48, v48 quad_perm:[2,3,0,1] row_mask:0xf bank_mask:0xf bound_ctrl:1
	s_nop 1
	v_add_f32_dpp v48, v48, v48 row_half_mirror row_mask:0xf bank_mask:0xf bound_ctrl:1
	s_nop 1
	v_add_f32_dpp v48, v48, v48 row_mirror row_mask:0xf bank_mask:0xf bound_ctrl:1
	s_nop 0
	v_readlane_b32 s0, v48, 16
	v_readlane_b32 s7, v48, 48
	v_readlane_b32 s2, v48, 0
	v_readlane_b32 s3, v48, 32
	v_mov_b32_e32 v48, s0
	v_mov_b32_e32 v49, s7
	v_pk_add_f32 v[48:49], s[2:3], v[48:49]
	s_nop 0
	v_add_f32_e32 v48, v48, v49
	v_mul_f32_e32 v80, 0x3a000000, v48
	v_pk_add_f32 v[74:75], v[60:61], v[80:81] op_sel_hi:[1,0] neg_lo:[0,1] neg_hi:[0,1]
	v_pk_add_f32 v[72:73], v[66:67], v[80:81] op_sel_hi:[1,0] neg_lo:[0,1] neg_hi:[0,1]
	v_pk_mul_f32 v[92:93], v[74:75], v[74:75]
	v_pk_mul_f32 v[94:95], v[72:73], v[72:73]
	v_pk_add_f32 v[78:79], v[62:63], v[80:81] op_sel_hi:[1,0] neg_lo:[0,1] neg_hi:[0,1]
	v_pk_add_f32 v[76:77], v[64:65], v[80:81] op_sel_hi:[1,0] neg_lo:[0,1] neg_hi:[0,1]
	v_pk_add_f32 v[66:67], v[56:57], v[80:81] op_sel_hi:[1,0] neg_lo:[0,1] neg_hi:[0,1]
	v_pk_add_f32 v[64:65], v[70:71], v[80:81] op_sel_hi:[1,0] neg_lo:[0,1] neg_hi:[0,1]
	v_pk_add_f32 v[70:71], v[58:59], v[80:81] op_sel_hi:[1,0] neg_lo:[0,1] neg_hi:[0,1]
	v_pk_add_f32 v[68:69], v[68:69], v[80:81] op_sel_hi:[1,0] neg_lo:[0,1] neg_hi:[0,1]
	v_pk_add_f32 v[52:53], v[52:53], v[80:81] op_sel_hi:[1,0] neg_lo:[0,1] neg_hi:[0,1]
	v_pk_add_f32 v[48:49], v[84:85], v[80:81] op_sel_hi:[1,0] neg_lo:[0,1] neg_hi:[0,1]
	v_pk_add_f32 v[60:61], v[54:55], v[80:81] op_sel_hi:[1,0] neg_lo:[0,1] neg_hi:[0,1]
	v_pk_add_f32 v[56:57], v[82:83], v[80:81] op_sel_hi:[1,0] neg_lo:[0,1] neg_hi:[0,1]
	v_pk_add_f32 v[50:51], v[50:51], v[80:81] op_sel_hi:[1,0] neg_lo:[0,1] neg_hi:[0,1]
	v_pk_add_f32 v[54:55], v[90:91], v[80:81] op_sel_hi:[1,0] neg_lo:[0,1] neg_hi:[0,1]
	v_pk_add_f32 v[58:59], v[88:89], v[80:81] op_sel_hi:[1,0] neg_lo:[0,1] neg_hi:[0,1]
	v_pk_add_f32 v[62:63], v[86:87], v[80:81] op_sel_hi:[1,0] neg_lo:[0,1] neg_hi:[0,1]
	v_add_f32_e32 v81, v92, v93
	v_add_f32_e32 v81, v94, v81
	v_pk_mul_f32 v[96:97], v[78:79], v[78:79]
	v_add_f32_e32 v81, v95, v81
	v_add_f32_e32 v81, v96, v81
	v_pk_mul_f32 v[98:99], v[76:77], v[76:77]
	v_add_f32_e32 v81, v97, v81
	v_add_f32_e32 v81, v98, v81
	v_pk_mul_f32 v[100:101], v[66:67], v[66:67]
	v_add_f32_e32 v81, v99, v81
	v_add_f32_e32 v81, v100, v81
	v_pk_mul_f32 v[102:103], v[64:65], v[64:65]
	v_add_f32_e32 v81, v101, v81
	v_add_f32_e32 v81, v102, v81
	v_pk_mul_f32 v[104:105], v[70:71], v[70:71]
	v_add_f32_e32 v81, v103, v81
	v_add_f32_e32 v81, v104, v81
	v_pk_mul_f32 v[106:107], v[68:69], v[68:69]
	v_add_f32_e32 v81, v105, v81
	v_add_f32_e32 v81, v106, v81
	v_pk_mul_f32 v[108:109], v[52:53], v[52:53]
	v_add_f32_e32 v81, v107, v81
	v_add_f32_e32 v81, v108, v81
	v_pk_mul_f32 v[84:85], v[48:49], v[48:49]
	v_add_f32_e32 v81, v109, v81
	v_add_f32_e32 v81, v84, v81
	v_pk_mul_f32 v[110:111], v[60:61], v[60:61]
	v_add_f32_e32 v81, v85, v81
	v_add_f32_e32 v81, v110, v81
	v_pk_mul_f32 v[82:83], v[56:57], v[56:57]
	v_add_f32_e32 v81, v111, v81
	v_add_f32_e32 v81, v82, v81
	v_pk_mul_f32 v[114:115], v[50:51], v[50:51]
	v_add_f32_e32 v81, v83, v81
	v_add_f32_e32 v81, v114, v81
	v_pk_mul_f32 v[90:91], v[54:55], v[54:55]
	v_add_f32_e32 v81, v115, v81
	v_add_f32_e32 v81, v90, v81
	v_pk_mul_f32 v[88:89], v[58:59], v[58:59]
	v_add_f32_e32 v81, v91, v81
	v_add_f32_e32 v81, v88, v81
	v_pk_mul_f32 v[86:87], v[62:63], v[62:63]
	v_add_f32_e32 v81, v89, v81
	v_add_f32_e32 v81, v86, v81
	v_add_f32_e32 v81, v87, v81
	s_nop 1
	v_add_f32_dpp v81, v81, v81 quad_perm:[1,0,3,2] row_mask:0xf bank_mask:0xf bound_ctrl:1
	s_nop 1
	v_add_f32_dpp v81, v81, v81 quad_perm:[2,3,0,1] row_mask:0xf bank_mask:0xf bound_ctrl:1
	s_nop 1
	v_add_f32_dpp v81, v81, v81 row_half_mirror row_mask:0xf bank_mask:0xf bound_ctrl:1
	s_nop 1
	v_add_f32_dpp v81, v81, v81 row_mirror row_mask:0xf bank_mask:0xf bound_ctrl:1
	s_nop 0
	v_readlane_b32 s2, v81, 16
	v_readlane_b32 s0, v81, 0
	s_nop 0
	v_mov_b32_e32 v82, s2
	v_readlane_b32 s2, v81, 48
	v_add_f32_e32 v82, s0, v82
	v_readlane_b32 s0, v81, 32
	v_mov_b32_e32 v81, s2
	s_nop 0
	v_add_f32_e32 v81, s0, v81
	v_add_f32_e32 v81, v82, v81
	v_fmamk_f32 v81, v81, 0x3a000000, v245
	v_cmp_gt_f32_e32 vcc, s87, v81
	v_mul_f32_e32 v82, 0x4f800000, v81
	s_nop 0
	v_cndmask_b32_e32 v81, v81, v82, vcc
	v_sqrt_f32_e32 v82, v81
	s_nop 0
	v_add_u32_e32 v83, -1, v82
	v_fma_f32 v84, -v83, v82, v81
	v_cmp_ge_f32_e64 s[40:41], 0, v84
	v_add_u32_e32 v84, 1, v82
	s_nop 0
	v_cndmask_b32_e64 v83, v82, v83, s[40:41]
	v_fma_f32 v82, -v84, v82, v81
	v_cmp_lt_f32_e64 s[40:41], 0, v82
	s_nop 1
	v_cndmask_b32_e64 v82, v83, v84, s[40:41]
	v_mul_f32_e32 v83, 0x37800000, v82
	v_cndmask_b32_e32 v82, v82, v83, vcc
	v_cmp_class_f32_e32 vcc, v81, v243
	s_nop 1
	v_cndmask_b32_e32 v81, v82, v81, vcc
	v_div_scale_f32 v82, s[2:3], v81, v81, 1.0
	v_rcp_f32_e32 v83, v82
	s_nop 0
	v_fma_f32 v84, -v82, v83, 1.0
	v_fmac_f32_e32 v83, v84, v83
	v_div_scale_f32 v84, vcc, 1.0, v81, 1.0
	v_mul_f32_e32 v85, v84, v83
	v_fma_f32 v86, -v82, v85, v84
	v_fmac_f32_e32 v85, v86, v83
	v_fma_f32 v82, -v82, v85, v84
	v_div_fmas_f32 v82, v82, v83, v85
	v_div_fixup_f32 v82, v82, v81, 1.0
	s_and_saveexec_b64 s[8:9], s[42:43]
	s_cbranch_execz .LBB0_1972
	s_ashr_i32 s45, s44, 31
	s_lshl_b64 s[2:3], s[44:45], 2
	s_add_u32 s2, s12, s2
	v_mov_b32_e32 v81, v82
	s_addc_u32 s3, s13, s3
	global_store_dwordx2 v225, v[80:81], s[2:3] offset:32
.LBB0_1972:
	s_or_b64 exec, exec, s[8:9]
	s_nop 0
	ds_read_b128 v[84:87], v195 offset:16
	ds_read_b128 v[88:91], v195 offset:0
	ds_read_b128 v[92:95], v195 offset:8208
	ds_read_b128 v[96:99], v195 offset:8192
	v_pk_mul_f32 v[72:73], v[72:73], v[82:83] op_sel_hi:[1,0]
	v_pk_mul_f32 v[74:75], v[74:75], v[82:83] op_sel_hi:[1,0]
	v_pk_mul_f32 v[78:79], v[78:79], v[82:83] op_sel_hi:[1,0]
	v_pk_mul_f32 v[76:77], v[76:77], v[82:83] op_sel_hi:[1,0]
	s_mov_b32 s0, 0x16b04000
	v_pk_mul_f32 v[66:67], v[66:67], v[82:83] op_sel_hi:[1,0]
	v_pk_mul_f32 v[70:71], v[70:71], v[82:83] op_sel_hi:[1,0]
	v_pk_mul_f32 v[64:65], v[64:65], v[82:83] op_sel_hi:[1,0]
	v_pk_mul_f32 v[68:69], v[68:69], v[82:83] op_sel_hi:[1,0]
	v_pk_mul_f32 v[52:53], v[52:53], v[82:83] op_sel_hi:[1,0]
	v_pk_mul_f32 v[60:61], v[60:61], v[82:83] op_sel_hi:[1,0]
	v_pk_mul_f32 v[48:49], v[48:49], v[82:83] op_sel_hi:[1,0]
	v_pk_mul_f32 v[56:57], v[56:57], v[82:83] op_sel_hi:[1,0]
	s_waitcnt lgkmcnt(1)
	v_pk_fma_f32 v[78:79], v[78:79], v[84:85], v[92:93]
	s_waitcnt lgkmcnt(0)
	v_pk_fma_f32 v[80:81], v[72:73], v[90:91], v[98:99]
	v_pk_fma_f32 v[74:75], v[74:75], v[88:89], v[96:97]
	v_pk_fma_f32 v[76:77], v[76:77], v[86:87], v[94:95]
	v_cvt_pk_bf16_f32 v73, v80, v81
	v_add_co_u32_e32 v80, vcc, s0, v112
	v_cvt_pk_bf16_f32 v72, v74, v75
	v_cvt_pk_bf16_f32 v74, v78, v79
	v_cvt_pk_bf16_f32 v75, v76, v77
	v_addc_co_u32_e32 v81, vcc, 0, v113, vcc
	global_store_dwordx4 v[80:81], v[72:75], off
	s_nop 0
	ds_read_b128 v[72:75], v195 offset:2064
	s_nop 0
	ds_read_b128 v[76:79], v195 offset:2048
	ds_read_b128 v[84:87], v195 offset:10256
	ds_read_b128 v[88:91], v195 offset:10240
	s_waitcnt lgkmcnt(1)
	v_pk_fma_f32 v[70:71], v[70:71], v[72:73], v[84:85]
	s_waitcnt lgkmcnt(0)
	v_pk_fma_f32 v[66:67], v[66:67], v[76:77], v[88:89]
	v_pk_fma_f32 v[72:73], v[64:65], v[78:79], v[90:91]
	v_pk_fma_f32 v[68:69], v[68:69], v[74:75], v[86:87]
	v_cvt_pk_bf16_f32 v64, v66, v67
	v_cvt_pk_bf16_f32 v65, v72, v73
	v_cvt_pk_bf16_f32 v66, v70, v71
	v_cvt_pk_bf16_f32 v67, v68, v69
	global_store_dwordx4 v[80:81], v[64:67], off offset:1024
	s_nop 0
	ds_read_b128 v[64:67], v195 offset:4112
	s_nop 0
	ds_read_b128 v[68:71], v195 offset:4096
	ds_read_b128 v[72:75], v195 offset:12304
	ds_read_b128 v[76:79], v195 offset:12288
	s_waitcnt lgkmcnt(1)
	v_pk_fma_f32 v[60:61], v[60:61], v[64:65], v[72:73]
	s_waitcnt lgkmcnt(0)
	v_pk_fma_f32 v[52:53], v[52:53], v[68:69], v[76:77]
	v_pk_fma_f32 v[48:49], v[48:49], v[70:71], v[78:79]
	v_pk_fma_f32 v[56:57], v[56:57], v[66:67], v[74:75]
	v_cvt_pk_bf16_f32 v64, v52, v53
	v_cvt_pk_bf16_f32 v65, v48, v49
	v_cvt_pk_bf16_f32 v66, v60, v61
	v_cvt_pk_bf16_f32 v67, v56, v57
	global_store_dwordx4 v[80:81], v[64:67], off offset:2048
	s_nop 0
	ds_read_b128 v[64:67], v195 offset:6160
	s_nop 0
	ds_read_b128 v[68:71], v195 offset:6144
	ds_read_b128 v[72:75], v195 offset:14352
	ds_read_b128 v[76:79], v195 offset:14336
	v_pk_mul_f32 v[48:49], v[50:51], v[82:83] op_sel_hi:[1,0]
	v_pk_mul_f32 v[50:51], v[58:59], v[82:83] op_sel_hi:[1,0]
	v_pk_mul_f32 v[52:53], v[54:55], v[82:83] op_sel_hi:[1,0]
	v_pk_mul_f32 v[54:55], v[62:63], v[82:83] op_sel_hi:[1,0]
	s_waitcnt lgkmcnt(1)
	v_pk_fma_f32 v[50:51], v[50:51], v[64:65], v[72:73]
	s_waitcnt lgkmcnt(0)
	v_pk_fma_f32 v[48:49], v[48:49], v[68:69], v[76:77]
	v_pk_fma_f32 v[52:53], v[52:53], v[70:71], v[78:79]
	v_pk_fma_f32 v[54:55], v[54:55], v[66:67], v[74:75]
	v_cvt_pk_bf16_f32 v48, v48, v49
	v_cvt_pk_bf16_f32 v49, v52, v53
	v_cvt_pk_bf16_f32 v50, v50, v51
	v_cvt_pk_bf16_f32 v51, v54, v55
	global_store_dwordx4 v[80:81], v[48:51], off offset:3072
	s_waitcnt vmcnt(33)
	v_cvt_f32_f16_sdwa v55, v41 dst_sel:DWORD dst_unused:UNUSED_PAD src0_sel:WORD_1
	v_cvt_f32_f16_e32 v54, v41
	v_cvt_f32_f16_sdwa v51, v45 dst_sel:DWORD dst_unused:UNUSED_PAD src0_sel:WORD_1
	v_cvt_f32_f16_e32 v50, v45
	v_cvt_f32_f16_sdwa v45, v44 dst_sel:DWORD dst_unused:UNUSED_PAD src0_sel:WORD_1
	v_cvt_f32_f16_e32 v44, v44
	v_cvt_f32_f16_sdwa v49, v47 dst_sel:DWORD dst_unused:UNUSED_PAD src0_sel:WORD_1
	v_cvt_f32_f16_e32 v48, v47
	v_cvt_f32_f16_sdwa v47, v46 dst_sel:DWORD dst_unused:UNUSED_PAD src0_sel:WORD_1
	v_cvt_f32_f16_e32 v46, v46
	v_add_f32_e32 v52, 0, v44
	v_add_f32_e32 v52, v52, v45
	v_add_f32_e32 v52, v52, v50
	v_add_f32_e32 v52, v52, v51
	v_add_f32_e32 v52, v52, v46
	v_cvt_f32_f16_sdwa v41, v40 dst_sel:DWORD dst_unused:UNUSED_PAD src0_sel:WORD_1
	v_cvt_f32_f16_e32 v40, v40
	v_add_f32_e32 v52, v52, v47
	v_add_f32_e32 v52, v52, v48
	v_add_f32_e32 v56, v52, v49
	v_cvt_f32_f16_sdwa v53, v43 dst_sel:DWORD dst_unused:UNUSED_PAD src0_sel:WORD_1
	v_cvt_f32_f16_e32 v52, v43
	v_cvt_f32_f16_sdwa v43, v42 dst_sel:DWORD dst_unused:UNUSED_PAD src0_sel:WORD_1
	v_cvt_f32_f16_e32 v42, v42
	v_add_f32_e32 v56, v56, v40
	v_add_f32_e32 v56, v56, v41
	v_add_f32_e32 v56, v56, v54
	v_add_f32_e32 v56, v56, v55
	v_add_f32_e32 v56, v56, v42
	v_cvt_f32_f16_sdwa v69, v37 dst_sel:DWORD dst_unused:UNUSED_PAD src0_sel:WORD_1
	v_cvt_f32_f16_e32 v68, v37
	v_cvt_f32_f16_sdwa v37, v36 dst_sel:DWORD dst_unused:UNUSED_PAD src0_sel:WORD_1
	v_cvt_f32_f16_e32 v36, v36
	v_add_f32_e32 v56, v56, v43
	v_add_f32_e32 v56, v56, v52
	v_add_f32_e32 v56, v56, v53
	v_cvt_f32_f16_sdwa v67, v39 dst_sel:DWORD dst_unused:UNUSED_PAD src0_sel:WORD_1
	v_cvt_f32_f16_e32 v66, v39
	v_cvt_f32_f16_sdwa v39, v38 dst_sel:DWORD dst_unused:UNUSED_PAD src0_sel:WORD_1
	v_cvt_f32_f16_e32 v38, v38
	v_add_f32_e32 v56, v56, v36
	v_add_f32_e32 v56, v56, v37
	v_add_f32_e32 v56, v56, v68
	v_add_f32_e32 v56, v56, v69
	v_add_f32_e32 v56, v56, v38
	v_cvt_f32_f16_sdwa v73, v34 dst_sel:DWORD dst_unused:UNUSED_PAD src0_sel:WORD_1
	v_cvt_f32_f16_e32 v72, v34
	v_cvt_f32_f16_e32 v34, v32
	v_add_f32_e32 v56, v56, v39
	v_cvt_f32_f16_sdwa v71, v35 dst_sel:DWORD dst_unused:UNUSED_PAD src0_sel:WORD_1
	v_cvt_f32_f16_e32 v70, v35
	v_cvt_f32_f16_sdwa v35, v32 dst_sel:DWORD dst_unused:UNUSED_PAD src0_sel:WORD_1
	v_add_f32_e32 v56, v56, v66
	v_cvt_f32_f16_e32 v74, v33
	v_add_f32_e32 v56, v56, v67
	v_cvt_f32_f16_sdwa v75, v33 dst_sel:DWORD dst_unused:UNUSED_PAD src0_sel:WORD_1
	v_add_f32_e32 v32, v56, v34
	v_add_f32_e32 v32, v32, v35
	v_add_f32_e32 v32, v32, v74
	v_add_f32_e32 v32, v32, v75
	v_add_f32_e32 v32, v32, v72
	v_add_f32_e32 v32, v32, v73
	v_add_f32_e32 v32, v32, v70
	v_add_f32_e32 v32, v32, v71
	s_nop 1
	v_add_f32_dpp v32, v32, v32 quad_perm:[1,0,3,2] row_mask:0xf bank_mask:0xf bound_ctrl:1
	s_nop 1
	v_add_f32_dpp v32, v32, v32 quad_perm:[2,3,0,1] row_mask:0xf bank_mask:0xf bound_ctrl:1
	s_nop 1
	v_add_f32_dpp v32, v32, v32 row_half_mirror row_mask:0xf bank_mask:0xf bound_ctrl:1
	s_nop 1
	v_add_f32_dpp v32, v32, v32 row_mirror row_mask:0xf bank_mask:0xf bound_ctrl:1
	s_nop 0
	v_readlane_b32 s0, v32, 16
	v_readlane_b32 s7, v32, 48
	v_readlane_b32 s2, v32, 0
	v_readlane_b32 s3, v32, 32
	v_mov_b32_e32 v32, s0
	v_mov_b32_e32 v33, s7
	v_pk_add_f32 v[32:33], s[2:3], v[32:33]
	s_nop 0
	v_add_f32_e32 v32, v32, v33
	v_mul_f32_e32 v64, 0x3a000000, v32
	v_pk_add_f32 v[58:59], v[44:45], v[64:65] op_sel_hi:[1,0] neg_lo:[0,1] neg_hi:[0,1]
	v_pk_add_f32 v[56:57], v[50:51], v[64:65] op_sel_hi:[1,0] neg_lo:[0,1] neg_hi:[0,1]
	v_pk_mul_f32 v[76:77], v[58:59], v[58:59]
	v_pk_mul_f32 v[78:79], v[56:57], v[56:57]
	v_pk_add_f32 v[62:63], v[46:47], v[64:65] op_sel_hi:[1,0] neg_lo:[0,1] neg_hi:[0,1]
	v_pk_add_f32 v[60:61], v[48:49], v[64:65] op_sel_hi:[1,0] neg_lo:[0,1] neg_hi:[0,1]
	v_pk_add_f32 v[50:51], v[40:41], v[64:65] op_sel_hi:[1,0] neg_lo:[0,1] neg_hi:[0,1]
	v_pk_add_f32 v[48:49], v[54:55], v[64:65] op_sel_hi:[1,0] neg_lo:[0,1] neg_hi:[0,1]
	v_pk_add_f32 v[54:55], v[42:43], v[64:65] op_sel_hi:[1,0] neg_lo:[0,1] neg_hi:[0,1]
	v_pk_add_f32 v[52:53], v[52:53], v[64:65] op_sel_hi:[1,0] neg_lo:[0,1] neg_hi:[0,1]
	v_pk_add_f32 v[36:37], v[36:37], v[64:65] op_sel_hi:[1,0] neg_lo:[0,1] neg_hi:[0,1]
	v_pk_add_f32 v[32:33], v[68:69], v[64:65] op_sel_hi:[1,0] neg_lo:[0,1] neg_hi:[0,1]
	v_pk_add_f32 v[44:45], v[38:39], v[64:65] op_sel_hi:[1,0] neg_lo:[0,1] neg_hi:[0,1]
	v_pk_add_f32 v[40:41], v[66:67], v[64:65] op_sel_hi:[1,0] neg_lo:[0,1] neg_hi:[0,1]
	v_pk_add_f32 v[34:35], v[34:35], v[64:65] op_sel_hi:[1,0] neg_lo:[0,1] neg_hi:[0,1]
	v_pk_add_f32 v[38:39], v[74:75], v[64:65] op_sel_hi:[1,0] neg_lo:[0,1] neg_hi:[0,1]
	v_pk_add_f32 v[42:43], v[72:73], v[64:65] op_sel_hi:[1,0] neg_lo:[0,1] neg_hi:[0,1]
	v_pk_add_f32 v[46:47], v[70:71], v[64:65] op_sel_hi:[1,0] neg_lo:[0,1] neg_hi:[0,1]
	v_add_f32_e32 v65, v76, v77
	v_add_f32_e32 v65, v78, v65
	v_pk_mul_f32 v[80:81], v[62:63], v[62:63]
	v_add_f32_e32 v65, v79, v65
	v_add_f32_e32 v65, v80, v65
	v_pk_mul_f32 v[82:83], v[60:61], v[60:61]
	v_add_f32_e32 v65, v81, v65
	v_add_f32_e32 v65, v82, v65
	v_pk_mul_f32 v[84:85], v[50:51], v[50:51]
	v_add_f32_e32 v65, v83, v65
	v_add_f32_e32 v65, v84, v65
	v_pk_mul_f32 v[86:87], v[48:49], v[48:49]
	v_add_f32_e32 v65, v85, v65
	v_add_f32_e32 v65, v86, v65
	v_pk_mul_f32 v[88:89], v[54:55], v[54:55]
	v_add_f32_e32 v65, v87, v65
	v_add_f32_e32 v65, v88, v65
	v_pk_mul_f32 v[90:91], v[52:53], v[52:53]
	v_add_f32_e32 v65, v89, v65
	v_add_f32_e32 v65, v90, v65
	v_pk_mul_f32 v[92:93], v[36:37], v[36:37]
	v_add_f32_e32 v65, v91, v65
	v_add_f32_e32 v65, v92, v65
	v_pk_mul_f32 v[68:69], v[32:33], v[32:33]
	v_add_f32_e32 v65, v93, v65
	v_add_f32_e32 v65, v68, v65
	v_pk_mul_f32 v[94:95], v[44:45], v[44:45]
	v_add_f32_e32 v65, v69, v65
	v_add_f32_e32 v65, v94, v65
	v_pk_mul_f32 v[66:67], v[40:41], v[40:41]
	v_add_f32_e32 v65, v95, v65
	v_add_f32_e32 v65, v66, v65
	v_pk_mul_f32 v[96:97], v[34:35], v[34:35]
	v_add_f32_e32 v65, v67, v65
	v_add_f32_e32 v65, v96, v65
	v_pk_mul_f32 v[74:75], v[38:39], v[38:39]
	v_add_f32_e32 v65, v97, v65
	v_add_f32_e32 v65, v74, v65
	v_pk_mul_f32 v[72:73], v[42:43], v[42:43]
	v_add_f32_e32 v65, v75, v65
	v_add_f32_e32 v65, v72, v65
	v_pk_mul_f32 v[70:71], v[46:47], v[46:47]
	v_add_f32_e32 v65, v73, v65
	v_add_f32_e32 v65, v70, v65
	v_add_f32_e32 v65, v71, v65
	s_nop 1
	v_add_f32_dpp v65, v65, v65 quad_perm:[1,0,3,2] row_mask:0xf bank_mask:0xf bound_ctrl:1
	s_nop 1
	v_add_f32_dpp v65, v65, v65 quad_perm:[2,3,0,1] row_mask:0xf bank_mask:0xf bound_ctrl:1
	s_nop 1
	v_add_f32_dpp v65, v65, v65 row_half_mirror row_mask:0xf bank_mask:0xf bound_ctrl:1
	s_nop 1
	v_add_f32_dpp v65, v65, v65 row_mirror row_mask:0xf bank_mask:0xf bound_ctrl:1
	s_nop 0
	v_readlane_b32 s2, v65, 16
	v_readlane_b32 s0, v65, 0
	s_nop 0
	v_mov_b32_e32 v66, s2
	v_readlane_b32 s2, v65, 48
	v_add_f32_e32 v66, s0, v66
	v_readlane_b32 s0, v65, 32
	v_mov_b32_e32 v65, s2
	s_nop 0
	v_add_f32_e32 v65, s0, v65
	v_add_f32_e32 v65, v66, v65
	v_fmamk_f32 v65, v65, 0x3a000000, v245
	v_cmp_gt_f32_e32 vcc, s87, v65
	v_mul_f32_e32 v66, 0x4f800000, v65
	s_nop 0
	v_cndmask_b32_e32 v65, v65, v66, vcc
	v_sqrt_f32_e32 v66, v65
	s_nop 0
	v_add_u32_e32 v67, -1, v66
	v_fma_f32 v68, -v67, v66, v65
	v_cmp_ge_f32_e64 s[40:41], 0, v68
	v_add_u32_e32 v68, 1, v66
	s_nop 0
	v_cndmask_b32_e64 v67, v66, v67, s[40:41]
	v_fma_f32 v66, -v68, v66, v65
	v_cmp_lt_f32_e64 s[40:41], 0, v66
	s_nop 1
	v_cndmask_b32_e64 v66, v67, v68, s[40:41]
	v_mul_f32_e32 v67, 0x37800000, v66
	v_cndmask_b32_e32 v66, v66, v67, vcc
	v_cmp_class_f32_e32 vcc, v65, v243
	s_nop 1
	v_cndmask_b32_e32 v65, v66, v65, vcc
	v_div_scale_f32 v66, s[2:3], v65, v65, 1.0
	v_rcp_f32_e32 v67, v66
	s_nop 0
	v_fma_f32 v68, -v66, v67, 1.0
	v_fmac_f32_e32 v67, v68, v67
	v_div_scale_f32 v68, vcc, 1.0, v65, 1.0
	v_mul_f32_e32 v69, v68, v67
	v_fma_f32 v70, -v66, v69, v68
	v_fmac_f32_e32 v69, v70, v67
	v_fma_f32 v66, -v66, v69, v68
	v_div_fmas_f32 v66, v66, v67, v69
	v_div_fixup_f32 v66, v66, v65, 1.0
	s_and_saveexec_b64 s[8:9], s[42:43]
	s_cbranch_execz .LBB0_1974
	s_ashr_i32 s45, s44, 31
	s_lshl_b64 s[2:3], s[44:45], 2
	s_add_u32 s2, s12, s2
	v_mov_b32_e32 v65, v66
	s_addc_u32 s3, s13, s3
	global_store_dwordx2 v225, v[64:65], s[2:3] offset:40
.LBB0_1974:
	s_or_b64 exec, exec, s[8:9]
	s_nop 0
	ds_read_b128 v[68:71], v195 offset:16
	ds_read_b128 v[72:75], v195 offset:0
	ds_read_b128 v[76:79], v195 offset:8208
	ds_read_b128 v[80:83], v195 offset:8192
	v_pk_mul_f32 v[56:57], v[56:57], v[66:67] op_sel_hi:[1,0]
	v_pk_mul_f32 v[58:59], v[58:59], v[66:67] op_sel_hi:[1,0]
	v_pk_mul_f32 v[62:63], v[62:63], v[66:67] op_sel_hi:[1,0]
	v_pk_mul_f32 v[60:61], v[60:61], v[66:67] op_sel_hi:[1,0]
	s_mov_b32 s0, 0x16b05000
	v_pk_mul_f32 v[50:51], v[50:51], v[66:67] op_sel_hi:[1,0]
	v_pk_mul_f32 v[54:55], v[54:55], v[66:67] op_sel_hi:[1,0]
	v_pk_mul_f32 v[48:49], v[48:49], v[66:67] op_sel_hi:[1,0]
	v_pk_mul_f32 v[52:53], v[52:53], v[66:67] op_sel_hi:[1,0]
	v_pk_mul_f32 v[36:37], v[36:37], v[66:67] op_sel_hi:[1,0]
	v_pk_mul_f32 v[44:45], v[44:45], v[66:67] op_sel_hi:[1,0]
	v_pk_mul_f32 v[32:33], v[32:33], v[66:67] op_sel_hi:[1,0]
	v_pk_mul_f32 v[40:41], v[40:41], v[66:67] op_sel_hi:[1,0]
	s_waitcnt lgkmcnt(1)
	v_pk_fma_f32 v[62:63], v[62:63], v[68:69], v[76:77]
	s_waitcnt lgkmcnt(0)
	v_pk_fma_f32 v[64:65], v[56:57], v[74:75], v[82:83]
	v_pk_fma_f32 v[58:59], v[58:59], v[72:73], v[80:81]
	v_pk_fma_f32 v[60:61], v[60:61], v[70:71], v[78:79]
	v_cvt_pk_bf16_f32 v57, v64, v65
	v_add_co_u32_e32 v64, vcc, s0, v112
	v_cvt_pk_bf16_f32 v56, v58, v59
	v_cvt_pk_bf16_f32 v58, v62, v63
	v_cvt_pk_bf16_f32 v59, v60, v61
	v_addc_co_u32_e32 v65, vcc, 0, v113, vcc
	global_store_dwordx4 v[64:65], v[56:59], off
	s_nop 0
	ds_read_b128 v[56:59], v195 offset:2064
	s_nop 0
	ds_read_b128 v[60:63], v195 offset:2048
	ds_read_b128 v[68:71], v195 offset:10256
	ds_read_b128 v[72:75], v195 offset:10240
	s_waitcnt lgkmcnt(1)
	v_pk_fma_f32 v[54:55], v[54:55], v[56:57], v[68:69]
	s_waitcnt lgkmcnt(0)
	v_pk_fma_f32 v[50:51], v[50:51], v[60:61], v[72:73]
	v_pk_fma_f32 v[56:57], v[48:49], v[62:63], v[74:75]
	v_pk_fma_f32 v[52:53], v[52:53], v[58:59], v[70:71]
	v_cvt_pk_bf16_f32 v48, v50, v51
	v_cvt_pk_bf16_f32 v49, v56, v57
	v_cvt_pk_bf16_f32 v50, v54, v55
	v_cvt_pk_bf16_f32 v51, v52, v53
	global_store_dwordx4 v[64:65], v[48:51], off offset:1024
	s_nop 0
	ds_read_b128 v[48:51], v195 offset:4112
	s_nop 0
	ds_read_b128 v[52:55], v195 offset:4096
	ds_read_b128 v[56:59], v195 offset:12304
	ds_read_b128 v[60:63], v195 offset:12288
	s_waitcnt lgkmcnt(1)
	v_pk_fma_f32 v[44:45], v[44:45], v[48:49], v[56:57]
	s_waitcnt lgkmcnt(0)
	v_pk_fma_f32 v[36:37], v[36:37], v[52:53], v[60:61]
	v_pk_fma_f32 v[32:33], v[32:33], v[54:55], v[62:63]
	v_pk_fma_f32 v[40:41], v[40:41], v[50:51], v[58:59]
	v_cvt_pk_bf16_f32 v48, v36, v37
	v_cvt_pk_bf16_f32 v49, v32, v33
	v_cvt_pk_bf16_f32 v50, v44, v45
	v_cvt_pk_bf16_f32 v51, v40, v41
	global_store_dwordx4 v[64:65], v[48:51], off offset:2048
	s_nop 0
	ds_read_b128 v[48:51], v195 offset:6160
	s_nop 0
	ds_read_b128 v[52:55], v195 offset:6144
	ds_read_b128 v[56:59], v195 offset:14352
	ds_read_b128 v[60:63], v195 offset:14336
	v_pk_mul_f32 v[32:33], v[34:35], v[66:67] op_sel_hi:[1,0]
	v_pk_mul_f32 v[34:35], v[42:43], v[66:67] op_sel_hi:[1,0]
	v_pk_mul_f32 v[36:37], v[38:39], v[66:67] op_sel_hi:[1,0]
	v_pk_mul_f32 v[38:39], v[46:47], v[66:67] op_sel_hi:[1,0]
	s_waitcnt lgkmcnt(1)
	v_pk_fma_f32 v[34:35], v[34:35], v[48:49], v[56:57]
	s_waitcnt lgkmcnt(0)
	v_pk_fma_f32 v[32:33], v[32:33], v[52:53], v[60:61]
	v_pk_fma_f32 v[36:37], v[36:37], v[54:55], v[62:63]
	v_pk_fma_f32 v[38:39], v[38:39], v[50:51], v[58:59]
	v_cvt_pk_bf16_f32 v32, v32, v33
	v_cvt_pk_bf16_f32 v33, v36, v37
	v_cvt_pk_bf16_f32 v34, v34, v35
	v_cvt_pk_bf16_f32 v35, v38, v39
	global_store_dwordx4 v[64:65], v[32:35], off offset:3072
	s_waitcnt vmcnt(34)
	v_cvt_f32_f16_sdwa v39, v25 dst_sel:DWORD dst_unused:UNUSED_PAD src0_sel:WORD_1
	v_cvt_f32_f16_e32 v38, v25
	v_cvt_f32_f16_sdwa v35, v29 dst_sel:DWORD dst_unused:UNUSED_PAD src0_sel:WORD_1
	v_cvt_f32_f16_e32 v34, v29
	v_cvt_f32_f16_sdwa v29, v28 dst_sel:DWORD dst_unused:UNUSED_PAD src0_sel:WORD_1
	v_cvt_f32_f16_e32 v28, v28
	v_cvt_f32_f16_sdwa v33, v31 dst_sel:DWORD dst_unused:UNUSED_PAD src0_sel:WORD_1
	v_cvt_f32_f16_e32 v32, v31
	v_cvt_f32_f16_sdwa v31, v30 dst_sel:DWORD dst_unused:UNUSED_PAD src0_sel:WORD_1
	v_cvt_f32_f16_e32 v30, v30
	v_add_f32_e32 v36, 0, v28
	v_add_f32_e32 v36, v36, v29
	v_add_f32_e32 v36, v36, v34
	v_add_f32_e32 v36, v36, v35
	v_add_f32_e32 v36, v36, v30
	v_cvt_f32_f16_sdwa v25, v24 dst_sel:DWORD dst_unused:UNUSED_PAD src0_sel:WORD_1
	v_cvt_f32_f16_e32 v24, v24
	v_add_f32_e32 v36, v36, v31
	v_add_f32_e32 v36, v36, v32
	v_add_f32_e32 v40, v36, v33
	v_cvt_f32_f16_sdwa v37, v27 dst_sel:DWORD dst_unused:UNUSED_PAD src0_sel:WORD_1
	v_cvt_f32_f16_e32 v36, v27
	v_cvt_f32_f16_sdwa v27, v26 dst_sel:DWORD dst_unused:UNUSED_PAD src0_sel:WORD_1
	v_cvt_f32_f16_e32 v26, v26
	v_add_f32_e32 v40, v40, v24
	v_add_f32_e32 v40, v40, v25
	v_add_f32_e32 v40, v40, v38
	v_add_f32_e32 v40, v40, v39
	v_add_f32_e32 v40, v40, v26
	v_cvt_f32_f16_sdwa v53, v21 dst_sel:DWORD dst_unused:UNUSED_PAD src0_sel:WORD_1
	v_cvt_f32_f16_e32 v52, v21
	v_cvt_f32_f16_sdwa v21, v20 dst_sel:DWORD dst_unused:UNUSED_PAD src0_sel:WORD_1
	v_cvt_f32_f16_e32 v20, v20
	v_add_f32_e32 v40, v40, v27
	v_add_f32_e32 v40, v40, v36
	v_add_f32_e32 v40, v40, v37
	v_cvt_f32_f16_sdwa v51, v23 dst_sel:DWORD dst_unused:UNUSED_PAD src0_sel:WORD_1
	v_cvt_f32_f16_e32 v50, v23
	v_cvt_f32_f16_sdwa v23, v22 dst_sel:DWORD dst_unused:UNUSED_PAD src0_sel:WORD_1
	v_cvt_f32_f16_e32 v22, v22
	v_add_f32_e32 v40, v40, v20
	v_add_f32_e32 v40, v40, v21
	v_add_f32_e32 v40, v40, v52
	v_add_f32_e32 v40, v40, v53
	v_add_f32_e32 v40, v40, v22
	v_cvt_f32_f16_sdwa v57, v18 dst_sel:DWORD dst_unused:UNUSED_PAD src0_sel:WORD_1
	v_cvt_f32_f16_e32 v56, v18
	v_cvt_f32_f16_e32 v18, v16
	v_add_f32_e32 v40, v40, v23
	v_cvt_f32_f16_sdwa v55, v19 dst_sel:DWORD dst_unused:UNUSED_PAD src0_sel:WORD_1
	v_cvt_f32_f16_e32 v54, v19
	v_cvt_f32_f16_sdwa v19, v16 dst_sel:DWORD dst_unused:UNUSED_PAD src0_sel:WORD_1
	v_add_f32_e32 v40, v40, v50
	v_cvt_f32_f16_e32 v58, v17
	v_add_f32_e32 v40, v40, v51
	v_cvt_f32_f16_sdwa v59, v17 dst_sel:DWORD dst_unused:UNUSED_PAD src0_sel:WORD_1
	v_add_f32_e32 v16, v40, v18
	v_add_f32_e32 v16, v16, v19
	v_add_f32_e32 v16, v16, v58
	v_add_f32_e32 v16, v16, v59
	v_add_f32_e32 v16, v16, v56
	v_add_f32_e32 v16, v16, v57
	v_add_f32_e32 v16, v16, v54
	v_add_f32_e32 v16, v16, v55
	s_nop 1
	v_add_f32_dpp v16, v16, v16 quad_perm:[1,0,3,2] row_mask:0xf bank_mask:0xf bound_ctrl:1
	s_nop 1
	v_add_f32_dpp v16, v16, v16 quad_perm:[2,3,0,1] row_mask:0xf bank_mask:0xf bound_ctrl:1
	s_nop 1
	v_add_f32_dpp v16, v16, v16 row_half_mirror row_mask:0xf bank_mask:0xf bound_ctrl:1
	s_nop 1
	v_add_f32_dpp v16, v16, v16 row_mirror row_mask:0xf bank_mask:0xf bound_ctrl:1
	s_nop 0
	v_readlane_b32 s0, v16, 16
	v_readlane_b32 s7, v16, 48
	v_readlane_b32 s2, v16, 0
	v_readlane_b32 s3, v16, 32
	v_mov_b32_e32 v16, s0
	v_mov_b32_e32 v17, s7
	v_pk_add_f32 v[16:17], s[2:3], v[16:17]
	s_nop 0
	v_add_f32_e32 v16, v16, v17
	v_mul_f32_e32 v48, 0x3a000000, v16
	v_pk_add_f32 v[42:43], v[28:29], v[48:49] op_sel_hi:[1,0] neg_lo:[0,1] neg_hi:[0,1]
	v_pk_add_f32 v[40:41], v[34:35], v[48:49] op_sel_hi:[1,0] neg_lo:[0,1] neg_hi:[0,1]
	v_pk_mul_f32 v[60:61], v[42:43], v[42:43]
	v_pk_mul_f32 v[62:63], v[40:41], v[40:41]
	v_pk_add_f32 v[46:47], v[30:31], v[48:49] op_sel_hi:[1,0] neg_lo:[0,1] neg_hi:[0,1]
	v_pk_add_f32 v[44:45], v[32:33], v[48:49] op_sel_hi:[1,0] neg_lo:[0,1] neg_hi:[0,1]
	v_pk_add_f32 v[34:35], v[24:25], v[48:49] op_sel_hi:[1,0] neg_lo:[0,1] neg_hi:[0,1]
	v_pk_add_f32 v[32:33], v[38:39], v[48:49] op_sel_hi:[1,0] neg_lo:[0,1] neg_hi:[0,1]
	v_pk_add_f32 v[38:39], v[26:27], v[48:49] op_sel_hi:[1,0] neg_lo:[0,1] neg_hi:[0,1]
	v_pk_add_f32 v[36:37], v[36:37], v[48:49] op_sel_hi:[1,0] neg_lo:[0,1] neg_hi:[0,1]
	v_pk_add_f32 v[20:21], v[20:21], v[48:49] op_sel_hi:[1,0] neg_lo:[0,1] neg_hi:[0,1]
	v_pk_add_f32 v[16:17], v[52:53], v[48:49] op_sel_hi:[1,0] neg_lo:[0,1] neg_hi:[0,1]
	v_pk_add_f32 v[28:29], v[22:23], v[48:49] op_sel_hi:[1,0] neg_lo:[0,1] neg_hi:[0,1]
	v_pk_add_f32 v[24:25], v[50:51], v[48:49] op_sel_hi:[1,0] neg_lo:[0,1] neg_hi:[0,1]
	v_pk_add_f32 v[18:19], v[18:19], v[48:49] op_sel_hi:[1,0] neg_lo:[0,1] neg_hi:[0,1]
	v_pk_add_f32 v[22:23], v[58:59], v[48:49] op_sel_hi:[1,0] neg_lo:[0,1] neg_hi:[0,1]
	v_pk_add_f32 v[26:27], v[56:57], v[48:49] op_sel_hi:[1,0] neg_lo:[0,1] neg_hi:[0,1]
	v_pk_add_f32 v[30:31], v[54:55], v[48:49] op_sel_hi:[1,0] neg_lo:[0,1] neg_hi:[0,1]
	v_add_f32_e32 v49, v60, v61
	v_add_f32_e32 v49, v62, v49
	v_pk_mul_f32 v[64:65], v[46:47], v[46:47]
	v_add_f32_e32 v49, v63, v49
	v_add_f32_e32 v49, v64, v49
	v_pk_mul_f32 v[66:67], v[44:45], v[44:45]
	v_add_f32_e32 v49, v65, v49
	v_add_f32_e32 v49, v66, v49
	v_pk_mul_f32 v[68:69], v[34:35], v[34:35]
	v_add_f32_e32 v49, v67, v49
	v_add_f32_e32 v49, v68, v49
	v_pk_mul_f32 v[70:71], v[32:33], v[32:33]
	v_add_f32_e32 v49, v69, v49
	v_add_f32_e32 v49, v70, v49
	v_pk_mul_f32 v[72:73], v[38:39], v[38:39]
	v_add_f32_e32 v49, v71, v49
	v_add_f32_e32 v49, v72, v49
	v_pk_mul_f32 v[74:75], v[36:37], v[36:37]
	v_add_f32_e32 v49, v73, v49
	v_add_f32_e32 v49, v74, v49
	v_pk_mul_f32 v[76:77], v[20:21], v[20:21]
	v_add_f32_e32 v49, v75, v49
	v_add_f32_e32 v49, v76, v49
	v_pk_mul_f32 v[52:53], v[16:17], v[16:17]
	v_add_f32_e32 v49, v77, v49
	v_add_f32_e32 v49, v52, v49
	v_pk_mul_f32 v[78:79], v[28:29], v[28:29]
	v_add_f32_e32 v49, v53, v49
	v_add_f32_e32 v49, v78, v49
	v_pk_mul_f32 v[50:51], v[24:25], v[24:25]
	v_add_f32_e32 v49, v79, v49
	v_add_f32_e32 v49, v50, v49
	v_pk_mul_f32 v[80:81], v[18:19], v[18:19]
	v_add_f32_e32 v49, v51, v49
	v_add_f32_e32 v49, v80, v49
	v_pk_mul_f32 v[58:59], v[22:23], v[22:23]
	v_add_f32_e32 v49, v81, v49
	v_add_f32_e32 v49, v58, v49
	v_pk_mul_f32 v[56:57], v[26:27], v[26:27]
	v_add_f32_e32 v49, v59, v49
	v_add_f32_e32 v49, v56, v49
	v_pk_mul_f32 v[54:55], v[30:31], v[30:31]
	v_add_f32_e32 v49, v57, v49
	v_add_f32_e32 v49, v54, v49
	v_add_f32_e32 v49, v55, v49
	s_nop 1
	v_add_f32_dpp v49, v49, v49 quad_perm:[1,0,3,2] row_mask:0xf bank_mask:0xf bound_ctrl:1
	s_nop 1
	v_add_f32_dpp v49, v49, v49 quad_perm:[2,3,0,1] row_mask:0xf bank_mask:0xf bound_ctrl:1
	s_nop 1
	v_add_f32_dpp v49, v49, v49 row_half_mirror row_mask:0xf bank_mask:0xf bound_ctrl:1
	s_nop 1
	v_add_f32_dpp v49, v49, v49 row_mirror row_mask:0xf bank_mask:0xf bound_ctrl:1
	s_nop 0
	v_readlane_b32 s2, v49, 16
	v_readlane_b32 s0, v49, 0
	s_nop 0
	v_mov_b32_e32 v50, s2
	v_readlane_b32 s2, v49, 48
	v_add_f32_e32 v50, s0, v50
	v_readlane_b32 s0, v49, 32
	v_mov_b32_e32 v49, s2
	s_nop 0
	v_add_f32_e32 v49, s0, v49
	v_add_f32_e32 v49, v50, v49
	v_fmamk_f32 v49, v49, 0x3a000000, v245
	v_cmp_gt_f32_e32 vcc, s87, v49
	v_mul_f32_e32 v50, 0x4f800000, v49
	s_nop 0
	v_cndmask_b32_e32 v49, v49, v50, vcc
	v_sqrt_f32_e32 v50, v49
	s_nop 0
	v_add_u32_e32 v51, -1, v50
	v_fma_f32 v52, -v51, v50, v49
	v_cmp_ge_f32_e64 s[40:41], 0, v52
	v_add_u32_e32 v52, 1, v50
	s_nop 0
	v_cndmask_b32_e64 v51, v50, v51, s[40:41]
	v_fma_f32 v50, -v52, v50, v49
	v_cmp_lt_f32_e64 s[40:41], 0, v50
	s_nop 1
	v_cndmask_b32_e64 v50, v51, v52, s[40:41]
	v_mul_f32_e32 v51, 0x37800000, v50
	v_cndmask_b32_e32 v50, v50, v51, vcc
	v_cmp_class_f32_e32 vcc, v49, v243
	s_nop 1
	v_cndmask_b32_e32 v49, v50, v49, vcc
	v_div_scale_f32 v50, s[2:3], v49, v49, 1.0
	v_rcp_f32_e32 v51, v50
	s_nop 0
	v_fma_f32 v52, -v50, v51, 1.0
	v_fmac_f32_e32 v51, v52, v51
	v_div_scale_f32 v52, vcc, 1.0, v49, 1.0
	v_mul_f32_e32 v53, v52, v51
	v_fma_f32 v54, -v50, v53, v52
	v_fmac_f32_e32 v53, v54, v51
	v_fma_f32 v50, -v50, v53, v52
	v_div_fmas_f32 v50, v50, v51, v53
	v_div_fixup_f32 v50, v50, v49, 1.0
	s_and_saveexec_b64 s[8:9], s[42:43]
	s_cbranch_execz .LBB0_1976
	s_ashr_i32 s45, s44, 31
	s_lshl_b64 s[2:3], s[44:45], 2
	s_add_u32 s2, s12, s2
	v_mov_b32_e32 v49, v50
	s_addc_u32 s3, s13, s3
	global_store_dwordx2 v225, v[48:49], s[2:3] offset:48
.LBB0_1976:
	s_or_b64 exec, exec, s[8:9]
	s_nop 0
	ds_read_b128 v[52:55], v195 offset:16
	ds_read_b128 v[56:59], v195 offset:0
	ds_read_b128 v[60:63], v195 offset:8208
	ds_read_b128 v[64:67], v195 offset:8192
	v_pk_mul_f32 v[40:41], v[40:41], v[50:51] op_sel_hi:[1,0]
	v_pk_mul_f32 v[42:43], v[42:43], v[50:51] op_sel_hi:[1,0]
	v_pk_mul_f32 v[46:47], v[46:47], v[50:51] op_sel_hi:[1,0]
	v_pk_mul_f32 v[44:45], v[44:45], v[50:51] op_sel_hi:[1,0]
	s_mov_b32 s0, 0x16b06000
	v_pk_mul_f32 v[34:35], v[34:35], v[50:51] op_sel_hi:[1,0]
	v_pk_mul_f32 v[38:39], v[38:39], v[50:51] op_sel_hi:[1,0]
	v_pk_mul_f32 v[32:33], v[32:33], v[50:51] op_sel_hi:[1,0]
	v_pk_mul_f32 v[36:37], v[36:37], v[50:51] op_sel_hi:[1,0]
	v_pk_mul_f32 v[20:21], v[20:21], v[50:51] op_sel_hi:[1,0]
	v_pk_mul_f32 v[28:29], v[28:29], v[50:51] op_sel_hi:[1,0]
	v_pk_mul_f32 v[16:17], v[16:17], v[50:51] op_sel_hi:[1,0]
	v_pk_mul_f32 v[24:25], v[24:25], v[50:51] op_sel_hi:[1,0]
	s_waitcnt lgkmcnt(1)
	v_pk_fma_f32 v[46:47], v[46:47], v[52:53], v[60:61]
	s_waitcnt lgkmcnt(0)
	v_pk_fma_f32 v[48:49], v[40:41], v[58:59], v[66:67]
	v_pk_fma_f32 v[42:43], v[42:43], v[56:57], v[64:65]
	v_pk_fma_f32 v[44:45], v[44:45], v[54:55], v[62:63]
	v_cvt_pk_bf16_f32 v41, v48, v49
	v_add_co_u32_e32 v48, vcc, s0, v112
	v_cvt_pk_bf16_f32 v40, v42, v43
	v_cvt_pk_bf16_f32 v42, v46, v47
	v_cvt_pk_bf16_f32 v43, v44, v45
	v_addc_co_u32_e32 v49, vcc, 0, v113, vcc
	global_store_dwordx4 v[48:49], v[40:43], off
	s_nop 0
	ds_read_b128 v[40:43], v195 offset:2064
	s_nop 0
	ds_read_b128 v[44:47], v195 offset:2048
	ds_read_b128 v[52:55], v195 offset:10256
	ds_read_b128 v[56:59], v195 offset:10240
	s_waitcnt lgkmcnt(1)
	v_pk_fma_f32 v[38:39], v[38:39], v[40:41], v[52:53]
	s_waitcnt lgkmcnt(0)
	v_pk_fma_f32 v[34:35], v[34:35], v[44:45], v[56:57]
	v_pk_fma_f32 v[40:41], v[32:33], v[46:47], v[58:59]
	v_pk_fma_f32 v[36:37], v[36:37], v[42:43], v[54:55]
	v_cvt_pk_bf16_f32 v32, v34, v35
	v_cvt_pk_bf16_f32 v33, v40, v41
	v_cvt_pk_bf16_f32 v34, v38, v39
	v_cvt_pk_bf16_f32 v35, v36, v37
	global_store_dwordx4 v[48:49], v[32:35], off offset:1024
	s_nop 0
	ds_read_b128 v[32:35], v195 offset:4112
	s_nop 0
	ds_read_b128 v[36:39], v195 offset:4096
	ds_read_b128 v[40:43], v195 offset:12304
	ds_read_b128 v[44:47], v195 offset:12288
	s_waitcnt lgkmcnt(1)
	v_pk_fma_f32 v[28:29], v[28:29], v[32:33], v[40:41]
	s_waitcnt lgkmcnt(0)
	v_pk_fma_f32 v[20:21], v[20:21], v[36:37], v[44:45]
	v_pk_fma_f32 v[16:17], v[16:17], v[38:39], v[46:47]
	v_pk_fma_f32 v[24:25], v[24:25], v[34:35], v[42:43]
	v_cvt_pk_bf16_f32 v32, v20, v21
	v_cvt_pk_bf16_f32 v33, v16, v17
	v_cvt_pk_bf16_f32 v34, v28, v29
	v_cvt_pk_bf16_f32 v35, v24, v25
	global_store_dwordx4 v[48:49], v[32:35], off offset:2048
	s_nop 0
	ds_read_b128 v[32:35], v195 offset:6160
	s_nop 0
	ds_read_b128 v[36:39], v195 offset:6144
	ds_read_b128 v[40:43], v195 offset:14352
	ds_read_b128 v[44:47], v195 offset:14336
	v_pk_mul_f32 v[16:17], v[18:19], v[50:51] op_sel_hi:[1,0]
	v_pk_mul_f32 v[18:19], v[26:27], v[50:51] op_sel_hi:[1,0]
	v_pk_mul_f32 v[20:21], v[22:23], v[50:51] op_sel_hi:[1,0]
	v_pk_mul_f32 v[22:23], v[30:31], v[50:51] op_sel_hi:[1,0]
	s_waitcnt lgkmcnt(1)
	v_pk_fma_f32 v[18:19], v[18:19], v[32:33], v[40:41]
	s_waitcnt lgkmcnt(0)
	v_pk_fma_f32 v[16:17], v[16:17], v[36:37], v[44:45]
	v_pk_fma_f32 v[20:21], v[20:21], v[38:39], v[46:47]
	v_pk_fma_f32 v[22:23], v[22:23], v[34:35], v[42:43]
	v_cvt_pk_bf16_f32 v16, v16, v17
	v_cvt_pk_bf16_f32 v17, v20, v21
	v_cvt_pk_bf16_f32 v18, v18, v19
	v_cvt_pk_bf16_f32 v19, v22, v23
	global_store_dwordx4 v[48:49], v[16:19], off offset:3072
	s_waitcnt vmcnt(35)
	v_cvt_f32_f16_sdwa v21, v9 dst_sel:DWORD dst_unused:UNUSED_PAD src0_sel:WORD_1
	v_cvt_f32_f16_sdwa v23, v11 dst_sel:DWORD dst_unused:UNUSED_PAD src0_sel:WORD_1
	v_cvt_f32_f16_sdwa v19, v13 dst_sel:DWORD dst_unused:UNUSED_PAD src0_sel:WORD_1
	v_cvt_f32_f16_e32 v18, v13
	v_cvt_f32_f16_sdwa v13, v12 dst_sel:DWORD dst_unused:UNUSED_PAD src0_sel:WORD_1
	v_cvt_f32_f16_e32 v12, v12
	v_cvt_f32_f16_sdwa v17, v15 dst_sel:DWORD dst_unused:UNUSED_PAD src0_sel:WORD_1
	v_cvt_f32_f16_e32 v16, v15
	v_cvt_f32_f16_sdwa v15, v14 dst_sel:DWORD dst_unused:UNUSED_PAD src0_sel:WORD_1
	v_cvt_f32_f16_e32 v14, v14
	v_add_f32_e32 v20, 0, v12
	v_add_f32_e32 v20, v20, v13
	v_add_f32_e32 v20, v20, v18
	v_add_f32_e32 v20, v20, v19
	v_add_f32_e32 v20, v20, v14
	v_add_f32_e32 v20, v20, v15
	v_add_f32_e32 v20, v20, v16
	v_add_f32_e32 v24, v20, v17
	v_cvt_f32_f16_e32 v20, v9
	v_cvt_f32_f16_sdwa v9, v8 dst_sel:DWORD dst_unused:UNUSED_PAD src0_sel:WORD_1
	v_cvt_f32_f16_e32 v8, v8
	v_cvt_f32_f16_e32 v22, v11
	v_cvt_f32_f16_sdwa v11, v10 dst_sel:DWORD dst_unused:UNUSED_PAD src0_sel:WORD_1
	v_cvt_f32_f16_e32 v10, v10
	v_add_f32_e32 v24, v24, v8
	v_add_f32_e32 v24, v24, v9
	v_add_f32_e32 v24, v24, v20
	v_add_f32_e32 v24, v24, v21
	v_add_f32_e32 v24, v24, v10
	v_cvt_f32_f16_sdwa v39, v5 dst_sel:DWORD dst_unused:UNUSED_PAD src0_sel:WORD_1
	v_cvt_f32_f16_e32 v38, v5
	v_cvt_f32_f16_sdwa v5, v4 dst_sel:DWORD dst_unused:UNUSED_PAD src0_sel:WORD_1
	v_cvt_f32_f16_e32 v4, v4
	v_add_f32_e32 v24, v24, v11
	v_add_f32_e32 v24, v24, v22
	v_add_f32_e32 v24, v24, v23
	v_cvt_f32_f16_sdwa v37, v6 dst_sel:DWORD dst_unused:UNUSED_PAD src0_sel:WORD_1
	v_cvt_f32_f16_e32 v36, v6
	v_add_f32_e32 v6, v24, v4
	v_add_f32_e32 v6, v6, v5
	v_cvt_f32_f16_e32 v34, v7
	v_add_f32_e32 v6, v6, v38
	v_cvt_f32_f16_sdwa v35, v7 dst_sel:DWORD dst_unused:UNUSED_PAD src0_sel:WORD_1
	v_add_f32_e32 v6, v6, v39
	v_add_f32_e32 v6, v6, v36
	v_cvt_f32_f16_sdwa v45, v1 dst_sel:DWORD dst_unused:UNUSED_PAD src0_sel:WORD_1
	v_cvt_f32_f16_e32 v44, v1
	v_cvt_f32_f16_sdwa v1, v0 dst_sel:DWORD dst_unused:UNUSED_PAD src0_sel:WORD_1
	v_cvt_f32_f16_e32 v0, v0
	v_add_f32_e32 v6, v6, v37
	v_add_f32_e32 v6, v6, v34
	v_add_f32_e32 v6, v6, v35
	v_cvt_f32_f16_sdwa v43, v2 dst_sel:DWORD dst_unused:UNUSED_PAD src0_sel:WORD_1
	v_cvt_f32_f16_e32 v42, v2
	v_add_f32_e32 v2, v6, v0
	v_add_f32_e32 v2, v2, v1
	v_cvt_f32_f16_e32 v40, v3
	v_add_f32_e32 v2, v2, v44
	v_cvt_f32_f16_sdwa v41, v3 dst_sel:DWORD dst_unused:UNUSED_PAD src0_sel:WORD_1
	v_add_f32_e32 v2, v2, v45
	v_add_f32_e32 v2, v2, v42
	v_add_f32_e32 v2, v2, v43
	v_add_f32_e32 v2, v2, v40
	v_add_f32_e32 v2, v2, v41
	s_nop 1
	v_add_f32_dpp v2, v2, v2 quad_perm:[1,0,3,2] row_mask:0xf bank_mask:0xf bound_ctrl:1
	s_nop 1
	v_add_f32_dpp v2, v2, v2 quad_perm:[2,3,0,1] row_mask:0xf bank_mask:0xf bound_ctrl:1
	s_nop 1
	v_add_f32_dpp v2, v2, v2 row_half_mirror row_mask:0xf bank_mask:0xf bound_ctrl:1
	s_nop 1
	v_add_f32_dpp v2, v2, v2 row_mirror row_mask:0xf bank_mask:0xf bound_ctrl:1
	s_nop 0
	v_readlane_b32 s0, v2, 16
	v_readlane_b32 s7, v2, 48
	v_readlane_b32 s2, v2, 0
	v_readlane_b32 s3, v2, 32
	v_mov_b32_e32 v2, s0
	v_mov_b32_e32 v3, s7
	v_pk_add_f32 v[2:3], s[2:3], v[2:3]
	s_nop 0
	v_add_f32_e32 v2, v2, v3
	v_mul_f32_e32 v28, 0x3a000000, v2
	v_pk_add_f32 v[24:25], v[12:13], v[28:29] op_sel_hi:[1,0] neg_lo:[0,1] neg_hi:[0,1]
	v_pk_add_f32 v[26:27], v[18:19], v[28:29] op_sel_hi:[1,0] neg_lo:[0,1] neg_hi:[0,1]
	v_pk_mul_f32 v[46:47], v[24:25], v[24:25]
	v_pk_mul_f32 v[48:49], v[26:27], v[26:27]
	v_pk_add_f32 v[30:31], v[14:15], v[28:29] op_sel_hi:[1,0] neg_lo:[0,1] neg_hi:[0,1]
	v_pk_add_f32 v[32:33], v[16:17], v[28:29] op_sel_hi:[1,0] neg_lo:[0,1] neg_hi:[0,1]
	v_pk_add_f32 v[12:13], v[8:9], v[28:29] op_sel_hi:[1,0] neg_lo:[0,1] neg_hi:[0,1]
	v_pk_add_f32 v[14:15], v[20:21], v[28:29] op_sel_hi:[1,0] neg_lo:[0,1] neg_hi:[0,1]
	v_pk_add_f32 v[20:21], v[10:11], v[28:29] op_sel_hi:[1,0] neg_lo:[0,1] neg_hi:[0,1]
	v_pk_add_f32 v[22:23], v[22:23], v[28:29] op_sel_hi:[1,0] neg_lo:[0,1] neg_hi:[0,1]
	v_pk_add_f32 v[4:5], v[4:5], v[28:29] op_sel_hi:[1,0] neg_lo:[0,1] neg_hi:[0,1]
	v_pk_add_f32 v[6:7], v[38:39], v[28:29] op_sel_hi:[1,0] neg_lo:[0,1] neg_hi:[0,1]
	v_pk_add_f32 v[16:17], v[36:37], v[28:29] op_sel_hi:[1,0] neg_lo:[0,1] neg_hi:[0,1]
	v_pk_add_f32 v[18:19], v[34:35], v[28:29] op_sel_hi:[1,0] neg_lo:[0,1] neg_hi:[0,1]
	v_pk_add_f32 v[0:1], v[0:1], v[28:29] op_sel_hi:[1,0] neg_lo:[0,1] neg_hi:[0,1]
	v_pk_add_f32 v[2:3], v[44:45], v[28:29] op_sel_hi:[1,0] neg_lo:[0,1] neg_hi:[0,1]
	v_pk_add_f32 v[8:9], v[42:43], v[28:29] op_sel_hi:[1,0] neg_lo:[0,1] neg_hi:[0,1]
	v_pk_add_f32 v[10:11], v[40:41], v[28:29] op_sel_hi:[1,0] neg_lo:[0,1] neg_hi:[0,1]
	v_add_f32_e32 v29, v46, v47
	v_add_f32_e32 v29, v48, v29
	v_pk_mul_f32 v[50:51], v[30:31], v[30:31]
	v_add_f32_e32 v29, v49, v29
	v_add_f32_e32 v29, v50, v29
	v_pk_mul_f32 v[52:53], v[32:33], v[32:33]
	v_add_f32_e32 v29, v51, v29
	v_add_f32_e32 v29, v52, v29
	v_pk_mul_f32 v[54:55], v[12:13], v[12:13]
	v_add_f32_e32 v29, v53, v29
	v_add_f32_e32 v29, v54, v29
	v_pk_mul_f32 v[56:57], v[14:15], v[14:15]
	v_add_f32_e32 v29, v55, v29
	v_add_f32_e32 v29, v56, v29
	v_pk_mul_f32 v[58:59], v[20:21], v[20:21]
	v_add_f32_e32 v29, v57, v29
	v_add_f32_e32 v29, v58, v29
	v_pk_mul_f32 v[60:61], v[22:23], v[22:23]
	v_add_f32_e32 v29, v59, v29
	v_add_f32_e32 v29, v60, v29
	v_pk_mul_f32 v[62:63], v[4:5], v[4:5]
	v_add_f32_e32 v29, v61, v29
	v_add_f32_e32 v29, v62, v29
	v_pk_mul_f32 v[38:39], v[6:7], v[6:7]
	v_add_f32_e32 v29, v63, v29
	v_add_f32_e32 v29, v38, v29
	v_pk_mul_f32 v[36:37], v[16:17], v[16:17]
	v_add_f32_e32 v29, v39, v29
	v_add_f32_e32 v29, v36, v29
	v_pk_mul_f32 v[34:35], v[18:19], v[18:19]
	v_add_f32_e32 v29, v37, v29
	v_add_f32_e32 v29, v34, v29
	v_pk_mul_f32 v[64:65], v[0:1], v[0:1]
	v_add_f32_e32 v29, v35, v29
	v_add_f32_e32 v29, v64, v29
	v_pk_mul_f32 v[44:45], v[2:3], v[2:3]
	v_add_f32_e32 v29, v65, v29
	v_add_f32_e32 v29, v44, v29
	v_pk_mul_f32 v[42:43], v[8:9], v[8:9]
	v_add_f32_e32 v29, v45, v29
	v_add_f32_e32 v29, v42, v29
	v_pk_mul_f32 v[40:41], v[10:11], v[10:11]
	v_add_f32_e32 v29, v43, v29
	v_add_f32_e32 v29, v40, v29
	v_add_f32_e32 v29, v41, v29
	s_nop 1
	v_add_f32_dpp v29, v29, v29 quad_perm:[1,0,3,2] row_mask:0xf bank_mask:0xf bound_ctrl:1
	s_nop 1
	v_add_f32_dpp v29, v29, v29 quad_perm:[2,3,0,1] row_mask:0xf bank_mask:0xf bound_ctrl:1
	s_nop 1
	v_add_f32_dpp v29, v29, v29 row_half_mirror row_mask:0xf bank_mask:0xf bound_ctrl:1
	s_nop 1
	v_add_f32_dpp v29, v29, v29 row_mirror row_mask:0xf bank_mask:0xf bound_ctrl:1
	s_nop 0
	v_readlane_b32 s2, v29, 16
	v_readlane_b32 s0, v29, 0
	s_nop 0
	v_mov_b32_e32 v34, s2
	v_readlane_b32 s2, v29, 48
	v_add_f32_e32 v34, s0, v34
	v_readlane_b32 s0, v29, 32
	v_mov_b32_e32 v29, s2
	s_nop 0
	v_add_f32_e32 v29, s0, v29
	v_add_f32_e32 v29, v34, v29
	v_fmamk_f32 v29, v29, 0x3a000000, v245
	v_cmp_gt_f32_e32 vcc, s87, v29
	v_mul_f32_e32 v34, 0x4f800000, v29
	s_nop 0
	v_cndmask_b32_e32 v29, v29, v34, vcc
	v_sqrt_f32_e32 v34, v29
	s_nop 0
	v_add_u32_e32 v35, -1, v34
	v_fma_f32 v36, -v35, v34, v29
	v_cmp_ge_f32_e64 s[40:41], 0, v36
	v_add_u32_e32 v36, 1, v34
	s_nop 0
	v_cndmask_b32_e64 v35, v34, v35, s[40:41]
	v_fma_f32 v34, -v36, v34, v29
	v_cmp_lt_f32_e64 s[40:41], 0, v34
	s_nop 1
	v_cndmask_b32_e64 v34, v35, v36, s[40:41]
	v_mul_f32_e32 v35, 0x37800000, v34
	v_cndmask_b32_e32 v34, v34, v35, vcc
	v_cmp_class_f32_e32 vcc, v29, v243
	s_nop 1
	v_cndmask_b32_e32 v29, v34, v29, vcc
	v_div_scale_f32 v34, s[2:3], v29, v29, 1.0
	v_rcp_f32_e32 v35, v34
	s_nop 0
	v_fma_f32 v36, -v34, v35, 1.0
	v_fmac_f32_e32 v35, v36, v35
	v_div_scale_f32 v36, vcc, 1.0, v29, 1.0
	v_mul_f32_e32 v37, v36, v35
	v_fma_f32 v38, -v34, v37, v36
	v_fmac_f32_e32 v37, v38, v35
	v_fma_f32 v34, -v34, v37, v36
	v_div_fmas_f32 v34, v34, v35, v37
	v_div_fixup_f32 v34, v34, v29, 1.0
	s_and_saveexec_b64 s[8:9], s[42:43]
	s_cbranch_execz .LBB0_1961
	s_ashr_i32 s45, s44, 31
	s_lshl_b64 s[2:3], s[44:45], 2
	s_add_u32 s2, s12, s2
	v_mov_b32_e32 v29, v34
	s_addc_u32 s3, s13, s3
	global_store_dwordx2 v225, v[28:29], s[2:3] offset:56
	s_branch .LBB0_1961

.LBB0_2307:
	s_andn2_b64 vcc, exec, s[8:9]
	s_cbranch_vccnz .LBB0_2383
	s_mov_b32 s0, s80
	s_mov_b32 s2, -1
	s_mov_b64 s[8:9], s[96:97]
	v_mbcnt_lo_u32_b32 v0, s2, 0
	v_mbcnt_hi_u32_b32 v0, s2, v0
	s_add_i32 s2, s0, s67
	s_mov_b64 s[12:13], s[96:97]
	s_mov_b64 s[16:17], s[96:97]
	s_mov_b64 s[20:21], s[96:97]
	s_mov_b64 s[18:19], s[96:97]
	s_cmpk_gt_i32 s2, 0x7ff
	s_cbranch_scc1 .LBB0_2327
	s_load_dwordx2 s[20:21], s[20:21], 0x110
	s_nop 0
	s_load_dwordx2 s[8:9], s[8:9], 0x110
	s_nop 0
	s_load_dwordx2 s[22:23], s[12:13], 0x10
	s_nop 0
	s_load_dwordx2 s[16:17], s[16:17], 0x18
	s_nop 0
	s_load_dwordx2 s[18:19], s[18:19], 0x110
	s_waitcnt lgkmcnt(0)
	s_add_u32 s12, s20, 0x920000
	s_addc_u32 s13, s21, 0
	s_lshl_b32 s3, s48, 12
	s_or_b32 s10, s3, 0x800
	s_lshl_b64 s[20:21], s[10:11], 2
	s_add_u32 s16, s16, s20
	s_addc_u32 s17, s17, s21
	v_lshlrev_b32_e32 v2, 3, v0
	s_add_u32 s20, s22, s20
	v_ashrrev_i32_e32 v3, 31, v2
	s_addc_u32 s21, s23, s21
	s_lshl_b32 s36, s2, 3
	v_lshlrev_b64 v[4:5], 2, v[2:3]
	s_mov_b64 s[2:3], 0x1000
	v_lshl_add_u64 v[6:7], v[4:5], 0, s[2:3]
	s_mov_b64 s[2:3], 0x1800
	v_ashrrev_i32_e32 v1, 31, v0
	s_lshl_b32 s100, s80, 10
	v_lshl_add_u32 v194, v0, 4, s100
	global_load_dwordx4 v[196:199], v194, s[20:21]
	global_load_dwordx4 v[200:203], v194, s[16:17]
	v_lshlrev_b32_e32 v195, 5, v0
	s_waitcnt vmcnt(0)
	ds_write_b128 v194, v[196:199]
	ds_write_b128 v194, v[200:203] offset:8192
	s_waitcnt lgkmcnt(0)
	s_barrier
	v_lshl_add_u64 v[116:117], s[20:21], 0, v[4:5]
	v_lshl_add_u64 v[118:119], s[16:17], 0, v[4:5]
	v_lshl_add_u64 v[4:5], v[4:5], 0, s[2:3]
	s_lshl_b32 s0, s0, 4
	s_ashr_i32 s37, s36, 31
	v_cmp_eq_u32_e64 s[40:41], 0, v0
	v_lshl_add_u64 v[120:121], s[20:21], 0, v[6:7]
	v_lshl_add_u64 v[122:123], s[16:17], 0, v[6:7]
	v_lshl_add_u64 v[124:125], s[20:21], 0, v[4:5]
	v_lshl_add_u64 v[126:127], s[16:17], 0, v[4:5]
	s_add_i32 s44, s88, s0
	s_lshl_b64 s[46:47], s[36:37], 12
	v_lshl_add_u64 v[128:129], v[2:3], 1, s[18:19]
	v_lshl_add_u64 v[130:131], v[0:1], 4, s[8:9]
	s_branch .LBB0_2311

.LBB0_2311:
	s_nop 0
	v_lshl_add_u64 v[0:1], v[130:131], 0, s[46:47]
	v_add_co_u32_e32 v2, vcc, 0x12b00000, v0
	s_nop 1
	v_addc_co_u32_e32 v3, vcc, 0, v1, vcc
	global_load_dwordx4 v[132:135], v[2:3], off
	global_load_dwordx4 v[136:139], v[2:3], off offset:1024
	global_load_dwordx4 v[140:143], v[2:3], off offset:2048
	global_load_dwordx4 v[112:115], v[2:3], off offset:3072
	v_add_co_u32_e32 v4, vcc, 0x12b01000, v0
	s_nop 1
	v_addc_co_u32_e32 v5, vcc, 0, v1, vcc
	v_add_co_u32_e32 v2, vcc, 0x12b02000, v0
	s_nop 1
	v_addc_co_u32_e32 v3, vcc, 0, v1, vcc
	global_load_dwordx4 v[108:111], v[4:5], off
	global_load_dwordx4 v[104:107], v[4:5], off offset:1024
	global_load_dwordx4 v[100:103], v[4:5], off offset:2048
	global_load_dwordx4 v[96:99], v[4:5], off offset:3072
	v_add_co_u32_e32 v4, vcc, 0x12b03000, v0
	s_nop 1
	v_addc_co_u32_e32 v5, vcc, 0, v1, vcc
	global_load_dwordx4 v[92:95], v[2:3], off
	global_load_dwordx4 v[88:91], v[2:3], off offset:1024
	global_load_dwordx4 v[84:87], v[2:3], off offset:2048
	global_load_dwordx4 v[80:83], v[2:3], off offset:3072
	v_add_co_u32_e32 v2, vcc, 0x12b04000, v0
	s_nop 1
	v_addc_co_u32_e32 v3, vcc, 0, v1, vcc
	global_load_dwordx4 v[76:79], v[4:5], off
	global_load_dwordx4 v[72:75], v[4:5], off offset:1024
	global_load_dwordx4 v[68:71], v[4:5], off offset:2048
	global_load_dwordx4 v[64:67], v[4:5], off offset:3072
	v_add_co_u32_e32 v4, vcc, 0x12b05000, v0
	s_nop 1
	v_addc_co_u32_e32 v5, vcc, 0, v1, vcc
	global_load_dwordx4 v[60:63], v[2:3], off
	global_load_dwordx4 v[56:59], v[2:3], off offset:1024
	global_load_dwordx4 v[52:55], v[2:3], off offset:2048
	global_load_dwordx4 v[48:51], v[2:3], off offset:3072
	v_add_co_u32_e32 v2, vcc, 0x12b06000, v0
	s_nop 1
	v_addc_co_u32_e32 v3, vcc, 0, v1, vcc
	v_add_co_u32_e32 v0, vcc, 0x12b07000, v0
	s_nop 1
	v_addc_co_u32_e32 v1, vcc, 0, v1, vcc
	global_load_dwordx4 v[44:47], v[4:5], off
	global_load_dwordx4 v[40:43], v[4:5], off offset:1024
	global_load_dwordx4 v[36:39], v[4:5], off offset:2048
	global_load_dwordx4 v[32:35], v[4:5], off offset:3072
	global_load_dwordx4 v[28:31], v[2:3], off
	global_load_dwordx4 v[24:27], v[2:3], off offset:1024
	global_load_dwordx4 v[20:23], v[2:3], off offset:2048
	global_load_dwordx4 v[16:19], v[2:3], off offset:3072
	global_load_dwordx4 v[12:15], v[0:1], off
	global_load_dwordx4 v[8:11], v[0:1], off offset:1024
	global_load_dwordx4 v[4:7], v[0:1], off offset:2048
	global_load_dwordx4 v[0:3], v[0:1], off offset:3072
	s_waitcnt vmcnt(28)
	v_cvt_f32_f16_e32 v148, v134
	v_cvt_f32_f16_sdwa v149, v134 dst_sel:DWORD dst_unused:UNUSED_PAD src0_sel:WORD_1
	v_cvt_f32_f16_e32 v134, v132
	v_cvt_f32_f16_e32 v144, v135
	v_cvt_f32_f16_sdwa v145, v135 dst_sel:DWORD dst_unused:UNUSED_PAD src0_sel:WORD_1
	v_cvt_f32_f16_sdwa v135, v132 dst_sel:DWORD dst_unused:UNUSED_PAD src0_sel:WORD_1
	v_cvt_f32_f16_e32 v146, v133
	v_cvt_f32_f16_sdwa v147, v133 dst_sel:DWORD dst_unused:UNUSED_PAD src0_sel:WORD_1
	v_cvt_f32_f16_e32 v152, v136
	v_cvt_f32_f16_sdwa v153, v136 dst_sel:DWORD dst_unused:UNUSED_PAD src0_sel:WORD_1
	v_add_f32_e32 v136, 0, v134
	v_add_f32_e32 v136, v136, v135
	v_add_f32_e32 v136, v136, v146
	v_add_f32_e32 v136, v136, v147
	v_add_f32_e32 v136, v136, v148
	v_add_f32_e32 v136, v136, v149
	v_cvt_f32_f16_e32 v150, v137
	v_add_f32_e32 v136, v136, v144
	v_cvt_f32_f16_e32 v132, v139
	v_cvt_f32_f16_sdwa v133, v139 dst_sel:DWORD dst_unused:UNUSED_PAD src0_sel:WORD_1
	v_cvt_f32_f16_sdwa v151, v137 dst_sel:DWORD dst_unused:UNUSED_PAD src0_sel:WORD_1
	v_add_f32_e32 v139, v136, v145
	v_cvt_f32_f16_e32 v136, v138
	v_cvt_f32_f16_sdwa v137, v138 dst_sel:DWORD dst_unused:UNUSED_PAD src0_sel:WORD_1
	v_add_f32_e32 v138, v139, v152
	v_add_f32_e32 v138, v138, v153
	v_add_f32_e32 v138, v138, v150
	v_add_f32_e32 v138, v138, v151
	v_add_f32_e32 v138, v138, v136
	v_add_f32_e32 v138, v138, v137
	v_cvt_f32_f16_e32 v166, v140
	v_add_f32_e32 v138, v138, v132
	v_cvt_f32_f16_sdwa v167, v140 dst_sel:DWORD dst_unused:UNUSED_PAD src0_sel:WORD_1
	v_add_f32_e32 v154, v138, v133
	v_cvt_f32_f16_e32 v138, v141
	v_cvt_f32_f16_sdwa v139, v141 dst_sel:DWORD dst_unused:UNUSED_PAD src0_sel:WORD_1
	v_cvt_f32_f16_e32 v140, v142
	v_cvt_f32_f16_sdwa v141, v142 dst_sel:DWORD dst_unused:UNUSED_PAD src0_sel:WORD_1
	v_add_f32_e32 v142, v154, v166
	v_add_f32_e32 v142, v142, v167
	v_cvt_f32_f16_e32 v164, v143
	v_add_f32_e32 v142, v142, v138
	v_cvt_f32_f16_sdwa v165, v143 dst_sel:DWORD dst_unused:UNUSED_PAD src0_sel:WORD_1
	v_add_f32_e32 v142, v142, v139
	v_add_f32_e32 v142, v142, v140
	v_cvt_f32_f16_e32 v172, v112
	v_add_f32_e32 v142, v142, v141
	v_cvt_f32_f16_sdwa v173, v112 dst_sel:DWORD dst_unused:UNUSED_PAD src0_sel:WORD_1
	v_add_f32_e32 v142, v142, v164
	v_cvt_f32_f16_e32 v170, v113
	v_add_f32_e32 v142, v142, v165
	v_cvt_f32_f16_sdwa v171, v113 dst_sel:DWORD dst_unused:UNUSED_PAD src0_sel:WORD_1
	v_cvt_f32_f16_e32 v174, v114
	v_add_f32_e32 v112, v142, v172
	v_cvt_f32_f16_sdwa v175, v114 dst_sel:DWORD dst_unused:UNUSED_PAD src0_sel:WORD_1
	v_add_f32_e32 v112, v112, v173
	v_cvt_f32_f16_e32 v168, v115
	v_add_f32_e32 v112, v112, v170
	v_cvt_f32_f16_sdwa v169, v115 dst_sel:DWORD dst_unused:UNUSED_PAD src0_sel:WORD_1
	v_add_f32_e32 v112, v112, v171
	v_add_f32_e32 v112, v112, v174
	v_add_f32_e32 v112, v112, v175
	v_add_f32_e32 v112, v112, v168
	v_add_f32_e32 v112, v112, v169
	s_nop 1
	v_add_f32_dpp v112, v112, v112 quad_perm:[1,0,3,2] row_mask:0xf bank_mask:0xf bound_ctrl:1
	s_nop 1
	v_add_f32_dpp v112, v112, v112 quad_perm:[2,3,0,1] row_mask:0xf bank_mask:0xf bound_ctrl:1
	s_nop 1
	v_add_f32_dpp v112, v112, v112 row_half_mirror row_mask:0xf bank_mask:0xf bound_ctrl:1
	s_nop 1
	v_add_f32_dpp v112, v112, v112 row_mirror row_mask:0xf bank_mask:0xf bound_ctrl:1
	s_nop 0
	v_readlane_b32 s0, v112, 16
	v_readlane_b32 s7, v112, 48
	v_readlane_b32 s2, v112, 0
	v_readlane_b32 s3, v112, 32
	v_mov_b32_e32 v112, s0
	v_mov_b32_e32 v113, s7
	v_pk_add_f32 v[112:113], s[2:3], v[112:113]
	s_nop 0
	v_add_f32_e32 v112, v112, v113
	v_mul_f32_e32 v162, 0x3a000000, v112
	v_pk_add_f32 v[158:159], v[134:135], v[162:163] op_sel_hi:[1,0] neg_lo:[0,1] neg_hi:[0,1]
	v_pk_add_f32 v[112:113], v[146:147], v[162:163] op_sel_hi:[1,0] neg_lo:[0,1] neg_hi:[0,1]
	v_pk_mul_f32 v[176:177], v[158:159], v[158:159]
	v_pk_mul_f32 v[146:147], v[112:113], v[112:113]
	v_pk_add_f32 v[160:161], v[148:149], v[162:163] op_sel_hi:[1,0] neg_lo:[0,1] neg_hi:[0,1]
	v_pk_add_f32 v[156:157], v[144:145], v[162:163] op_sel_hi:[1,0] neg_lo:[0,1] neg_hi:[0,1]
	v_pk_add_f32 v[152:153], v[152:153], v[162:163] op_sel_hi:[1,0] neg_lo:[0,1] neg_hi:[0,1]
	v_pk_add_f32 v[148:149], v[150:151], v[162:163] op_sel_hi:[1,0] neg_lo:[0,1] neg_hi:[0,1]
	v_pk_add_f32 v[154:155], v[136:137], v[162:163] op_sel_hi:[1,0] neg_lo:[0,1] neg_hi:[0,1]
	v_pk_add_f32 v[150:151], v[132:133], v[162:163] op_sel_hi:[1,0] neg_lo:[0,1] neg_hi:[0,1]
	v_pk_add_f32 v[142:143], v[166:167], v[162:163] op_sel_hi:[1,0] neg_lo:[0,1] neg_hi:[0,1]
	v_pk_add_f32 v[138:139], v[138:139], v[162:163] op_sel_hi:[1,0] neg_lo:[0,1] neg_hi:[0,1]
	v_pk_add_f32 v[144:145], v[140:141], v[162:163] op_sel_hi:[1,0] neg_lo:[0,1] neg_hi:[0,1]
	v_pk_add_f32 v[140:141], v[164:165], v[162:163] op_sel_hi:[1,0] neg_lo:[0,1] neg_hi:[0,1]
	v_pk_add_f32 v[132:133], v[172:173], v[162:163] op_sel_hi:[1,0] neg_lo:[0,1] neg_hi:[0,1]
	v_pk_add_f32 v[114:115], v[170:171], v[162:163] op_sel_hi:[1,0] neg_lo:[0,1] neg_hi:[0,1]
	v_pk_add_f32 v[136:137], v[174:175], v[162:163] op_sel_hi:[1,0] neg_lo:[0,1] neg_hi:[0,1]
	v_pk_add_f32 v[134:135], v[168:169], v[162:163] op_sel_hi:[1,0] neg_lo:[0,1] neg_hi:[0,1]
	v_add_f32_e32 v163, v176, v177
	v_add_f32_e32 v146, v146, v163
	v_pk_mul_f32 v[178:179], v[160:161], v[160:161]
	v_add_f32_e32 v146, v147, v146
	v_add_f32_e32 v146, v178, v146
	v_pk_mul_f32 v[180:181], v[156:157], v[156:157]
	v_add_f32_e32 v146, v179, v146
	v_add_f32_e32 v146, v180, v146
	v_pk_mul_f32 v[182:183], v[152:153], v[152:153]
	v_add_f32_e32 v146, v181, v146
	v_add_f32_e32 v146, v182, v146
	v_pk_mul_f32 v[184:185], v[148:149], v[148:149]
	v_add_f32_e32 v146, v183, v146
	v_add_f32_e32 v146, v184, v146
	v_pk_mul_f32 v[186:187], v[154:155], v[154:155]
	v_add_f32_e32 v146, v185, v146
	v_add_f32_e32 v146, v186, v146
	v_pk_mul_f32 v[188:189], v[150:151], v[150:151]
	v_add_f32_e32 v146, v187, v146
	v_add_f32_e32 v146, v188, v146
	v_pk_mul_f32 v[166:167], v[142:143], v[142:143]
	v_add_f32_e32 v146, v189, v146
	v_add_f32_e32 v146, v166, v146
	v_pk_mul_f32 v[190:191], v[138:139], v[138:139]
	v_add_f32_e32 v146, v167, v146
	v_add_f32_e32 v146, v190, v146
	v_pk_mul_f32 v[192:193], v[144:145], v[144:145]
	v_add_f32_e32 v146, v191, v146
	v_add_f32_e32 v146, v192, v146
	v_pk_mul_f32 v[164:165], v[140:141], v[140:141]
	v_add_f32_e32 v146, v193, v146
	v_add_f32_e32 v146, v164, v146
	v_pk_mul_f32 v[172:173], v[132:133], v[132:133]
	v_add_f32_e32 v146, v165, v146
	v_add_f32_e32 v146, v172, v146
	v_pk_mul_f32 v[170:171], v[114:115], v[114:115]
	v_add_f32_e32 v146, v173, v146
	v_add_f32_e32 v146, v170, v146
	v_pk_mul_f32 v[174:175], v[136:137], v[136:137]
	v_add_f32_e32 v146, v171, v146
	v_add_f32_e32 v146, v174, v146
	v_pk_mul_f32 v[168:169], v[134:135], v[134:135]
	v_add_f32_e32 v146, v175, v146
	v_add_f32_e32 v146, v168, v146
	v_add_f32_e32 v146, v169, v146
	s_nop 1
	v_add_f32_dpp v146, v146, v146 quad_perm:[1,0,3,2] row_mask:0xf bank_mask:0xf bound_ctrl:1
	s_nop 1
	v_add_f32_dpp v146, v146, v146 quad_perm:[2,3,0,1] row_mask:0xf bank_mask:0xf bound_ctrl:1
	s_nop 1
	v_add_f32_dpp v146, v146, v146 row_half_mirror row_mask:0xf bank_mask:0xf bound_ctrl:1
	s_nop 1
	v_add_f32_dpp v146, v146, v146 row_mirror row_mask:0xf bank_mask:0xf bound_ctrl:1
	s_nop 0
	v_readlane_b32 s2, v146, 16
	v_readlane_b32 s0, v146, 0
	s_nop 0
	v_mov_b32_e32 v147, s2
	v_readlane_b32 s2, v146, 48
	v_add_f32_e32 v147, s0, v147
	v_readlane_b32 s0, v146, 32
	v_mov_b32_e32 v146, s2
	s_nop 0
	v_add_f32_e32 v146, s0, v146
	v_add_f32_e32 v146, v147, v146
	v_fmamk_f32 v146, v146, 0x3a000000, v245
	v_mul_f32_e32 v147, 0x4f800000, v146
	v_cmp_gt_f32_e32 vcc, s87, v146
	s_nop 1
	v_cndmask_b32_e32 v146, v146, v147, vcc
	v_sqrt_f32_e32 v147, v146
	s_nop 0
	v_add_u32_e32 v163, -1, v147
	v_fma_f32 v164, -v163, v147, v146
	v_cmp_ge_f32_e64 s[42:43], 0, v164
	v_add_u32_e32 v164, 1, v147
	s_nop 0
	v_cndmask_b32_e64 v163, v147, v163, s[42:43]
	v_fma_f32 v147, -v164, v147, v146
	v_cmp_lt_f32_e64 s[42:43], 0, v147
	s_nop 1
	v_cndmask_b32_e64 v147, v163, v164, s[42:43]
	v_mul_f32_e32 v163, 0x37800000, v147
	v_cndmask_b32_e32 v147, v147, v163, vcc
	v_cmp_class_f32_e32 vcc, v146, v243
	s_nop 1
	v_cndmask_b32_e32 v146, v147, v146, vcc
	v_div_scale_f32 v147, s[2:3], v146, v146, 1.0
	v_rcp_f32_e32 v163, v147
	s_nop 0
	v_fma_f32 v164, -v147, v163, 1.0
	v_fmac_f32_e32 v163, v164, v163
	v_div_scale_f32 v164, vcc, 1.0, v146, 1.0
	v_mul_f32_e32 v165, v164, v163
	v_fma_f32 v166, -v147, v165, v164
	v_fmac_f32_e32 v165, v166, v163
	v_fma_f32 v147, -v147, v165, v164
	v_div_fmas_f32 v147, v147, v163, v165
	v_div_fixup_f32 v146, v147, v146, 1.0
	s_and_saveexec_b64 s[8:9], s[40:41]
	s_cbranch_execz .LBB0_2313
	s_ashr_i32 s45, s44, 31
	s_lshl_b64 s[2:3], s[44:45], 2
	s_add_u32 s2, s12, s2
	v_mov_b32_e32 v163, v146
	s_addc_u32 s3, s13, s3
	global_store_dwordx2 v225, v[162:163], s[2:3]
.LBB0_2313:
	s_or_b64 exec, exec, s[8:9]
	s_nop 0
	ds_read_b128 v[162:165], v195 offset:16
	ds_read_b128 v[166:169], v195 offset:0
	ds_read_b128 v[170:173], v195 offset:8208
	ds_read_b128 v[174:177], v195 offset:8192
	v_pk_mul_f32 v[112:113], v[112:113], v[146:147] op_sel_hi:[1,0]
	v_pk_mul_f32 v[160:161], v[160:161], v[146:147] op_sel_hi:[1,0]
	v_pk_mul_f32 v[156:157], v[156:157], v[146:147] op_sel_hi:[1,0]
	v_pk_mul_f32 v[158:159], v[158:159], v[146:147] op_sel_hi:[1,0]
	s_mov_b32 s0, 0x16b00000
	v_pk_mul_f32 v[152:153], v[152:153], v[146:147] op_sel_hi:[1,0]
	v_pk_mul_f32 v[154:155], v[154:155], v[146:147] op_sel_hi:[1,0]
	v_pk_mul_f32 v[148:149], v[148:149], v[146:147] op_sel_hi:[1,0]
	v_pk_mul_f32 v[150:151], v[150:151], v[146:147] op_sel_hi:[1,0]
	v_pk_mul_f32 v[142:143], v[142:143], v[146:147] op_sel_hi:[1,0]
	v_pk_mul_f32 v[144:145], v[144:145], v[146:147] op_sel_hi:[1,0]
	v_pk_mul_f32 v[138:139], v[138:139], v[146:147] op_sel_hi:[1,0]
	v_pk_mul_f32 v[140:141], v[140:141], v[146:147] op_sel_hi:[1,0]
	v_pk_mul_f32 v[132:133], v[132:133], v[146:147] op_sel_hi:[1,0]
	v_pk_mul_f32 v[136:137], v[136:137], v[146:147] op_sel_hi:[1,0]
	v_pk_mul_f32 v[114:115], v[114:115], v[146:147] op_sel_hi:[1,0]
	v_pk_mul_f32 v[134:135], v[134:135], v[146:147] op_sel_hi:[1,0]
	s_waitcnt lgkmcnt(1)
	v_pk_fma_f32 v[160:161], v[160:161], v[162:163], v[170:171]
	s_waitcnt lgkmcnt(0)
	v_pk_fma_f32 v[112:113], v[112:113], v[168:169], v[176:177]
	v_pk_fma_f32 v[162:163], v[156:157], v[164:165], v[172:173]
	v_cvt_pk_bf16_f32 v157, v112, v113
	v_lshl_add_u64 v[112:113], v[128:129], 0, s[46:47]
	v_pk_fma_f32 v[158:159], v[158:159], v[166:167], v[174:175]
	v_add_co_u32_e32 v172, vcc, s0, v112
	v_cvt_pk_bf16_f32 v156, v158, v159
	v_cvt_pk_bf16_f32 v158, v160, v161
	v_cvt_pk_bf16_f32 v159, v162, v163
	v_addc_co_u32_e32 v173, vcc, 0, v113, vcc
	global_store_dwordx4 v[172:173], v[156:159], off
	s_nop 0
	ds_read_b128 v[156:159], v195 offset:2064
	s_nop 0
	ds_read_b128 v[160:163], v195 offset:2048
	ds_read_b128 v[164:167], v195 offset:10256
	ds_read_b128 v[168:171], v195 offset:10240
	s_waitcnt lgkmcnt(1)
	v_pk_fma_f32 v[154:155], v[154:155], v[156:157], v[164:165]
	s_waitcnt lgkmcnt(0)
	v_pk_fma_f32 v[152:153], v[152:153], v[160:161], v[168:169]
	v_pk_fma_f32 v[156:157], v[148:149], v[162:163], v[170:171]
	v_pk_fma_f32 v[158:159], v[150:151], v[158:159], v[166:167]
	v_cvt_pk_bf16_f32 v148, v152, v153
	v_cvt_pk_bf16_f32 v149, v156, v157
	v_cvt_pk_bf16_f32 v150, v154, v155
	v_cvt_pk_bf16_f32 v151, v158, v159
	global_store_dwordx4 v[172:173], v[148:151], off offset:1024
	s_nop 0
	ds_read_b128 v[148:151], v195 offset:4112
	s_nop 0
	ds_read_b128 v[152:155], v195 offset:4096
	ds_read_b128 v[156:159], v195 offset:12304
	ds_read_b128 v[160:163], v195 offset:12288
	s_waitcnt lgkmcnt(1)
	v_pk_fma_f32 v[144:145], v[144:145], v[148:149], v[156:157]
	s_waitcnt lgkmcnt(0)
	v_pk_fma_f32 v[142:143], v[142:143], v[152:153], v[160:161]
	v_pk_fma_f32 v[148:149], v[138:139], v[154:155], v[162:163]
	v_pk_fma_f32 v[150:151], v[140:141], v[150:151], v[158:159]
	v_cvt_pk_bf16_f32 v138, v142, v143
	v_cvt_pk_bf16_f32 v139, v148, v149
	v_cvt_pk_bf16_f32 v140, v144, v145
	v_cvt_pk_bf16_f32 v141, v150, v151
	global_store_dwordx4 v[172:173], v[138:141], off offset:2048
	s_nop 0
	ds_read_b128 v[138:141], v195 offset:6160
	s_nop 0
	ds_read_b128 v[142:145], v195 offset:6144
	ds_read_b128 v[148:151], v195 offset:14352
	ds_read_b128 v[152:155], v195 offset:14336
	s_waitcnt vmcnt(28)
	v_cvt_f32_f16_e32 v156, v97
	v_cvt_f32_f16_sdwa v157, v97 dst_sel:DWORD dst_unused:UNUSED_PAD src0_sel:WORD_1
	s_waitcnt lgkmcnt(1)
	v_pk_fma_f32 v[136:137], v[136:137], v[138:139], v[148:149]
	s_waitcnt lgkmcnt(0)
	v_pk_fma_f32 v[132:133], v[132:133], v[142:143], v[152:153]
	v_pk_fma_f32 v[114:115], v[114:115], v[144:145], v[154:155]
	v_pk_fma_f32 v[138:139], v[134:135], v[140:141], v[150:151]
	v_cvt_pk_bf16_f32 v132, v132, v133
	v_cvt_pk_bf16_f32 v133, v114, v115
	v_cvt_pk_bf16_f32 v134, v136, v137
	v_cvt_pk_bf16_f32 v135, v138, v139
	global_store_dwordx4 v[172:173], v[132:135], off offset:3072
	v_cvt_f32_f16_sdwa v115, v111 dst_sel:DWORD dst_unused:UNUSED_PAD src0_sel:WORD_1
	v_cvt_f32_f16_e32 v114, v111
	v_cvt_f32_f16_sdwa v133, v109 dst_sel:DWORD dst_unused:UNUSED_PAD src0_sel:WORD_1
	v_cvt_f32_f16_e32 v132, v109
	v_cvt_f32_f16_sdwa v109, v108 dst_sel:DWORD dst_unused:UNUSED_PAD src0_sel:WORD_1
	v_cvt_f32_f16_e32 v108, v108
	v_cvt_f32_f16_sdwa v111, v110 dst_sel:DWORD dst_unused:UNUSED_PAD src0_sel:WORD_1
	v_cvt_f32_f16_e32 v110, v110
	v_cvt_f32_f16_sdwa v137, v105 dst_sel:DWORD dst_unused:UNUSED_PAD src0_sel:WORD_1
	v_add_f32_e32 v134, 0, v108
	v_add_f32_e32 v134, v134, v109
	v_add_f32_e32 v134, v134, v132
	v_add_f32_e32 v134, v134, v133
	v_add_f32_e32 v134, v134, v110
	v_cvt_f32_f16_e32 v136, v105
	v_cvt_f32_f16_sdwa v105, v104 dst_sel:DWORD dst_unused:UNUSED_PAD src0_sel:WORD_1
	v_cvt_f32_f16_e32 v104, v104
	v_add_f32_e32 v134, v134, v111
	v_add_f32_e32 v134, v134, v114
	v_add_f32_e32 v138, v134, v115
	v_cvt_f32_f16_sdwa v135, v107 dst_sel:DWORD dst_unused:UNUSED_PAD src0_sel:WORD_1
	v_cvt_f32_f16_e32 v134, v107
	v_cvt_f32_f16_sdwa v107, v106 dst_sel:DWORD dst_unused:UNUSED_PAD src0_sel:WORD_1
	v_cvt_f32_f16_e32 v106, v106
	v_add_f32_e32 v138, v138, v104
	v_add_f32_e32 v138, v138, v105
	v_add_f32_e32 v138, v138, v136
	v_add_f32_e32 v138, v138, v137
	v_add_f32_e32 v138, v138, v106
	v_cvt_f32_f16_sdwa v151, v101 dst_sel:DWORD dst_unused:UNUSED_PAD src0_sel:WORD_1
	v_cvt_f32_f16_e32 v150, v101
	v_cvt_f32_f16_sdwa v101, v100 dst_sel:DWORD dst_unused:UNUSED_PAD src0_sel:WORD_1
	v_cvt_f32_f16_e32 v100, v100
	v_add_f32_e32 v138, v138, v107
	v_add_f32_e32 v138, v138, v134
	v_add_f32_e32 v138, v138, v135
	v_cvt_f32_f16_sdwa v149, v103 dst_sel:DWORD dst_unused:UNUSED_PAD src0_sel:WORD_1
	v_cvt_f32_f16_e32 v148, v103
	v_cvt_f32_f16_sdwa v103, v102 dst_sel:DWORD dst_unused:UNUSED_PAD src0_sel:WORD_1
	v_cvt_f32_f16_e32 v102, v102
	v_add_f32_e32 v138, v138, v100
	v_add_f32_e32 v138, v138, v101
	v_add_f32_e32 v138, v138, v150
	v_add_f32_e32 v138, v138, v151
	v_add_f32_e32 v138, v138, v102
	v_cvt_f32_f16_sdwa v155, v98 dst_sel:DWORD dst_unused:UNUSED_PAD src0_sel:WORD_1
	v_cvt_f32_f16_e32 v154, v98
	v_cvt_f32_f16_e32 v98, v96
	v_add_f32_e32 v138, v138, v103
	v_cvt_f32_f16_sdwa v153, v99 dst_sel:DWORD dst_unused:UNUSED_PAD src0_sel:WORD_1
	v_cvt_f32_f16_e32 v152, v99
	v_cvt_f32_f16_sdwa v99, v96 dst_sel:DWORD dst_unused:UNUSED_PAD src0_sel:WORD_1
	v_add_f32_e32 v138, v138, v148
	v_add_f32_e32 v138, v138, v149
	v_add_f32_e32 v96, v138, v98
	v_add_f32_e32 v96, v96, v99
	v_add_f32_e32 v96, v96, v156
	v_add_f32_e32 v96, v96, v157
	v_add_f32_e32 v96, v96, v154
	v_add_f32_e32 v96, v96, v155
	v_add_f32_e32 v96, v96, v152
	v_add_f32_e32 v96, v96, v153
	s_nop 1
	v_add_f32_dpp v96, v96, v96 quad_perm:[1,0,3,2] row_mask:0xf bank_mask:0xf bound_ctrl:1
	s_nop 1
	v_add_f32_dpp v96, v96, v96 quad_perm:[2,3,0,1] row_mask:0xf bank_mask:0xf bound_ctrl:1
	s_nop 1
	v_add_f32_dpp v96, v96, v96 row_half_mirror row_mask:0xf bank_mask:0xf bound_ctrl:1
	s_nop 1
	v_add_f32_dpp v96, v96, v96 row_mirror row_mask:0xf bank_mask:0xf bound_ctrl:1
	s_nop 0
	v_readlane_b32 s0, v96, 16
	v_readlane_b32 s7, v96, 48
	v_readlane_b32 s2, v96, 0
	v_readlane_b32 s3, v96, 32
	v_mov_b32_e32 v96, s0
	v_mov_b32_e32 v97, s7
	v_pk_add_f32 v[96:97], s[2:3], v[96:97]
	s_nop 0
	v_add_f32_e32 v96, v96, v97
	v_mul_f32_e32 v146, 0x3a000000, v96
	v_pk_add_f32 v[140:141], v[108:109], v[146:147] op_sel_hi:[1,0] neg_lo:[0,1] neg_hi:[0,1]
	v_pk_add_f32 v[138:139], v[132:133], v[146:147] op_sel_hi:[1,0] neg_lo:[0,1] neg_hi:[0,1]
	v_pk_mul_f32 v[158:159], v[140:141], v[140:141]
	v_pk_mul_f32 v[160:161], v[138:139], v[138:139]
	v_pk_add_f32 v[144:145], v[110:111], v[146:147] op_sel_hi:[1,0] neg_lo:[0,1] neg_hi:[0,1]
	v_pk_add_f32 v[142:143], v[114:115], v[146:147] op_sel_hi:[1,0] neg_lo:[0,1] neg_hi:[0,1]
	v_pk_add_f32 v[132:133], v[104:105], v[146:147] op_sel_hi:[1,0] neg_lo:[0,1] neg_hi:[0,1]
	v_pk_add_f32 v[114:115], v[136:137], v[146:147] op_sel_hi:[1,0] neg_lo:[0,1] neg_hi:[0,1]
	v_pk_add_f32 v[136:137], v[106:107], v[146:147] op_sel_hi:[1,0] neg_lo:[0,1] neg_hi:[0,1]
	v_pk_add_f32 v[134:135], v[134:135], v[146:147] op_sel_hi:[1,0] neg_lo:[0,1] neg_hi:[0,1]
	v_pk_add_f32 v[100:101], v[100:101], v[146:147] op_sel_hi:[1,0] neg_lo:[0,1] neg_hi:[0,1]
	v_pk_add_f32 v[96:97], v[150:151], v[146:147] op_sel_hi:[1,0] neg_lo:[0,1] neg_hi:[0,1]
	v_pk_add_f32 v[108:109], v[102:103], v[146:147] op_sel_hi:[1,0] neg_lo:[0,1] neg_hi:[0,1]
	v_pk_add_f32 v[104:105], v[148:149], v[146:147] op_sel_hi:[1,0] neg_lo:[0,1] neg_hi:[0,1]
	v_pk_add_f32 v[98:99], v[98:99], v[146:147] op_sel_hi:[1,0] neg_lo:[0,1] neg_hi:[0,1]
	v_pk_add_f32 v[102:103], v[156:157], v[146:147] op_sel_hi:[1,0] neg_lo:[0,1] neg_hi:[0,1]
	v_pk_add_f32 v[106:107], v[154:155], v[146:147] op_sel_hi:[1,0] neg_lo:[0,1] neg_hi:[0,1]
	v_pk_add_f32 v[110:111], v[152:153], v[146:147] op_sel_hi:[1,0] neg_lo:[0,1] neg_hi:[0,1]
	v_add_f32_e32 v147, v158, v159
	v_add_f32_e32 v147, v160, v147
	v_pk_mul_f32 v[162:163], v[144:145], v[144:145]
	v_add_f32_e32 v147, v161, v147
	v_add_f32_e32 v147, v162, v147
	v_pk_mul_f32 v[164:165], v[142:143], v[142:143]
	v_add_f32_e32 v147, v163, v147
	v_add_f32_e32 v147, v164, v147
	v_pk_mul_f32 v[166:167], v[132:133], v[132:133]
	v_add_f32_e32 v147, v165, v147
	v_add_f32_e32 v147, v166, v147
	v_pk_mul_f32 v[168:169], v[114:115], v[114:115]
	v_add_f32_e32 v147, v167, v147
	v_add_f32_e32 v147, v168, v147
	v_pk_mul_f32 v[170:171], v[136:137], v[136:137]
	v_add_f32_e32 v147, v169, v147
	v_add_f32_e32 v147, v170, v147
	v_pk_mul_f32 v[172:173], v[134:135], v[134:135]
	v_add_f32_e32 v147, v171, v147
	v_add_f32_e32 v147, v172, v147
	v_pk_mul_f32 v[174:175], v[100:101], v[100:101]
	v_add_f32_e32 v147, v173, v147
	v_add_f32_e32 v147, v174, v147
	v_pk_mul_f32 v[150:151], v[96:97], v[96:97]
	v_add_f32_e32 v147, v175, v147
	v_add_f32_e32 v147, v150, v147
	v_pk_mul_f32 v[176:177], v[108:109], v[108:109]
	v_add_f32_e32 v147, v151, v147
	v_add_f32_e32 v147, v176, v147
	v_pk_mul_f32 v[148:149], v[104:105], v[104:105]
	v_add_f32_e32 v147, v177, v147
	v_add_f32_e32 v147, v148, v147
	v_pk_mul_f32 v[178:179], v[98:99], v[98:99]
	v_add_f32_e32 v147, v149, v147
	v_add_f32_e32 v147, v178, v147
	v_pk_mul_f32 v[156:157], v[102:103], v[102:103]
	v_add_f32_e32 v147, v179, v147
	v_add_f32_e32 v147, v156, v147
	v_pk_mul_f32 v[154:155], v[106:107], v[106:107]
	v_add_f32_e32 v147, v157, v147
	v_add_f32_e32 v147, v154, v147
	v_pk_mul_f32 v[152:153], v[110:111], v[110:111]
	v_add_f32_e32 v147, v155, v147
	v_add_f32_e32 v147, v152, v147
	v_add_f32_e32 v147, v153, v147
	s_nop 1
	v_add_f32_dpp v147, v147, v147 quad_perm:[1,0,3,2] row_mask:0xf bank_mask:0xf bound_ctrl:1
	s_nop 1
	v_add_f32_dpp v147, v147, v147 quad_perm:[2,3,0,1] row_mask:0xf bank_mask:0xf bound_ctrl:1
	s_nop 1
	v_add_f32_dpp v147, v147, v147 row_half_mirror row_mask:0xf bank_mask:0xf bound_ctrl:1
	s_nop 1
	v_add_f32_dpp v147, v147, v147 row_mirror row_mask:0xf bank_mask:0xf bound_ctrl:1
	s_nop 0
	v_readlane_b32 s2, v147, 16
	v_readlane_b32 s0, v147, 0
	s_nop 0
	v_mov_b32_e32 v148, s2
	v_readlane_b32 s2, v147, 48
	v_add_f32_e32 v148, s0, v148
	v_readlane_b32 s0, v147, 32
	v_mov_b32_e32 v147, s2
	s_nop 0
	v_add_f32_e32 v147, s0, v147
	v_add_f32_e32 v147, v148, v147
	v_fmamk_f32 v147, v147, 0x3a000000, v245
	v_cmp_gt_f32_e32 vcc, s87, v147
	v_mul_f32_e32 v148, 0x4f800000, v147
	s_nop 0
	v_cndmask_b32_e32 v147, v147, v148, vcc
	v_sqrt_f32_e32 v148, v147
	s_nop 0
	v_add_u32_e32 v149, -1, v148
	v_fma_f32 v150, -v149, v148, v147
	v_cmp_ge_f32_e64 s[42:43], 0, v150
	v_add_u32_e32 v150, 1, v148
	s_nop 0
	v_cndmask_b32_e64 v149, v148, v149, s[42:43]
	v_fma_f32 v148, -v150, v148, v147
	v_cmp_lt_f32_e64 s[42:43], 0, v148
	s_nop 1
	v_cndmask_b32_e64 v148, v149, v150, s[42:43]
	v_mul_f32_e32 v149, 0x37800000, v148
	v_cndmask_b32_e32 v148, v148, v149, vcc
	v_cmp_class_f32_e32 vcc, v147, v243
	s_nop 1
	v_cndmask_b32_e32 v147, v148, v147, vcc
	v_div_scale_f32 v148, s[2:3], v147, v147, 1.0
	v_rcp_f32_e32 v149, v148
	s_nop 0
	v_fma_f32 v150, -v148, v149, 1.0
	v_fmac_f32_e32 v149, v150, v149
	v_div_scale_f32 v150, vcc, 1.0, v147, 1.0
	v_mul_f32_e32 v151, v150, v149
	v_fma_f32 v152, -v148, v151, v150
	v_fmac_f32_e32 v151, v152, v149
	v_fma_f32 v148, -v148, v151, v150
	v_div_fmas_f32 v148, v148, v149, v151
	v_div_fixup_f32 v148, v148, v147, 1.0
	s_and_saveexec_b64 s[8:9], s[40:41]
	s_cbranch_execz .LBB0_2315
	s_ashr_i32 s45, s44, 31
	s_lshl_b64 s[2:3], s[44:45], 2
	s_add_u32 s2, s12, s2
	v_mov_b32_e32 v147, v148
	s_addc_u32 s3, s13, s3
	global_store_dwordx2 v225, v[146:147], s[2:3] offset:8
.LBB0_2315:
	s_or_b64 exec, exec, s[8:9]
	s_nop 0
	ds_read_b128 v[150:153], v195 offset:16
	ds_read_b128 v[154:157], v195 offset:0
	ds_read_b128 v[158:161], v195 offset:8208
	ds_read_b128 v[162:165], v195 offset:8192
	v_pk_mul_f32 v[140:141], v[140:141], v[148:149] op_sel_hi:[1,0]
	v_pk_mul_f32 v[144:145], v[144:145], v[148:149] op_sel_hi:[1,0]
	v_pk_mul_f32 v[138:139], v[138:139], v[148:149] op_sel_hi:[1,0]
	v_pk_mul_f32 v[142:143], v[142:143], v[148:149] op_sel_hi:[1,0]
	s_mov_b32 s0, 0x16b01000
	v_pk_mul_f32 v[132:133], v[132:133], v[148:149] op_sel_hi:[1,0]
	v_pk_mul_f32 v[136:137], v[136:137], v[148:149] op_sel_hi:[1,0]
	v_pk_mul_f32 v[114:115], v[114:115], v[148:149] op_sel_hi:[1,0]
	v_pk_mul_f32 v[134:135], v[134:135], v[148:149] op_sel_hi:[1,0]
	v_pk_mul_f32 v[100:101], v[100:101], v[148:149] op_sel_hi:[1,0]
	v_pk_mul_f32 v[108:109], v[108:109], v[148:149] op_sel_hi:[1,0]
	v_pk_mul_f32 v[96:97], v[96:97], v[148:149] op_sel_hi:[1,0]
	v_pk_mul_f32 v[104:105], v[104:105], v[148:149] op_sel_hi:[1,0]
	s_waitcnt lgkmcnt(1)
	v_pk_fma_f32 v[144:145], v[144:145], v[150:151], v[158:159]
	s_waitcnt lgkmcnt(0)
	v_pk_fma_f32 v[140:141], v[140:141], v[154:155], v[162:163]
	v_pk_fma_f32 v[146:147], v[138:139], v[156:157], v[164:165]
	v_pk_fma_f32 v[142:143], v[142:143], v[152:153], v[160:161]
	v_add_co_u32_e32 v158, vcc, s0, v112
	v_cvt_pk_bf16_f32 v138, v140, v141
	v_cvt_pk_bf16_f32 v139, v146, v147
	v_cvt_pk_bf16_f32 v140, v144, v145
	v_cvt_pk_bf16_f32 v141, v142, v143
	v_addc_co_u32_e32 v159, vcc, 0, v113, vcc
	global_store_dwordx4 v[158:159], v[138:141], off
	s_nop 0
	ds_read_b128 v[138:141], v195 offset:2064
	s_nop 0
	ds_read_b128 v[142:145], v195 offset:2048
	ds_read_b128 v[150:153], v195 offset:10256
	ds_read_b128 v[154:157], v195 offset:10240
	s_waitcnt lgkmcnt(1)
	v_pk_fma_f32 v[136:137], v[136:137], v[138:139], v[150:151]
	s_waitcnt lgkmcnt(0)
	v_pk_fma_f32 v[132:133], v[132:133], v[142:143], v[154:155]
	v_pk_fma_f32 v[114:115], v[114:115], v[144:145], v[156:157]
	v_pk_fma_f32 v[138:139], v[134:135], v[140:141], v[152:153]
	v_cvt_pk_bf16_f32 v132, v132, v133
	v_cvt_pk_bf16_f32 v133, v114, v115
	v_cvt_pk_bf16_f32 v134, v136, v137
	v_cvt_pk_bf16_f32 v135, v138, v139
	global_store_dwordx4 v[158:159], v[132:135], off offset:1024
	s_nop 0
	ds_read_b128 v[132:135], v195 offset:4112
	s_nop 0
	ds_read_b128 v[136:139], v195 offset:4096
	ds_read_b128 v[140:143], v195 offset:12304
	ds_read_b128 v[144:147], v195 offset:12288
	s_waitcnt lgkmcnt(1)
	v_pk_fma_f32 v[108:109], v[108:109], v[132:133], v[140:141]
	s_waitcnt lgkmcnt(0)
	v_pk_fma_f32 v[100:101], v[100:101], v[136:137], v[144:145]
	v_pk_fma_f32 v[96:97], v[96:97], v[138:139], v[146:147]
	v_pk_fma_f32 v[104:105], v[104:105], v[134:135], v[142:143]
	v_cvt_pk_bf16_f32 v132, v100, v101
	v_cvt_pk_bf16_f32 v133, v96, v97
	v_cvt_pk_bf16_f32 v134, v108, v109
	v_cvt_pk_bf16_f32 v135, v104, v105
	global_store_dwordx4 v[158:159], v[132:135], off offset:2048
	s_nop 0
	ds_read_b128 v[132:135], v195 offset:6160
	s_nop 0
	ds_read_b128 v[136:139], v195 offset:6144
	ds_read_b128 v[140:143], v195 offset:14352
	ds_read_b128 v[144:147], v195 offset:14336
	v_pk_mul_f32 v[96:97], v[98:99], v[148:149] op_sel_hi:[1,0]
	v_pk_mul_f32 v[98:99], v[106:107], v[148:149] op_sel_hi:[1,0]
	v_pk_mul_f32 v[100:101], v[102:103], v[148:149] op_sel_hi:[1,0]
	v_pk_mul_f32 v[102:103], v[110:111], v[148:149] op_sel_hi:[1,0]
	s_waitcnt lgkmcnt(1)
	v_pk_fma_f32 v[98:99], v[98:99], v[132:133], v[140:141]
	s_waitcnt lgkmcnt(0)
	v_pk_fma_f32 v[96:97], v[96:97], v[136:137], v[144:145]
	v_pk_fma_f32 v[100:101], v[100:101], v[138:139], v[146:147]
	v_pk_fma_f32 v[102:103], v[102:103], v[134:135], v[142:143]
	v_cvt_pk_bf16_f32 v96, v96, v97
	v_cvt_pk_bf16_f32 v97, v100, v101
	v_cvt_pk_bf16_f32 v98, v98, v99
	v_cvt_pk_bf16_f32 v99, v102, v103
	global_store_dwordx4 v[158:159], v[96:99], off offset:3072
	s_waitcnt vmcnt(30)
	v_cvt_f32_f16_sdwa v103, v89 dst_sel:DWORD dst_unused:UNUSED_PAD src0_sel:WORD_1
	v_cvt_f32_f16_e32 v102, v89
	v_cvt_f32_f16_sdwa v99, v93 dst_sel:DWORD dst_unused:UNUSED_PAD src0_sel:WORD_1
	v_cvt_f32_f16_e32 v98, v93
	v_cvt_f32_f16_sdwa v93, v92 dst_sel:DWORD dst_unused:UNUSED_PAD src0_sel:WORD_1
	v_cvt_f32_f16_e32 v92, v92
	v_cvt_f32_f16_sdwa v97, v95 dst_sel:DWORD dst_unused:UNUSED_PAD src0_sel:WORD_1
	v_cvt_f32_f16_e32 v96, v95
	v_cvt_f32_f16_sdwa v95, v94 dst_sel:DWORD dst_unused:UNUSED_PAD src0_sel:WORD_1
	v_cvt_f32_f16_e32 v94, v94
	v_add_f32_e32 v100, 0, v92
	v_add_f32_e32 v100, v100, v93
	v_add_f32_e32 v100, v100, v98
	v_add_f32_e32 v100, v100, v99
	v_add_f32_e32 v100, v100, v94
	v_cvt_f32_f16_sdwa v89, v88 dst_sel:DWORD dst_unused:UNUSED_PAD src0_sel:WORD_1
	v_cvt_f32_f16_e32 v88, v88
	v_add_f32_e32 v100, v100, v95
	v_add_f32_e32 v100, v100, v96
	v_add_f32_e32 v104, v100, v97
	v_cvt_f32_f16_sdwa v101, v91 dst_sel:DWORD dst_unused:UNUSED_PAD src0_sel:WORD_1
	v_cvt_f32_f16_e32 v100, v91
	v_cvt_f32_f16_sdwa v91, v90 dst_sel:DWORD dst_unused:UNUSED_PAD src0_sel:WORD_1
	v_cvt_f32_f16_e32 v90, v90
	v_add_f32_e32 v104, v104, v88
	v_add_f32_e32 v104, v104, v89
	v_add_f32_e32 v104, v104, v102
	v_add_f32_e32 v104, v104, v103
	v_add_f32_e32 v104, v104, v90
	v_cvt_f32_f16_sdwa v135, v85 dst_sel:DWORD dst_unused:UNUSED_PAD src0_sel:WORD_1
	v_cvt_f32_f16_e32 v134, v85
	v_cvt_f32_f16_sdwa v85, v84 dst_sel:DWORD dst_unused:UNUSED_PAD src0_sel:WORD_1
	v_cvt_f32_f16_e32 v84, v84
	v_add_f32_e32 v104, v104, v91
	v_add_f32_e32 v104, v104, v100
	v_add_f32_e32 v104, v104, v101
	v_cvt_f32_f16_sdwa v133, v87 dst_sel:DWORD dst_unused:UNUSED_PAD src0_sel:WORD_1
	v_cvt_f32_f16_e32 v132, v87
	v_cvt_f32_f16_sdwa v87, v86 dst_sel:DWORD dst_unused:UNUSED_PAD src0_sel:WORD_1
	v_cvt_f32_f16_e32 v86, v86
	v_add_f32_e32 v104, v104, v84
	v_add_f32_e32 v104, v104, v85
	v_add_f32_e32 v104, v104, v134
	v_add_f32_e32 v104, v104, v135
	v_add_f32_e32 v104, v104, v86
	v_cvt_f32_f16_sdwa v139, v82 dst_sel:DWORD dst_unused:UNUSED_PAD src0_sel:WORD_1
	v_cvt_f32_f16_e32 v138, v82
	v_cvt_f32_f16_e32 v82, v80
	v_add_f32_e32 v104, v104, v87
	v_cvt_f32_f16_sdwa v137, v83 dst_sel:DWORD dst_unused:UNUSED_PAD src0_sel:WORD_1
	v_cvt_f32_f16_e32 v136, v83
	v_cvt_f32_f16_sdwa v83, v80 dst_sel:DWORD dst_unused:UNUSED_PAD src0_sel:WORD_1
	v_add_f32_e32 v104, v104, v132
	v_cvt_f32_f16_e32 v140, v81
	v_add_f32_e32 v104, v104, v133
	v_cvt_f32_f16_sdwa v141, v81 dst_sel:DWORD dst_unused:UNUSED_PAD src0_sel:WORD_1
	v_add_f32_e32 v80, v104, v82
	v_add_f32_e32 v80, v80, v83
	v_add_f32_e32 v80, v80, v140
	v_add_f32_e32 v80, v80, v141
	v_add_f32_e32 v80, v80, v138
	v_add_f32_e32 v80, v80, v139
	v_add_f32_e32 v80, v80, v136
	v_add_f32_e32 v80, v80, v137
	s_nop 1
	v_add_f32_dpp v80, v80, v80 quad_perm:[1,0,3,2] row_mask:0xf bank_mask:0xf bound_ctrl:1
	s_nop 1
	v_add_f32_dpp v80, v80, v80 quad_perm:[2,3,0,1] row_mask:0xf bank_mask:0xf bound_ctrl:1
	s_nop 1
	v_add_f32_dpp v80, v80, v80 row_half_mirror row_mask:0xf bank_mask:0xf bound_ctrl:1
	s_nop 1
	v_add_f32_dpp v80, v80, v80 row_mirror row_mask:0xf bank_mask:0xf bound_ctrl:1
	s_nop 0
	v_readlane_b32 s0, v80, 16
	v_readlane_b32 s7, v80, 48
	v_readlane_b32 s2, v80, 0
	v_readlane_b32 s3, v80, 32
	v_mov_b32_e32 v80, s0
	v_mov_b32_e32 v81, s7
	v_pk_add_f32 v[80:81], s[2:3], v[80:81]
	s_nop 0
	v_add_f32_e32 v80, v80, v81
	v_mul_f32_e32 v114, 0x3a000000, v80
	v_pk_add_f32 v[106:107], v[92:93], v[114:115] op_sel_hi:[1,0] neg_lo:[0,1] neg_hi:[0,1]
	v_pk_add_f32 v[104:105], v[98:99], v[114:115] op_sel_hi:[1,0] neg_lo:[0,1] neg_hi:[0,1]
	v_pk_mul_f32 v[142:143], v[106:107], v[106:107]
	v_pk_mul_f32 v[144:145], v[104:105], v[104:105]
	v_pk_add_f32 v[110:111], v[94:95], v[114:115] op_sel_hi:[1,0] neg_lo:[0,1] neg_hi:[0,1]
	v_pk_add_f32 v[108:109], v[96:97], v[114:115] op_sel_hi:[1,0] neg_lo:[0,1] neg_hi:[0,1]
	v_pk_add_f32 v[98:99], v[88:89], v[114:115] op_sel_hi:[1,0] neg_lo:[0,1] neg_hi:[0,1]
	v_pk_add_f32 v[96:97], v[102:103], v[114:115] op_sel_hi:[1,0] neg_lo:[0,1] neg_hi:[0,1]
	v_pk_add_f32 v[102:103], v[90:91], v[114:115] op_sel_hi:[1,0] neg_lo:[0,1] neg_hi:[0,1]
	v_pk_add_f32 v[100:101], v[100:101], v[114:115] op_sel_hi:[1,0] neg_lo:[0,1] neg_hi:[0,1]
	v_pk_add_f32 v[84:85], v[84:85], v[114:115] op_sel_hi:[1,0] neg_lo:[0,1] neg_hi:[0,1]
	v_pk_add_f32 v[80:81], v[134:135], v[114:115] op_sel_hi:[1,0] neg_lo:[0,1] neg_hi:[0,1]
	v_pk_add_f32 v[92:93], v[86:87], v[114:115] op_sel_hi:[1,0] neg_lo:[0,1] neg_hi:[0,1]
	v_pk_add_f32 v[88:89], v[132:133], v[114:115] op_sel_hi:[1,0] neg_lo:[0,1] neg_hi:[0,1]
	v_pk_add_f32 v[82:83], v[82:83], v[114:115] op_sel_hi:[1,0] neg_lo:[0,1] neg_hi:[0,1]
	v_pk_add_f32 v[86:87], v[140:141], v[114:115] op_sel_hi:[1,0] neg_lo:[0,1] neg_hi:[0,1]
	v_pk_add_f32 v[90:91], v[138:139], v[114:115] op_sel_hi:[1,0] neg_lo:[0,1] neg_hi:[0,1]
	v_pk_add_f32 v[94:95], v[136:137], v[114:115] op_sel_hi:[1,0] neg_lo:[0,1] neg_hi:[0,1]
	v_add_f32_e32 v115, v142, v143
	v_add_f32_e32 v115, v144, v115
	v_pk_mul_f32 v[146:147], v[110:111], v[110:111]
	v_add_f32_e32 v115, v145, v115
	v_add_f32_e32 v115, v146, v115
	v_pk_mul_f32 v[148:149], v[108:109], v[108:109]
	v_add_f32_e32 v115, v147, v115
	v_add_f32_e32 v115, v148, v115
	v_pk_mul_f32 v[150:151], v[98:99], v[98:99]
	v_add_f32_e32 v115, v149, v115
	v_add_f32_e32 v115, v150, v115
	v_pk_mul_f32 v[152:153], v[96:97], v[96:97]
	v_add_f32_e32 v115, v151, v115
	v_add_f32_e32 v115, v152, v115
	v_pk_mul_f32 v[154:155], v[102:103], v[102:103]
	v_add_f32_e32 v115, v153, v115
	v_add_f32_e32 v115, v154, v115
	v_pk_mul_f32 v[156:157], v[100:101], v[100:101]
	v_add_f32_e32 v115, v155, v115
	v_add_f32_e32 v115, v156, v115
	v_pk_mul_f32 v[158:159], v[84:85], v[84:85]
	v_add_f32_e32 v115, v157, v115
	v_add_f32_e32 v115, v158, v115
	v_pk_mul_f32 v[134:135], v[80:81], v[80:81]
	v_add_f32_e32 v115, v159, v115
	v_add_f32_e32 v115, v134, v115
	v_pk_mul_f32 v[160:161], v[92:93], v[92:93]
	v_add_f32_e32 v115, v135, v115
	v_add_f32_e32 v115, v160, v115
	v_pk_mul_f32 v[132:133], v[88:89], v[88:89]
	v_add_f32_e32 v115, v161, v115
	v_add_f32_e32 v115, v132, v115
	v_pk_mul_f32 v[162:163], v[82:83], v[82:83]
	v_add_f32_e32 v115, v133, v115
	v_add_f32_e32 v115, v162, v115
	v_pk_mul_f32 v[140:141], v[86:87], v[86:87]
	v_add_f32_e32 v115, v163, v115
	v_add_f32_e32 v115, v140, v115
	v_pk_mul_f32 v[138:139], v[90:91], v[90:91]
	v_add_f32_e32 v115, v141, v115
	v_add_f32_e32 v115, v138, v115
	v_pk_mul_f32 v[136:137], v[94:95], v[94:95]
	v_add_f32_e32 v115, v139, v115
	v_add_f32_e32 v115, v136, v115
	v_add_f32_e32 v115, v137, v115
	s_nop 1
	v_add_f32_dpp v115, v115, v115 quad_perm:[1,0,3,2] row_mask:0xf bank_mask:0xf bound_ctrl:1
	s_nop 1
	v_add_f32_dpp v115, v115, v115 quad_perm:[2,3,0,1] row_mask:0xf bank_mask:0xf bound_ctrl:1
	s_nop 1
	v_add_f32_dpp v115, v115, v115 row_half_mirror row_mask:0xf bank_mask:0xf bound_ctrl:1
	s_nop 1
	v_add_f32_dpp v115, v115, v115 row_mirror row_mask:0xf bank_mask:0xf bound_ctrl:1
	s_nop 0
	v_readlane_b32 s2, v115, 16
	v_readlane_b32 s0, v115, 0
	s_nop 0
	v_mov_b32_e32 v132, s2
	v_readlane_b32 s2, v115, 48
	v_add_f32_e32 v132, s0, v132
	v_readlane_b32 s0, v115, 32
	v_mov_b32_e32 v115, s2
	s_nop 0
	v_add_f32_e32 v115, s0, v115
	v_add_f32_e32 v115, v132, v115
	v_fmamk_f32 v115, v115, 0x3a000000, v245
	v_cmp_gt_f32_e32 vcc, s87, v115
	v_mul_f32_e32 v132, 0x4f800000, v115
	s_nop 0
	v_cndmask_b32_e32 v115, v115, v132, vcc
	v_sqrt_f32_e32 v132, v115
	s_nop 0
	v_add_u32_e32 v133, -1, v132
	v_fma_f32 v134, -v133, v132, v115
	v_cmp_ge_f32_e64 s[42:43], 0, v134
	v_add_u32_e32 v134, 1, v132
	s_nop 0
	v_cndmask_b32_e64 v133, v132, v133, s[42:43]
	v_fma_f32 v132, -v134, v132, v115
	v_cmp_lt_f32_e64 s[42:43], 0, v132
	s_nop 1
	v_cndmask_b32_e64 v132, v133, v134, s[42:43]
	v_mul_f32_e32 v133, 0x37800000, v132
	v_cndmask_b32_e32 v132, v132, v133, vcc
	v_cmp_class_f32_e32 vcc, v115, v243
	s_nop 1
	v_cndmask_b32_e32 v115, v132, v115, vcc
	v_div_scale_f32 v132, s[2:3], v115, v115, 1.0
	v_rcp_f32_e32 v133, v132
	s_nop 0
	v_fma_f32 v134, -v132, v133, 1.0
	v_fmac_f32_e32 v133, v134, v133
	v_div_scale_f32 v134, vcc, 1.0, v115, 1.0
	v_mul_f32_e32 v135, v134, v133
	v_fma_f32 v136, -v132, v135, v134
	v_fmac_f32_e32 v135, v136, v133
	v_fma_f32 v132, -v132, v135, v134
	v_div_fmas_f32 v132, v132, v133, v135
	v_div_fixup_f32 v132, v132, v115, 1.0
	s_and_saveexec_b64 s[8:9], s[40:41]
	s_cbranch_execz .LBB0_2317
	s_ashr_i32 s45, s44, 31
	s_lshl_b64 s[2:3], s[44:45], 2
	s_add_u32 s2, s12, s2
	v_mov_b32_e32 v115, v132
	s_addc_u32 s3, s13, s3
	global_store_dwordx2 v225, v[114:115], s[2:3] offset:16
.LBB0_2317:
	s_or_b64 exec, exec, s[8:9]
	s_nop 0
	ds_read_b128 v[134:137], v195 offset:16
	ds_read_b128 v[138:141], v195 offset:0
	ds_read_b128 v[142:145], v195 offset:8208
	ds_read_b128 v[146:149], v195 offset:8192
	v_pk_mul_f32 v[104:105], v[104:105], v[132:133] op_sel_hi:[1,0]
	v_pk_mul_f32 v[106:107], v[106:107], v[132:133] op_sel_hi:[1,0]
	v_pk_mul_f32 v[110:111], v[110:111], v[132:133] op_sel_hi:[1,0]
	v_pk_mul_f32 v[108:109], v[108:109], v[132:133] op_sel_hi:[1,0]
	s_mov_b32 s0, 0x16b02000
	v_pk_mul_f32 v[98:99], v[98:99], v[132:133] op_sel_hi:[1,0]
	v_pk_mul_f32 v[102:103], v[102:103], v[132:133] op_sel_hi:[1,0]
	v_pk_mul_f32 v[96:97], v[96:97], v[132:133] op_sel_hi:[1,0]
	v_pk_mul_f32 v[100:101], v[100:101], v[132:133] op_sel_hi:[1,0]
	v_pk_mul_f32 v[84:85], v[84:85], v[132:133] op_sel_hi:[1,0]
	v_pk_mul_f32 v[92:93], v[92:93], v[132:133] op_sel_hi:[1,0]
	v_pk_mul_f32 v[80:81], v[80:81], v[132:133] op_sel_hi:[1,0]
	v_pk_mul_f32 v[88:89], v[88:89], v[132:133] op_sel_hi:[1,0]
	s_waitcnt lgkmcnt(1)
	v_pk_fma_f32 v[110:111], v[110:111], v[134:135], v[142:143]
	s_waitcnt lgkmcnt(0)
	v_pk_fma_f32 v[114:115], v[104:105], v[140:141], v[148:149]
	v_pk_fma_f32 v[106:107], v[106:107], v[138:139], v[146:147]
	v_pk_fma_f32 v[108:109], v[108:109], v[136:137], v[144:145]
	v_cvt_pk_bf16_f32 v105, v114, v115
	v_add_co_u32_e32 v114, vcc, s0, v112
	v_cvt_pk_bf16_f32 v104, v106, v107
	v_cvt_pk_bf16_f32 v106, v110, v111
	v_cvt_pk_bf16_f32 v107, v108, v109
	v_addc_co_u32_e32 v115, vcc, 0, v113, vcc
	global_store_dwordx4 v[114:115], v[104:107], off
	s_nop 0
	ds_read_b128 v[104:107], v195 offset:2064
	s_nop 0
	ds_read_b128 v[108:111], v195 offset:2048
	ds_read_b128 v[134:137], v195 offset:10256
	ds_read_b128 v[138:141], v195 offset:10240
	s_waitcnt lgkmcnt(1)
	v_pk_fma_f32 v[102:103], v[102:103], v[104:105], v[134:135]
	s_waitcnt lgkmcnt(0)
	v_pk_fma_f32 v[98:99], v[98:99], v[108:109], v[138:139]
	v_pk_fma_f32 v[104:105], v[96:97], v[110:111], v[140:141]
	v_pk_fma_f32 v[100:101], v[100:101], v[106:107], v[136:137]
	v_cvt_pk_bf16_f32 v96, v98, v99
	v_cvt_pk_bf16_f32 v97, v104, v105
	v_cvt_pk_bf16_f32 v98, v102, v103
	v_cvt_pk_bf16_f32 v99, v100, v101
	global_store_dwordx4 v[114:115], v[96:99], off offset:1024
	s_nop 0
	ds_read_b128 v[96:99], v195 offset:4112
	s_nop 0
	ds_read_b128 v[100:103], v195 offset:4096
	ds_read_b128 v[104:107], v195 offset:12304
	ds_read_b128 v[108:111], v195 offset:12288
	s_waitcnt lgkmcnt(1)
	v_pk_fma_f32 v[92:93], v[92:93], v[96:97], v[104:105]
	s_waitcnt lgkmcnt(0)
	v_pk_fma_f32 v[84:85], v[84:85], v[100:101], v[108:109]
	v_pk_fma_f32 v[80:81], v[80:81], v[102:103], v[110:111]
	v_pk_fma_f32 v[88:89], v[88:89], v[98:99], v[106:107]
	v_cvt_pk_bf16_f32 v96, v84, v85
	v_cvt_pk_bf16_f32 v97, v80, v81
	v_cvt_pk_bf16_f32 v98, v92, v93
	v_cvt_pk_bf16_f32 v99, v88, v89
	global_store_dwordx4 v[114:115], v[96:99], off offset:2048
	s_nop 0
	ds_read_b128 v[96:99], v195 offset:6160
	s_nop 0
	ds_read_b128 v[100:103], v195 offset:6144
	ds_read_b128 v[104:107], v195 offset:14352
	ds_read_b128 v[108:111], v195 offset:14336
	v_pk_mul_f32 v[80:81], v[82:83], v[132:133] op_sel_hi:[1,0]
	v_pk_mul_f32 v[82:83], v[90:91], v[132:133] op_sel_hi:[1,0]
	v_pk_mul_f32 v[84:85], v[86:87], v[132:133] op_sel_hi:[1,0]
	v_pk_mul_f32 v[86:87], v[94:95], v[132:133] op_sel_hi:[1,0]
	s_waitcnt lgkmcnt(1)
	v_pk_fma_f32 v[82:83], v[82:83], v[96:97], v[104:105]
	s_waitcnt lgkmcnt(0)
	v_pk_fma_f32 v[80:81], v[80:81], v[100:101], v[108:109]
	v_pk_fma_f32 v[84:85], v[84:85], v[102:103], v[110:111]
	v_pk_fma_f32 v[86:87], v[86:87], v[98:99], v[106:107]
	v_cvt_pk_bf16_f32 v80, v80, v81
	v_cvt_pk_bf16_f32 v81, v84, v85
	v_cvt_pk_bf16_f32 v82, v82, v83
	v_cvt_pk_bf16_f32 v83, v86, v87
	global_store_dwordx4 v[114:115], v[80:83], off offset:3072
	s_waitcnt vmcnt(31)
	v_cvt_f32_f16_sdwa v87, v73 dst_sel:DWORD dst_unused:UNUSED_PAD src0_sel:WORD_1
	v_cvt_f32_f16_e32 v86, v73
	v_cvt_f32_f16_sdwa v83, v77 dst_sel:DWORD dst_unused:UNUSED_PAD src0_sel:WORD_1
	v_cvt_f32_f16_e32 v82, v77
	v_cvt_f32_f16_sdwa v77, v76 dst_sel:DWORD dst_unused:UNUSED_PAD src0_sel:WORD_1
	v_cvt_f32_f16_e32 v76, v76
	v_cvt_f32_f16_sdwa v81, v79 dst_sel:DWORD dst_unused:UNUSED_PAD src0_sel:WORD_1
	v_cvt_f32_f16_e32 v80, v79
	v_cvt_f32_f16_sdwa v79, v78 dst_sel:DWORD dst_unused:UNUSED_PAD src0_sel:WORD_1
	v_cvt_f32_f16_e32 v78, v78
	v_add_f32_e32 v84, 0, v76
	v_add_f32_e32 v84, v84, v77
	v_add_f32_e32 v84, v84, v82
	v_add_f32_e32 v84, v84, v83
	v_add_f32_e32 v84, v84, v78
	v_cvt_f32_f16_sdwa v73, v72 dst_sel:DWORD dst_unused:UNUSED_PAD src0_sel:WORD_1
	v_cvt_f32_f16_e32 v72, v72
	v_add_f32_e32 v84, v84, v79
	v_add_f32_e32 v84, v84, v80
	v_add_f32_e32 v88, v84, v81
	v_cvt_f32_f16_sdwa v85, v75 dst_sel:DWORD dst_unused:UNUSED_PAD src0_sel:WORD_1
	v_cvt_f32_f16_e32 v84, v75
	v_cvt_f32_f16_sdwa v75, v74 dst_sel:DWORD dst_unused:UNUSED_PAD src0_sel:WORD_1
	v_cvt_f32_f16_e32 v74, v74
	v_add_f32_e32 v88, v88, v72
	v_add_f32_e32 v88, v88, v73
	v_add_f32_e32 v88, v88, v86
	v_add_f32_e32 v88, v88, v87
	v_add_f32_e32 v88, v88, v74
	v_cvt_f32_f16_sdwa v101, v69 dst_sel:DWORD dst_unused:UNUSED_PAD src0_sel:WORD_1
	v_cvt_f32_f16_e32 v100, v69
	v_cvt_f32_f16_sdwa v69, v68 dst_sel:DWORD dst_unused:UNUSED_PAD src0_sel:WORD_1
	v_cvt_f32_f16_e32 v68, v68
	v_add_f32_e32 v88, v88, v75
	v_add_f32_e32 v88, v88, v84
	v_add_f32_e32 v88, v88, v85
	v_cvt_f32_f16_sdwa v99, v71 dst_sel:DWORD dst_unused:UNUSED_PAD src0_sel:WORD_1
	v_cvt_f32_f16_e32 v98, v71
	v_cvt_f32_f16_sdwa v71, v70 dst_sel:DWORD dst_unused:UNUSED_PAD src0_sel:WORD_1
	v_cvt_f32_f16_e32 v70, v70
	v_add_f32_e32 v88, v88, v68
	v_add_f32_e32 v88, v88, v69
	v_add_f32_e32 v88, v88, v100
	v_add_f32_e32 v88, v88, v101
	v_add_f32_e32 v88, v88, v70
	v_cvt_f32_f16_sdwa v105, v66 dst_sel:DWORD dst_unused:UNUSED_PAD src0_sel:WORD_1
	v_cvt_f32_f16_e32 v104, v66
	v_cvt_f32_f16_e32 v66, v64
	v_add_f32_e32 v88, v88, v71
	v_cvt_f32_f16_sdwa v103, v67 dst_sel:DWORD dst_unused:UNUSED_PAD src0_sel:WORD_1
	v_cvt_f32_f16_e32 v102, v67
	v_cvt_f32_f16_sdwa v67, v64 dst_sel:DWORD dst_unused:UNUSED_PAD src0_sel:WORD_1
	v_add_f32_e32 v88, v88, v98
	v_cvt_f32_f16_e32 v106, v65
	v_add_f32_e32 v88, v88, v99
	v_cvt_f32_f16_sdwa v107, v65 dst_sel:DWORD dst_unused:UNUSED_PAD src0_sel:WORD_1
	v_add_f32_e32 v64, v88, v66
	v_add_f32_e32 v64, v64, v67
	v_add_f32_e32 v64, v64, v106
	v_add_f32_e32 v64, v64, v107
	v_add_f32_e32 v64, v64, v104
	v_add_f32_e32 v64, v64, v105
	v_add_f32_e32 v64, v64, v102
	v_add_f32_e32 v64, v64, v103
	s_nop 1
	v_add_f32_dpp v64, v64, v64 quad_perm:[1,0,3,2] row_mask:0xf bank_mask:0xf bound_ctrl:1
	s_nop 1
	v_add_f32_dpp v64, v64, v64 quad_perm:[2,3,0,1] row_mask:0xf bank_mask:0xf bound_ctrl:1
	s_nop 1
	v_add_f32_dpp v64, v64, v64 row_half_mirror row_mask:0xf bank_mask:0xf bound_ctrl:1
	s_nop 1
	v_add_f32_dpp v64, v64, v64 row_mirror row_mask:0xf bank_mask:0xf bound_ctrl:1
	s_nop 0
	v_readlane_b32 s0, v64, 16
	v_readlane_b32 s7, v64, 48
	v_readlane_b32 s2, v64, 0
	v_readlane_b32 s3, v64, 32
	v_mov_b32_e32 v64, s0
	v_mov_b32_e32 v65, s7
	v_pk_add_f32 v[64:65], s[2:3], v[64:65]
	s_nop 0
	v_add_f32_e32 v64, v64, v65
	v_mul_f32_e32 v96, 0x3a000000, v64
	v_pk_add_f32 v[90:91], v[76:77], v[96:97] op_sel_hi:[1,0] neg_lo:[0,1] neg_hi:[0,1]
	v_pk_add_f32 v[88:89], v[82:83], v[96:97] op_sel_hi:[1,0] neg_lo:[0,1] neg_hi:[0,1]
	v_pk_mul_f32 v[108:109], v[90:91], v[90:91]
	v_pk_mul_f32 v[110:111], v[88:89], v[88:89]
	v_pk_add_f32 v[94:95], v[78:79], v[96:97] op_sel_hi:[1,0] neg_lo:[0,1] neg_hi:[0,1]
	v_pk_add_f32 v[92:93], v[80:81], v[96:97] op_sel_hi:[1,0] neg_lo:[0,1] neg_hi:[0,1]
	v_pk_add_f32 v[82:83], v[72:73], v[96:97] op_sel_hi:[1,0] neg_lo:[0,1] neg_hi:[0,1]
	v_pk_add_f32 v[80:81], v[86:87], v[96:97] op_sel_hi:[1,0] neg_lo:[0,1] neg_hi:[0,1]
	v_pk_add_f32 v[86:87], v[74:75], v[96:97] op_sel_hi:[1,0] neg_lo:[0,1] neg_hi:[0,1]
	v_pk_add_f32 v[84:85], v[84:85], v[96:97] op_sel_hi:[1,0] neg_lo:[0,1] neg_hi:[0,1]
	v_pk_add_f32 v[68:69], v[68:69], v[96:97] op_sel_hi:[1,0] neg_lo:[0,1] neg_hi:[0,1]
	v_pk_add_f32 v[64:65], v[100:101], v[96:97] op_sel_hi:[1,0] neg_lo:[0,1] neg_hi:[0,1]
	v_pk_add_f32 v[76:77], v[70:71], v[96:97] op_sel_hi:[1,0] neg_lo:[0,1] neg_hi:[0,1]
	v_pk_add_f32 v[72:73], v[98:99], v[96:97] op_sel_hi:[1,0] neg_lo:[0,1] neg_hi:[0,1]
	v_pk_add_f32 v[66:67], v[66:67], v[96:97] op_sel_hi:[1,0] neg_lo:[0,1] neg_hi:[0,1]
	v_pk_add_f32 v[70:71], v[106:107], v[96:97] op_sel_hi:[1,0] neg_lo:[0,1] neg_hi:[0,1]
	v_pk_add_f32 v[74:75], v[104:105], v[96:97] op_sel_hi:[1,0] neg_lo:[0,1] neg_hi:[0,1]
	v_pk_add_f32 v[78:79], v[102:103], v[96:97] op_sel_hi:[1,0] neg_lo:[0,1] neg_hi:[0,1]
	v_add_f32_e32 v97, v108, v109
	v_add_f32_e32 v97, v110, v97
	v_pk_mul_f32 v[114:115], v[94:95], v[94:95]
	v_add_f32_e32 v97, v111, v97
	v_add_f32_e32 v97, v114, v97
	v_pk_mul_f32 v[132:133], v[92:93], v[92:93]
	v_add_f32_e32 v97, v115, v97
	v_add_f32_e32 v97, v132, v97
	v_pk_mul_f32 v[134:135], v[82:83], v[82:83]
	v_add_f32_e32 v97, v133, v97
	v_add_f32_e32 v97, v134, v97
	v_pk_mul_f32 v[136:137], v[80:81], v[80:81]
	v_add_f32_e32 v97, v135, v97
	v_add_f32_e32 v97, v136, v97
	v_pk_mul_f32 v[138:139], v[86:87], v[86:87]
	v_add_f32_e32 v97, v137, v97
	v_add_f32_e32 v97, v138, v97
	v_pk_mul_f32 v[140:141], v[84:85], v[84:85]
	v_add_f32_e32 v97, v139, v97
	v_add_f32_e32 v97, v140, v97
	v_pk_mul_f32 v[142:143], v[68:69], v[68:69]
	v_add_f32_e32 v97, v141, v97
	v_add_f32_e32 v97, v142, v97
	v_pk_mul_f32 v[100:101], v[64:65], v[64:65]
	v_add_f32_e32 v97, v143, v97
	v_add_f32_e32 v97, v100, v97
	v_pk_mul_f32 v[144:145], v[76:77], v[76:77]
	v_add_f32_e32 v97, v101, v97
	v_add_f32_e32 v97, v144, v97
	v_pk_mul_f32 v[98:99], v[72:73], v[72:73]
	v_add_f32_e32 v97, v145, v97
	v_add_f32_e32 v97, v98, v97
	v_pk_mul_f32 v[146:147], v[66:67], v[66:67]
	v_add_f32_e32 v97, v99, v97
	v_add_f32_e32 v97, v146, v97
	v_pk_mul_f32 v[106:107], v[70:71], v[70:71]
	v_add_f32_e32 v97, v147, v97
	v_add_f32_e32 v97, v106, v97
	v_pk_mul_f32 v[104:105], v[74:75], v[74:75]
	v_add_f32_e32 v97, v107, v97
	v_add_f32_e32 v97, v104, v97
	v_pk_mul_f32 v[102:103], v[78:79], v[78:79]
	v_add_f32_e32 v97, v105, v97
	v_add_f32_e32 v97, v102, v97
	v_add_f32_e32 v97, v103, v97
	s_nop 1
	v_add_f32_dpp v97, v97, v97 quad_perm:[1,0,3,2] row_mask:0xf bank_mask:0xf bound_ctrl:1
	s_nop 1
	v_add_f32_dpp v97, v97, v97 quad_perm:[2,3,0,1] row_mask:0xf bank_mask:0xf bound_ctrl:1
	s_nop 1
	v_add_f32_dpp v97, v97, v97 row_half_mirror row_mask:0xf bank_mask:0xf bound_ctrl:1
	s_nop 1
	v_add_f32_dpp v97, v97, v97 row_mirror row_mask:0xf bank_mask:0xf bound_ctrl:1
	s_nop 0
	v_readlane_b32 s2, v97, 16
	v_readlane_b32 s0, v97, 0
	s_nop 0
	v_mov_b32_e32 v98, s2
	v_readlane_b32 s2, v97, 48
	v_add_f32_e32 v98, s0, v98
	v_readlane_b32 s0, v97, 32
	v_mov_b32_e32 v97, s2
	s_nop 0
	v_add_f32_e32 v97, s0, v97
	v_add_f32_e32 v97, v98, v97
	v_fmamk_f32 v97, v97, 0x3a000000, v245
	v_cmp_gt_f32_e32 vcc, s87, v97
	v_mul_f32_e32 v98, 0x4f800000, v97
	s_nop 0
	v_cndmask_b32_e32 v97, v97, v98, vcc
	v_sqrt_f32_e32 v98, v97
	s_nop 0
	v_add_u32_e32 v99, -1, v98
	v_fma_f32 v100, -v99, v98, v97
	v_cmp_ge_f32_e64 s[42:43], 0, v100
	v_add_u32_e32 v100, 1, v98
	s_nop 0
	v_cndmask_b32_e64 v99, v98, v99, s[42:43]
	v_fma_f32 v98, -v100, v98, v97
	v_cmp_lt_f32_e64 s[42:43], 0, v98
	s_nop 1
	v_cndmask_b32_e64 v98, v99, v100, s[42:43]
	v_mul_f32_e32 v99, 0x37800000, v98
	v_cndmask_b32_e32 v98, v98, v99, vcc
	v_cmp_class_f32_e32 vcc, v97, v243
	s_nop 1
	v_cndmask_b32_e32 v97, v98, v97, vcc
	v_div_scale_f32 v98, s[2:3], v97, v97, 1.0
	v_rcp_f32_e32 v99, v98
	s_nop 0
	v_fma_f32 v100, -v98, v99, 1.0
	v_fmac_f32_e32 v99, v100, v99
	v_div_scale_f32 v100, vcc, 1.0, v97, 1.0
	v_mul_f32_e32 v101, v100, v99
	v_fma_f32 v102, -v98, v101, v100
	v_fmac_f32_e32 v101, v102, v99
	v_fma_f32 v98, -v98, v101, v100
	v_div_fmas_f32 v98, v98, v99, v101
	v_div_fixup_f32 v98, v98, v97, 1.0
	s_and_saveexec_b64 s[8:9], s[40:41]
	s_cbranch_execz .LBB0_2319
	s_ashr_i32 s45, s44, 31
	s_lshl_b64 s[2:3], s[44:45], 2
	s_add_u32 s2, s12, s2
	v_mov_b32_e32 v97, v98
	s_addc_u32 s3, s13, s3
	global_store_dwordx2 v225, v[96:97], s[2:3] offset:24
.LBB0_2319:
	s_or_b64 exec, exec, s[8:9]
	s_nop 0
	ds_read_b128 v[100:103], v195 offset:16
	ds_read_b128 v[104:107], v195 offset:0
	ds_read_b128 v[108:111], v195 offset:8208
	ds_read_b128 v[132:135], v195 offset:8192
	v_pk_mul_f32 v[88:89], v[88:89], v[98:99] op_sel_hi:[1,0]
	v_pk_mul_f32 v[90:91], v[90:91], v[98:99] op_sel_hi:[1,0]
	v_pk_mul_f32 v[94:95], v[94:95], v[98:99] op_sel_hi:[1,0]
	v_pk_mul_f32 v[92:93], v[92:93], v[98:99] op_sel_hi:[1,0]
	s_mov_b32 s0, 0x16b03000
	v_pk_mul_f32 v[82:83], v[82:83], v[98:99] op_sel_hi:[1,0]
	v_pk_mul_f32 v[86:87], v[86:87], v[98:99] op_sel_hi:[1,0]
	v_pk_mul_f32 v[80:81], v[80:81], v[98:99] op_sel_hi:[1,0]
	v_pk_mul_f32 v[84:85], v[84:85], v[98:99] op_sel_hi:[1,0]
	v_pk_mul_f32 v[68:69], v[68:69], v[98:99] op_sel_hi:[1,0]
	v_pk_mul_f32 v[76:77], v[76:77], v[98:99] op_sel_hi:[1,0]
	v_pk_mul_f32 v[64:65], v[64:65], v[98:99] op_sel_hi:[1,0]
	v_pk_mul_f32 v[72:73], v[72:73], v[98:99] op_sel_hi:[1,0]
	s_waitcnt lgkmcnt(1)
	v_pk_fma_f32 v[94:95], v[94:95], v[100:101], v[108:109]
	s_waitcnt lgkmcnt(0)
	v_pk_fma_f32 v[96:97], v[88:89], v[106:107], v[134:135]
	v_pk_fma_f32 v[90:91], v[90:91], v[104:105], v[132:133]
	v_pk_fma_f32 v[92:93], v[92:93], v[102:103], v[110:111]
	v_cvt_pk_bf16_f32 v89, v96, v97
	v_add_co_u32_e32 v96, vcc, s0, v112
	v_cvt_pk_bf16_f32 v88, v90, v91
	v_cvt_pk_bf16_f32 v90, v94, v95
	v_cvt_pk_bf16_f32 v91, v92, v93
	v_addc_co_u32_e32 v97, vcc, 0, v113, vcc
	global_store_dwordx4 v[96:97], v[88:91], off
	s_nop 0
	ds_read_b128 v[88:91], v195 offset:2064
	s_nop 0
	ds_read_b128 v[92:95], v195 offset:2048
	ds_read_b128 v[100:103], v195 offset:10256
	ds_read_b128 v[104:107], v195 offset:10240
	s_waitcnt lgkmcnt(1)
	v_pk_fma_f32 v[86:87], v[86:87], v[88:89], v[100:101]
	s_waitcnt lgkmcnt(0)
	v_pk_fma_f32 v[82:83], v[82:83], v[92:93], v[104:105]
	v_pk_fma_f32 v[88:89], v[80:81], v[94:95], v[106:107]
	v_pk_fma_f32 v[84:85], v[84:85], v[90:91], v[102:103]
	v_cvt_pk_bf16_f32 v80, v82, v83
	v_cvt_pk_bf16_f32 v81, v88, v89
	v_cvt_pk_bf16_f32 v82, v86, v87
	v_cvt_pk_bf16_f32 v83, v84, v85
	global_store_dwordx4 v[96:97], v[80:83], off offset:1024
	s_nop 0
	ds_read_b128 v[80:83], v195 offset:4112
	s_nop 0
	ds_read_b128 v[84:87], v195 offset:4096
	ds_read_b128 v[88:91], v195 offset:12304
	ds_read_b128 v[92:95], v195 offset:12288
	s_waitcnt lgkmcnt(1)
	v_pk_fma_f32 v[76:77], v[76:77], v[80:81], v[88:89]
	s_waitcnt lgkmcnt(0)
	v_pk_fma_f32 v[68:69], v[68:69], v[84:85], v[92:93]
	v_pk_fma_f32 v[64:65], v[64:65], v[86:87], v[94:95]
	v_pk_fma_f32 v[72:73], v[72:73], v[82:83], v[90:91]
	v_cvt_pk_bf16_f32 v80, v68, v69
	v_cvt_pk_bf16_f32 v81, v64, v65
	v_cvt_pk_bf16_f32 v82, v76, v77
	v_cvt_pk_bf16_f32 v83, v72, v73
	global_store_dwordx4 v[96:97], v[80:83], off offset:2048
	s_nop 0
	ds_read_b128 v[80:83], v195 offset:6160
	s_nop 0
	ds_read_b128 v[84:87], v195 offset:6144
	ds_read_b128 v[88:91], v195 offset:14352
	ds_read_b128 v[92:95], v195 offset:14336
	v_pk_mul_f32 v[64:65], v[66:67], v[98:99] op_sel_hi:[1,0]
	v_pk_mul_f32 v[66:67], v[74:75], v[98:99] op_sel_hi:[1,0]
	v_pk_mul_f32 v[68:69], v[70:71], v[98:99] op_sel_hi:[1,0]
	v_pk_mul_f32 v[70:71], v[78:79], v[98:99] op_sel_hi:[1,0]
	s_waitcnt lgkmcnt(1)
	v_pk_fma_f32 v[66:67], v[66:67], v[80:81], v[88:89]
	s_waitcnt lgkmcnt(0)
	v_pk_fma_f32 v[64:65], v[64:65], v[84:85], v[92:93]
	v_pk_fma_f32 v[68:69], v[68:69], v[86:87], v[94:95]
	v_pk_fma_f32 v[70:71], v[70:71], v[82:83], v[90:91]
	v_cvt_pk_bf16_f32 v64, v64, v65
	v_cvt_pk_bf16_f32 v65, v68, v69
	v_cvt_pk_bf16_f32 v66, v66, v67
	v_cvt_pk_bf16_f32 v67, v70, v71
	global_store_dwordx4 v[96:97], v[64:67], off offset:3072
	s_waitcnt vmcnt(32)
	v_cvt_f32_f16_sdwa v71, v57 dst_sel:DWORD dst_unused:UNUSED_PAD src0_sel:WORD_1
	v_cvt_f32_f16_e32 v70, v57
	v_cvt_f32_f16_sdwa v67, v61 dst_sel:DWORD dst_unused:UNUSED_PAD src0_sel:WORD_1
	v_cvt_f32_f16_e32 v66, v61
	v_cvt_f32_f16_sdwa v61, v60 dst_sel:DWORD dst_unused:UNUSED_PAD src0_sel:WORD_1
	v_cvt_f32_f16_e32 v60, v60
	v_cvt_f32_f16_sdwa v65, v63 dst_sel:DWORD dst_unused:UNUSED_PAD src0_sel:WORD_1
	v_cvt_f32_f16_e32 v64, v63
	v_cvt_f32_f16_sdwa v63, v62 dst_sel:DWORD dst_unused:UNUSED_PAD src0_sel:WORD_1
	v_cvt_f32_f16_e32 v62, v62
	v_add_f32_e32 v68, 0, v60
	v_add_f32_e32 v68, v68, v61
	v_add_f32_e32 v68, v68, v66
	v_add_f32_e32 v68, v68, v67
	v_add_f32_e32 v68, v68, v62
	v_cvt_f32_f16_sdwa v57, v56 dst_sel:DWORD dst_unused:UNUSED_PAD src0_sel:WORD_1
	v_cvt_f32_f16_e32 v56, v56
	v_add_f32_e32 v68, v68, v63
	v_add_f32_e32 v68, v68, v64
	v_add_f32_e32 v72, v68, v65
	v_cvt_f32_f16_sdwa v69, v59 dst_sel:DWORD dst_unused:UNUSED_PAD src0_sel:WORD_1
	v_cvt_f32_f16_e32 v68, v59
	v_cvt_f32_f16_sdwa v59, v58 dst_sel:DWORD dst_unused:UNUSED_PAD src0_sel:WORD_1
	v_cvt_f32_f16_e32 v58, v58
	v_add_f32_e32 v72, v72, v56
	v_add_f32_e32 v72, v72, v57
	v_add_f32_e32 v72, v72, v70
	v_add_f32_e32 v72, v72, v71
	v_add_f32_e32 v72, v72, v58
	v_cvt_f32_f16_sdwa v85, v53 dst_sel:DWORD dst_unused:UNUSED_PAD src0_sel:WORD_1
	v_cvt_f32_f16_e32 v84, v53
	v_cvt_f32_f16_sdwa v53, v52 dst_sel:DWORD dst_unused:UNUSED_PAD src0_sel:WORD_1
	v_cvt_f32_f16_e32 v52, v52
	v_add_f32_e32 v72, v72, v59
	v_add_f32_e32 v72, v72, v68
	v_add_f32_e32 v72, v72, v69
	v_cvt_f32_f16_sdwa v83, v55 dst_sel:DWORD dst_unused:UNUSED_PAD src0_sel:WORD_1
	v_cvt_f32_f16_e32 v82, v55
	v_cvt_f32_f16_sdwa v55, v54 dst_sel:DWORD dst_unused:UNUSED_PAD src0_sel:WORD_1
	v_cvt_f32_f16_e32 v54, v54
	v_add_f32_e32 v72, v72, v52
	v_add_f32_e32 v72, v72, v53
	v_add_f32_e32 v72, v72, v84
	v_add_f32_e32 v72, v72, v85
	v_add_f32_e32 v72, v72, v54
	v_cvt_f32_f16_sdwa v89, v50 dst_sel:DWORD dst_unused:UNUSED_PAD src0_sel:WORD_1
	v_cvt_f32_f16_e32 v88, v50
	v_cvt_f32_f16_e32 v50, v48
	v_add_f32_e32 v72, v72, v55
	v_cvt_f32_f16_sdwa v87, v51 dst_sel:DWORD dst_unused:UNUSED_PAD src0_sel:WORD_1
	v_cvt_f32_f16_e32 v86, v51
	v_cvt_f32_f16_sdwa v51, v48 dst_sel:DWORD dst_unused:UNUSED_PAD src0_sel:WORD_1
	v_add_f32_e32 v72, v72, v82
	v_cvt_f32_f16_e32 v90, v49
	v_add_f32_e32 v72, v72, v83
	v_cvt_f32_f16_sdwa v91, v49 dst_sel:DWORD dst_unused:UNUSED_PAD src0_sel:WORD_1
	v_add_f32_e32 v48, v72, v50
	v_add_f32_e32 v48, v48, v51
	v_add_f32_e32 v48, v48, v90
	v_add_f32_e32 v48, v48, v91
	v_add_f32_e32 v48, v48, v88
	v_add_f32_e32 v48, v48, v89
	v_add_f32_e32 v48, v48, v86
	v_add_f32_e32 v48, v48, v87
	s_nop 1
	v_add_f32_dpp v48, v48, v48 quad_perm:[1,0,3,2] row_mask:0xf bank_mask:0xf bound_ctrl:1
	s_nop 1
	v_add_f32_dpp v48, v48, v48 quad_perm:[2,3,0,1] row_mask:0xf bank_mask:0xf bound_ctrl:1
	s_nop 1
	v_add_f32_dpp v48, v48, v48 row_half_mirror row_mask:0xf bank_mask:0xf bound_ctrl:1
	s_nop 1
	v_add_f32_dpp v48, v48, v48 row_mirror row_mask:0xf bank_mask:0xf bound_ctrl:1
	s_nop 0
	v_readlane_b32 s0, v48, 16
	v_readlane_b32 s7, v48, 48
	v_readlane_b32 s2, v48, 0
	v_readlane_b32 s3, v48, 32
	v_mov_b32_e32 v48, s0
	v_mov_b32_e32 v49, s7
	v_pk_add_f32 v[48:49], s[2:3], v[48:49]
	s_nop 0
	v_add_f32_e32 v48, v48, v49
	v_mul_f32_e32 v80, 0x3a000000, v48
	v_pk_add_f32 v[74:75], v[60:61], v[80:81] op_sel_hi:[1,0] neg_lo:[0,1] neg_hi:[0,1]
	v_pk_add_f32 v[72:73], v[66:67], v[80:81] op_sel_hi:[1,0] neg_lo:[0,1] neg_hi:[0,1]
	v_pk_mul_f32 v[92:93], v[74:75], v[74:75]
	v_pk_mul_f32 v[94:95], v[72:73], v[72:73]
	v_pk_add_f32 v[78:79], v[62:63], v[80:81] op_sel_hi:[1,0] neg_lo:[0,1] neg_hi:[0,1]
	v_pk_add_f32 v[76:77], v[64:65], v[80:81] op_sel_hi:[1,0] neg_lo:[0,1] neg_hi:[0,1]
	v_pk_add_f32 v[66:67], v[56:57], v[80:81] op_sel_hi:[1,0] neg_lo:[0,1] neg_hi:[0,1]
	v_pk_add_f32 v[64:65], v[70:71], v[80:81] op_sel_hi:[1,0] neg_lo:[0,1] neg_hi:[0,1]
	v_pk_add_f32 v[70:71], v[58:59], v[80:81] op_sel_hi:[1,0] neg_lo:[0,1] neg_hi:[0,1]
	v_pk_add_f32 v[68:69], v[68:69], v[80:81] op_sel_hi:[1,0] neg_lo:[0,1] neg_hi:[0,1]
	v_pk_add_f32 v[52:53], v[52:53], v[80:81] op_sel_hi:[1,0] neg_lo:[0,1] neg_hi:[0,1]
	v_pk_add_f32 v[48:49], v[84:85], v[80:81] op_sel_hi:[1,0] neg_lo:[0,1] neg_hi:[0,1]
	v_pk_add_f32 v[60:61], v[54:55], v[80:81] op_sel_hi:[1,0] neg_lo:[0,1] neg_hi:[0,1]
	v_pk_add_f32 v[56:57], v[82:83], v[80:81] op_sel_hi:[1,0] neg_lo:[0,1] neg_hi:[0,1]
	v_pk_add_f32 v[50:51], v[50:51], v[80:81] op_sel_hi:[1,0] neg_lo:[0,1] neg_hi:[0,1]
	v_pk_add_f32 v[54:55], v[90:91], v[80:81] op_sel_hi:[1,0] neg_lo:[0,1] neg_hi:[0,1]
	v_pk_add_f32 v[58:59], v[88:89], v[80:81] op_sel_hi:[1,0] neg_lo:[0,1] neg_hi:[0,1]
	v_pk_add_f32 v[62:63], v[86:87], v[80:81] op_sel_hi:[1,0] neg_lo:[0,1] neg_hi:[0,1]
	v_add_f32_e32 v81, v92, v93
	v_add_f32_e32 v81, v94, v81
	v_pk_mul_f32 v[96:97], v[78:79], v[78:79]
	v_add_f32_e32 v81, v95, v81
	v_add_f32_e32 v81, v96, v81
	v_pk_mul_f32 v[98:99], v[76:77], v[76:77]
	v_add_f32_e32 v81, v97, v81
	v_add_f32_e32 v81, v98, v81
	v_pk_mul_f32 v[100:101], v[66:67], v[66:67]
	v_add_f32_e32 v81, v99, v81
	v_add_f32_e32 v81, v100, v81
	v_pk_mul_f32 v[102:103], v[64:65], v[64:65]
	v_add_f32_e32 v81, v101, v81
	v_add_f32_e32 v81, v102, v81
	v_pk_mul_f32 v[104:105], v[70:71], v[70:71]
	v_add_f32_e32 v81, v103, v81
	v_add_f32_e32 v81, v104, v81
	v_pk_mul_f32 v[106:107], v[68:69], v[68:69]
	v_add_f32_e32 v81, v105, v81
	v_add_f32_e32 v81, v106, v81
	v_pk_mul_f32 v[108:109], v[52:53], v[52:53]
	v_add_f32_e32 v81, v107, v81
	v_add_f32_e32 v81, v108, v81
	v_pk_mul_f32 v[84:85], v[48:49], v[48:49]
	v_add_f32_e32 v81, v109, v81
	v_add_f32_e32 v81, v84, v81
	v_pk_mul_f32 v[110:111], v[60:61], v[60:61]
	v_add_f32_e32 v81, v85, v81
	v_add_f32_e32 v81, v110, v81
	v_pk_mul_f32 v[82:83], v[56:57], v[56:57]
	v_add_f32_e32 v81, v111, v81
	v_add_f32_e32 v81, v82, v81
	v_pk_mul_f32 v[114:115], v[50:51], v[50:51]
	v_add_f32_e32 v81, v83, v81
	v_add_f32_e32 v81, v114, v81
	v_pk_mul_f32 v[90:91], v[54:55], v[54:55]
	v_add_f32_e32 v81, v115, v81
	v_add_f32_e32 v81, v90, v81
	v_pk_mul_f32 v[88:89], v[58:59], v[58:59]
	v_add_f32_e32 v81, v91, v81
	v_add_f32_e32 v81, v88, v81
	v_pk_mul_f32 v[86:87], v[62:63], v[62:63]
	v_add_f32_e32 v81, v89, v81
	v_add_f32_e32 v81, v86, v81
	v_add_f32_e32 v81, v87, v81
	s_nop 1
	v_add_f32_dpp v81, v81, v81 quad_perm:[1,0,3,2] row_mask:0xf bank_mask:0xf bound_ctrl:1
	s_nop 1
	v_add_f32_dpp v81, v81, v81 quad_perm:[2,3,0,1] row_mask:0xf bank_mask:0xf bound_ctrl:1
	s_nop 1
	v_add_f32_dpp v81, v81, v81 row_half_mirror row_mask:0xf bank_mask:0xf bound_ctrl:1
	s_nop 1
	v_add_f32_dpp v81, v81, v81 row_mirror row_mask:0xf bank_mask:0xf bound_ctrl:1
	s_nop 0
	v_readlane_b32 s2, v81, 16
	v_readlane_b32 s0, v81, 0
	s_nop 0
	v_mov_b32_e32 v82, s2
	v_readlane_b32 s2, v81, 48
	v_add_f32_e32 v82, s0, v82
	v_readlane_b32 s0, v81, 32
	v_mov_b32_e32 v81, s2
	s_nop 0
	v_add_f32_e32 v81, s0, v81
	v_add_f32_e32 v81, v82, v81
	v_fmamk_f32 v81, v81, 0x3a000000, v245
	v_cmp_gt_f32_e32 vcc, s87, v81
	v_mul_f32_e32 v82, 0x4f800000, v81
	s_nop 0
	v_cndmask_b32_e32 v81, v81, v82, vcc
	v_sqrt_f32_e32 v82, v81
	s_nop 0
	v_add_u32_e32 v83, -1, v82
	v_fma_f32 v84, -v83, v82, v81
	v_cmp_ge_f32_e64 s[42:43], 0, v84
	v_add_u32_e32 v84, 1, v82
	s_nop 0
	v_cndmask_b32_e64 v83, v82, v83, s[42:43]
	v_fma_f32 v82, -v84, v82, v81
	v_cmp_lt_f32_e64 s[42:43], 0, v82
	s_nop 1
	v_cndmask_b32_e64 v82, v83, v84, s[42:43]
	v_mul_f32_e32 v83, 0x37800000, v82
	v_cndmask_b32_e32 v82, v82, v83, vcc
	v_cmp_class_f32_e32 vcc, v81, v243
	s_nop 1
	v_cndmask_b32_e32 v81, v82, v81, vcc
	v_div_scale_f32 v82, s[2:3], v81, v81, 1.0
	v_rcp_f32_e32 v83, v82
	s_nop 0
	v_fma_f32 v84, -v82, v83, 1.0
	v_fmac_f32_e32 v83, v84, v83
	v_div_scale_f32 v84, vcc, 1.0, v81, 1.0
	v_mul_f32_e32 v85, v84, v83
	v_fma_f32 v86, -v82, v85, v84
	v_fmac_f32_e32 v85, v86, v83
	v_fma_f32 v82, -v82, v85, v84
	v_div_fmas_f32 v82, v82, v83, v85
	v_div_fixup_f32 v82, v82, v81, 1.0
	s_and_saveexec_b64 s[8:9], s[40:41]
	s_cbranch_execz .LBB0_2321
	s_ashr_i32 s45, s44, 31
	s_lshl_b64 s[2:3], s[44:45], 2
	s_add_u32 s2, s12, s2
	v_mov_b32_e32 v81, v82
	s_addc_u32 s3, s13, s3
	global_store_dwordx2 v225, v[80:81], s[2:3] offset:32
.LBB0_2321:
	s_or_b64 exec, exec, s[8:9]
	s_nop 0
	ds_read_b128 v[84:87], v195 offset:16
	ds_read_b128 v[88:91], v195 offset:0
	ds_read_b128 v[92:95], v195 offset:8208
	ds_read_b128 v[96:99], v195 offset:8192
	v_pk_mul_f32 v[72:73], v[72:73], v[82:83] op_sel_hi:[1,0]
	v_pk_mul_f32 v[74:75], v[74:75], v[82:83] op_sel_hi:[1,0]
	v_pk_mul_f32 v[78:79], v[78:79], v[82:83] op_sel_hi:[1,0]
	v_pk_mul_f32 v[76:77], v[76:77], v[82:83] op_sel_hi:[1,0]
	s_mov_b32 s0, 0x16b04000
	v_pk_mul_f32 v[66:67], v[66:67], v[82:83] op_sel_hi:[1,0]
	v_pk_mul_f32 v[70:71], v[70:71], v[82:83] op_sel_hi:[1,0]
	v_pk_mul_f32 v[64:65], v[64:65], v[82:83] op_sel_hi:[1,0]
	v_pk_mul_f32 v[68:69], v[68:69], v[82:83] op_sel_hi:[1,0]
	v_pk_mul_f32 v[52:53], v[52:53], v[82:83] op_sel_hi:[1,0]
	v_pk_mul_f32 v[60:61], v[60:61], v[82:83] op_sel_hi:[1,0]
	v_pk_mul_f32 v[48:49], v[48:49], v[82:83] op_sel_hi:[1,0]
	v_pk_mul_f32 v[56:57], v[56:57], v[82:83] op_sel_hi:[1,0]
	s_waitcnt lgkmcnt(1)
	v_pk_fma_f32 v[78:79], v[78:79], v[84:85], v[92:93]
	s_waitcnt lgkmcnt(0)
	v_pk_fma_f32 v[80:81], v[72:73], v[90:91], v[98:99]
	v_pk_fma_f32 v[74:75], v[74:75], v[88:89], v[96:97]
	v_pk_fma_f32 v[76:77], v[76:77], v[86:87], v[94:95]
	v_cvt_pk_bf16_f32 v73, v80, v81
	v_add_co_u32_e32 v80, vcc, s0, v112
	v_cvt_pk_bf16_f32 v72, v74, v75
	v_cvt_pk_bf16_f32 v74, v78, v79
	v_cvt_pk_bf16_f32 v75, v76, v77
	v_addc_co_u32_e32 v81, vcc, 0, v113, vcc
	global_store_dwordx4 v[80:81], v[72:75], off
	s_nop 0
	ds_read_b128 v[72:75], v195 offset:2064
	s_nop 0
	ds_read_b128 v[76:79], v195 offset:2048
	ds_read_b128 v[84:87], v195 offset:10256
	ds_read_b128 v[88:91], v195 offset:10240
	s_waitcnt lgkmcnt(1)
	v_pk_fma_f32 v[70:71], v[70:71], v[72:73], v[84:85]
	s_waitcnt lgkmcnt(0)
	v_pk_fma_f32 v[66:67], v[66:67], v[76:77], v[88:89]
	v_pk_fma_f32 v[72:73], v[64:65], v[78:79], v[90:91]
	v_pk_fma_f32 v[68:69], v[68:69], v[74:75], v[86:87]
	v_cvt_pk_bf16_f32 v64, v66, v67
	v_cvt_pk_bf16_f32 v65, v72, v73
	v_cvt_pk_bf16_f32 v66, v70, v71
	v_cvt_pk_bf16_f32 v67, v68, v69
	global_store_dwordx4 v[80:81], v[64:67], off offset:1024
	s_nop 0
	ds_read_b128 v[64:67], v195 offset:4112
	s_nop 0
	ds_read_b128 v[68:71], v195 offset:4096
	ds_read_b128 v[72:75], v195 offset:12304
	ds_read_b128 v[76:79], v195 offset:12288
	s_waitcnt lgkmcnt(1)
	v_pk_fma_f32 v[60:61], v[60:61], v[64:65], v[72:73]
	s_waitcnt lgkmcnt(0)
	v_pk_fma_f32 v[52:53], v[52:53], v[68:69], v[76:77]
	v_pk_fma_f32 v[48:49], v[48:49], v[70:71], v[78:79]
	v_pk_fma_f32 v[56:57], v[56:57], v[66:67], v[74:75]
	v_cvt_pk_bf16_f32 v64, v52, v53
	v_cvt_pk_bf16_f32 v65, v48, v49
	v_cvt_pk_bf16_f32 v66, v60, v61
	v_cvt_pk_bf16_f32 v67, v56, v57
	global_store_dwordx4 v[80:81], v[64:67], off offset:2048
	s_nop 0
	ds_read_b128 v[64:67], v195 offset:6160
	s_nop 0
	ds_read_b128 v[68:71], v195 offset:6144
	ds_read_b128 v[72:75], v195 offset:14352
	ds_read_b128 v[76:79], v195 offset:14336
	v_pk_mul_f32 v[48:49], v[50:51], v[82:83] op_sel_hi:[1,0]
	v_pk_mul_f32 v[50:51], v[58:59], v[82:83] op_sel_hi:[1,0]
	v_pk_mul_f32 v[52:53], v[54:55], v[82:83] op_sel_hi:[1,0]
	v_pk_mul_f32 v[54:55], v[62:63], v[82:83] op_sel_hi:[1,0]
	s_waitcnt lgkmcnt(1)
	v_pk_fma_f32 v[50:51], v[50:51], v[64:65], v[72:73]
	s_waitcnt lgkmcnt(0)
	v_pk_fma_f32 v[48:49], v[48:49], v[68:69], v[76:77]
	v_pk_fma_f32 v[52:53], v[52:53], v[70:71], v[78:79]
	v_pk_fma_f32 v[54:55], v[54:55], v[66:67], v[74:75]
	v_cvt_pk_bf16_f32 v48, v48, v49
	v_cvt_pk_bf16_f32 v49, v52, v53
	v_cvt_pk_bf16_f32 v50, v50, v51
	v_cvt_pk_bf16_f32 v51, v54, v55
	global_store_dwordx4 v[80:81], v[48:51], off offset:3072
	s_waitcnt vmcnt(33)
	v_cvt_f32_f16_sdwa v55, v41 dst_sel:DWORD dst_unused:UNUSED_PAD src0_sel:WORD_1
	v_cvt_f32_f16_e32 v54, v41
	v_cvt_f32_f16_sdwa v51, v45 dst_sel:DWORD dst_unused:UNUSED_PAD src0_sel:WORD_1
	v_cvt_f32_f16_e32 v50, v45
	v_cvt_f32_f16_sdwa v45, v44 dst_sel:DWORD dst_unused:UNUSED_PAD src0_sel:WORD_1
	v_cvt_f32_f16_e32 v44, v44
	v_cvt_f32_f16_sdwa v49, v47 dst_sel:DWORD dst_unused:UNUSED_PAD src0_sel:WORD_1
	v_cvt_f32_f16_e32 v48, v47
	v_cvt_f32_f16_sdwa v47, v46 dst_sel:DWORD dst_unused:UNUSED_PAD src0_sel:WORD_1
	v_cvt_f32_f16_e32 v46, v46
	v_add_f32_e32 v52, 0, v44
	v_add_f32_e32 v52, v52, v45
	v_add_f32_e32 v52, v52, v50
	v_add_f32_e32 v52, v52, v51
	v_add_f32_e32 v52, v52, v46
	v_cvt_f32_f16_sdwa v41, v40 dst_sel:DWORD dst_unused:UNUSED_PAD src0_sel:WORD_1
	v_cvt_f32_f16_e32 v40, v40
	v_add_f32_e32 v52, v52, v47
	v_add_f32_e32 v52, v52, v48
	v_add_f32_e32 v56, v52, v49
	v_cvt_f32_f16_sdwa v53, v43 dst_sel:DWORD dst_unused:UNUSED_PAD src0_sel:WORD_1
	v_cvt_f32_f16_e32 v52, v43
	v_cvt_f32_f16_sdwa v43, v42 dst_sel:DWORD dst_unused:UNUSED_PAD src0_sel:WORD_1
	v_cvt_f32_f16_e32 v42, v42
	v_add_f32_e32 v56, v56, v40
	v_add_f32_e32 v56, v56, v41
	v_add_f32_e32 v56, v56, v54
	v_add_f32_e32 v56, v56, v55
	v_add_f32_e32 v56, v56, v42
	v_cvt_f32_f16_sdwa v69, v37 dst_sel:DWORD dst_unused:UNUSED_PAD src0_sel:WORD_1
	v_cvt_f32_f16_e32 v68, v37
	v_cvt_f32_f16_sdwa v37, v36 dst_sel:DWORD dst_unused:UNUSED_PAD src0_sel:WORD_1
	v_cvt_f32_f16_e32 v36, v36
	v_add_f32_e32 v56, v56, v43
	v_add_f32_e32 v56, v56, v52
	v_add_f32_e32 v56, v56, v53
	v_cvt_f32_f16_sdwa v67, v39 dst_sel:DWORD dst_unused:UNUSED_PAD src0_sel:WORD_1
	v_cvt_f32_f16_e32 v66, v39
	v_cvt_f32_f16_sdwa v39, v38 dst_sel:DWORD dst_unused:UNUSED_PAD src0_sel:WORD_1
	v_cvt_f32_f16_e32 v38, v38
	v_add_f32_e32 v56, v56, v36
	v_add_f32_e32 v56, v56, v37
	v_add_f32_e32 v56, v56, v68
	v_add_f32_e32 v56, v56, v69
	v_add_f32_e32 v56, v56, v38
	v_cvt_f32_f16_sdwa v73, v34 dst_sel:DWORD dst_unused:UNUSED_PAD src0_sel:WORD_1
	v_cvt_f32_f16_e32 v72, v34
	v_cvt_f32_f16_e32 v34, v32
	v_add_f32_e32 v56, v56, v39
	v_cvt_f32_f16_sdwa v71, v35 dst_sel:DWORD dst_unused:UNUSED_PAD src0_sel:WORD_1
	v_cvt_f32_f16_e32 v70, v35
	v_cvt_f32_f16_sdwa v35, v32 dst_sel:DWORD dst_unused:UNUSED_PAD src0_sel:WORD_1
	v_add_f32_e32 v56, v56, v66
	v_cvt_f32_f16_e32 v74, v33
	v_add_f32_e32 v56, v56, v67
	v_cvt_f32_f16_sdwa v75, v33 dst_sel:DWORD dst_unused:UNUSED_PAD src0_sel:WORD_1
	v_add_f32_e32 v32, v56, v34
	v_add_f32_e32 v32, v32, v35
	v_add_f32_e32 v32, v32, v74
	v_add_f32_e32 v32, v32, v75
	v_add_f32_e32 v32, v32, v72
	v_add_f32_e32 v32, v32, v73
	v_add_f32_e32 v32, v32, v70
	v_add_f32_e32 v32, v32, v71
	s_nop 1
	v_add_f32_dpp v32, v32, v32 quad_perm:[1,0,3,2] row_mask:0xf bank_mask:0xf bound_ctrl:1
	s_nop 1
	v_add_f32_dpp v32, v32, v32 quad_perm:[2,3,0,1] row_mask:0xf bank_mask:0xf bound_ctrl:1
	s_nop 1
	v_add_f32_dpp v32, v32, v32 row_half_mirror row_mask:0xf bank_mask:0xf bound_ctrl:1
	s_nop 1
	v_add_f32_dpp v32, v32, v32 row_mirror row_mask:0xf bank_mask:0xf bound_ctrl:1
	s_nop 0
	v_readlane_b32 s0, v32, 16
	v_readlane_b32 s7, v32, 48
	v_readlane_b32 s2, v32, 0
	v_readlane_b32 s3, v32, 32
	v_mov_b32_e32 v32, s0
	v_mov_b32_e32 v33, s7
	v_pk_add_f32 v[32:33], s[2:3], v[32:33]
	s_nop 0
	v_add_f32_e32 v32, v32, v33
	v_mul_f32_e32 v64, 0x3a000000, v32
	v_pk_add_f32 v[58:59], v[44:45], v[64:65] op_sel_hi:[1,0] neg_lo:[0,1] neg_hi:[0,1]
	v_pk_add_f32 v[56:57], v[50:51], v[64:65] op_sel_hi:[1,0] neg_lo:[0,1] neg_hi:[0,1]
	v_pk_mul_f32 v[76:77], v[58:59], v[58:59]
	v_pk_mul_f32 v[78:79], v[56:57], v[56:57]
	v_pk_add_f32 v[62:63], v[46:47], v[64:65] op_sel_hi:[1,0] neg_lo:[0,1] neg_hi:[0,1]
	v_pk_add_f32 v[60:61], v[48:49], v[64:65] op_sel_hi:[1,0] neg_lo:[0,1] neg_hi:[0,1]
	v_pk_add_f32 v[50:51], v[40:41], v[64:65] op_sel_hi:[1,0] neg_lo:[0,1] neg_hi:[0,1]
	v_pk_add_f32 v[48:49], v[54:55], v[64:65] op_sel_hi:[1,0] neg_lo:[0,1] neg_hi:[0,1]
	v_pk_add_f32 v[54:55], v[42:43], v[64:65] op_sel_hi:[1,0] neg_lo:[0,1] neg_hi:[0,1]
	v_pk_add_f32 v[52:53], v[52:53], v[64:65] op_sel_hi:[1,0] neg_lo:[0,1] neg_hi:[0,1]
	v_pk_add_f32 v[36:37], v[36:37], v[64:65] op_sel_hi:[1,0] neg_lo:[0,1] neg_hi:[0,1]
	v_pk_add_f32 v[32:33], v[68:69], v[64:65] op_sel_hi:[1,0] neg_lo:[0,1] neg_hi:[0,1]
	v_pk_add_f32 v[44:45], v[38:39], v[64:65] op_sel_hi:[1,0] neg_lo:[0,1] neg_hi:[0,1]
	v_pk_add_f32 v[40:41], v[66:67], v[64:65] op_sel_hi:[1,0] neg_lo:[0,1] neg_hi:[0,1]
	v_pk_add_f32 v[34:35], v[34:35], v[64:65] op_sel_hi:[1,0] neg_lo:[0,1] neg_hi:[0,1]
	v_pk_add_f32 v[38:39], v[74:75], v[64:65] op_sel_hi:[1,0] neg_lo:[0,1] neg_hi:[0,1]
	v_pk_add_f32 v[42:43], v[72:73], v[64:65] op_sel_hi:[1,0] neg_lo:[0,1] neg_hi:[0,1]
	v_pk_add_f32 v[46:47], v[70:71], v[64:65] op_sel_hi:[1,0] neg_lo:[0,1] neg_hi:[0,1]
	v_add_f32_e32 v65, v76, v77
	v_add_f32_e32 v65, v78, v65
	v_pk_mul_f32 v[80:81], v[62:63], v[62:63]
	v_add_f32_e32 v65, v79, v65
	v_add_f32_e32 v65, v80, v65
	v_pk_mul_f32 v[82:83], v[60:61], v[60:61]
	v_add_f32_e32 v65, v81, v65
	v_add_f32_e32 v65, v82, v65
	v_pk_mul_f32 v[84:85], v[50:51], v[50:51]
	v_add_f32_e32 v65, v83, v65
	v_add_f32_e32 v65, v84, v65
	v_pk_mul_f32 v[86:87], v[48:49], v[48:49]
	v_add_f32_e32 v65, v85, v65
	v_add_f32_e32 v65, v86, v65
	v_pk_mul_f32 v[88:89], v[54:55], v[54:55]
	v_add_f32_e32 v65, v87, v65
	v_add_f32_e32 v65, v88, v65
	v_pk_mul_f32 v[90:91], v[52:53], v[52:53]
	v_add_f32_e32 v65, v89, v65
	v_add_f32_e32 v65, v90, v65
	v_pk_mul_f32 v[92:93], v[36:37], v[36:37]
	v_add_f32_e32 v65, v91, v65
	v_add_f32_e32 v65, v92, v65
	v_pk_mul_f32 v[68:69], v[32:33], v[32:33]
	v_add_f32_e32 v65, v93, v65
	v_add_f32_e32 v65, v68, v65
	v_pk_mul_f32 v[94:95], v[44:45], v[44:45]
	v_add_f32_e32 v65, v69, v65
	v_add_f32_e32 v65, v94, v65
	v_pk_mul_f32 v[66:67], v[40:41], v[40:41]
	v_add_f32_e32 v65, v95, v65
	v_add_f32_e32 v65, v66, v65
	v_pk_mul_f32 v[96:97], v[34:35], v[34:35]
	v_add_f32_e32 v65, v67, v65
	v_add_f32_e32 v65, v96, v65
	v_pk_mul_f32 v[74:75], v[38:39], v[38:39]
	v_add_f32_e32 v65, v97, v65
	v_add_f32_e32 v65, v74, v65
	v_pk_mul_f32 v[72:73], v[42:43], v[42:43]
	v_add_f32_e32 v65, v75, v65
	v_add_f32_e32 v65, v72, v65
	v_pk_mul_f32 v[70:71], v[46:47], v[46:47]
	v_add_f32_e32 v65, v73, v65
	v_add_f32_e32 v65, v70, v65
	v_add_f32_e32 v65, v71, v65
	s_nop 1
	v_add_f32_dpp v65, v65, v65 quad_perm:[1,0,3,2] row_mask:0xf bank_mask:0xf bound_ctrl:1
	s_nop 1
	v_add_f32_dpp v65, v65, v65 quad_perm:[2,3,0,1] row_mask:0xf bank_mask:0xf bound_ctrl:1
	s_nop 1
	v_add_f32_dpp v65, v65, v65 row_half_mirror row_mask:0xf bank_mask:0xf bound_ctrl:1
	s_nop 1
	v_add_f32_dpp v65, v65, v65 row_mirror row_mask:0xf bank_mask:0xf bound_ctrl:1
	s_nop 0
	v_readlane_b32 s2, v65, 16
	v_readlane_b32 s0, v65, 0
	s_nop 0
	v_mov_b32_e32 v66, s2
	v_readlane_b32 s2, v65, 48
	v_add_f32_e32 v66, s0, v66
	v_readlane_b32 s0, v65, 32
	v_mov_b32_e32 v65, s2
	s_nop 0
	v_add_f32_e32 v65, s0, v65
	v_add_f32_e32 v65, v66, v65
	v_fmamk_f32 v65, v65, 0x3a000000, v245
	v_cmp_gt_f32_e32 vcc, s87, v65
	v_mul_f32_e32 v66, 0x4f800000, v65
	s_nop 0
	v_cndmask_b32_e32 v65, v65, v66, vcc
	v_sqrt_f32_e32 v66, v65
	s_nop 0
	v_add_u32_e32 v67, -1, v66
	v_fma_f32 v68, -v67, v66, v65
	v_cmp_ge_f32_e64 s[42:43], 0, v68
	v_add_u32_e32 v68, 1, v66
	s_nop 0
	v_cndmask_b32_e64 v67, v66, v67, s[42:43]
	v_fma_f32 v66, -v68, v66, v65
	v_cmp_lt_f32_e64 s[42:43], 0, v66
	s_nop 1
	v_cndmask_b32_e64 v66, v67, v68, s[42:43]
	v_mul_f32_e32 v67, 0x37800000, v66
	v_cndmask_b32_e32 v66, v66, v67, vcc
	v_cmp_class_f32_e32 vcc, v65, v243
	s_nop 1
	v_cndmask_b32_e32 v65, v66, v65, vcc
	v_div_scale_f32 v66, s[2:3], v65, v65, 1.0
	v_rcp_f32_e32 v67, v66
	s_nop 0
	v_fma_f32 v68, -v66, v67, 1.0
	v_fmac_f32_e32 v67, v68, v67
	v_div_scale_f32 v68, vcc, 1.0, v65, 1.0
	v_mul_f32_e32 v69, v68, v67
	v_fma_f32 v70, -v66, v69, v68
	v_fmac_f32_e32 v69, v70, v67
	v_fma_f32 v66, -v66, v69, v68
	v_div_fmas_f32 v66, v66, v67, v69
	v_div_fixup_f32 v66, v66, v65, 1.0
	s_and_saveexec_b64 s[8:9], s[40:41]
	s_cbranch_execz .LBB0_2323
	s_ashr_i32 s45, s44, 31
	s_lshl_b64 s[2:3], s[44:45], 2
	s_add_u32 s2, s12, s2
	v_mov_b32_e32 v65, v66
	s_addc_u32 s3, s13, s3
	global_store_dwordx2 v225, v[64:65], s[2:3] offset:40
.LBB0_2323:
	s_or_b64 exec, exec, s[8:9]
	s_nop 0
	ds_read_b128 v[68:71], v195 offset:16
	ds_read_b128 v[72:75], v195 offset:0
	ds_read_b128 v[76:79], v195 offset:8208
	ds_read_b128 v[80:83], v195 offset:8192
	v_pk_mul_f32 v[56:57], v[56:57], v[66:67] op_sel_hi:[1,0]
	v_pk_mul_f32 v[58:59], v[58:59], v[66:67] op_sel_hi:[1,0]
	v_pk_mul_f32 v[62:63], v[62:63], v[66:67] op_sel_hi:[1,0]
	v_pk_mul_f32 v[60:61], v[60:61], v[66:67] op_sel_hi:[1,0]
	s_mov_b32 s0, 0x16b05000
	v_pk_mul_f32 v[50:51], v[50:51], v[66:67] op_sel_hi:[1,0]
	v_pk_mul_f32 v[54:55], v[54:55], v[66:67] op_sel_hi:[1,0]
	v_pk_mul_f32 v[48:49], v[48:49], v[66:67] op_sel_hi:[1,0]
	v_pk_mul_f32 v[52:53], v[52:53], v[66:67] op_sel_hi:[1,0]
	v_pk_mul_f32 v[36:37], v[36:37], v[66:67] op_sel_hi:[1,0]
	v_pk_mul_f32 v[44:45], v[44:45], v[66:67] op_sel_hi:[1,0]
	v_pk_mul_f32 v[32:33], v[32:33], v[66:67] op_sel_hi:[1,0]
	v_pk_mul_f32 v[40:41], v[40:41], v[66:67] op_sel_hi:[1,0]
	s_waitcnt lgkmcnt(1)
	v_pk_fma_f32 v[62:63], v[62:63], v[68:69], v[76:77]
	s_waitcnt lgkmcnt(0)
	v_pk_fma_f32 v[64:65], v[56:57], v[74:75], v[82:83]
	v_pk_fma_f32 v[58:59], v[58:59], v[72:73], v[80:81]
	v_pk_fma_f32 v[60:61], v[60:61], v[70:71], v[78:79]
	v_cvt_pk_bf16_f32 v57, v64, v65
	v_add_co_u32_e32 v64, vcc, s0, v112
	v_cvt_pk_bf16_f32 v56, v58, v59
	v_cvt_pk_bf16_f32 v58, v62, v63
	v_cvt_pk_bf16_f32 v59, v60, v61
	v_addc_co_u32_e32 v65, vcc, 0, v113, vcc
	global_store_dwordx4 v[64:65], v[56:59], off
	s_nop 0
	ds_read_b128 v[56:59], v195 offset:2064
	s_nop 0
	ds_read_b128 v[60:63], v195 offset:2048
	ds_read_b128 v[68:71], v195 offset:10256
	ds_read_b128 v[72:75], v195 offset:10240
	s_waitcnt lgkmcnt(1)
	v_pk_fma_f32 v[54:55], v[54:55], v[56:57], v[68:69]
	s_waitcnt lgkmcnt(0)
	v_pk_fma_f32 v[50:51], v[50:51], v[60:61], v[72:73]
	v_pk_fma_f32 v[56:57], v[48:49], v[62:63], v[74:75]
	v_pk_fma_f32 v[52:53], v[52:53], v[58:59], v[70:71]
	v_cvt_pk_bf16_f32 v48, v50, v51
	v_cvt_pk_bf16_f32 v49, v56, v57
	v_cvt_pk_bf16_f32 v50, v54, v55
	v_cvt_pk_bf16_f32 v51, v52, v53
	global_store_dwordx4 v[64:65], v[48:51], off offset:1024
	s_nop 0
	ds_read_b128 v[48:51], v195 offset:4112
	s_nop 0
	ds_read_b128 v[52:55], v195 offset:4096
	ds_read_b128 v[56:59], v195 offset:12304
	ds_read_b128 v[60:63], v195 offset:12288
	s_waitcnt lgkmcnt(1)
	v_pk_fma_f32 v[44:45], v[44:45], v[48:49], v[56:57]
	s_waitcnt lgkmcnt(0)
	v_pk_fma_f32 v[36:37], v[36:37], v[52:53], v[60:61]
	v_pk_fma_f32 v[32:33], v[32:33], v[54:55], v[62:63]
	v_pk_fma_f32 v[40:41], v[40:41], v[50:51], v[58:59]
	v_cvt_pk_bf16_f32 v48, v36, v37
	v_cvt_pk_bf16_f32 v49, v32, v33
	v_cvt_pk_bf16_f32 v50, v44, v45
	v_cvt_pk_bf16_f32 v51, v40, v41
	global_store_dwordx4 v[64:65], v[48:51], off offset:2048
	s_nop 0
	ds_read_b128 v[48:51], v195 offset:6160
	s_nop 0
	ds_read_b128 v[52:55], v195 offset:6144
	ds_read_b128 v[56:59], v195 offset:14352
	ds_read_b128 v[60:63], v195 offset:14336
	v_pk_mul_f32 v[32:33], v[34:35], v[66:67] op_sel_hi:[1,0]
	v_pk_mul_f32 v[34:35], v[42:43], v[66:67] op_sel_hi:[1,0]
	v_pk_mul_f32 v[36:37], v[38:39], v[66:67] op_sel_hi:[1,0]
	v_pk_mul_f32 v[38:39], v[46:47], v[66:67] op_sel_hi:[1,0]
	s_waitcnt lgkmcnt(1)
	v_pk_fma_f32 v[34:35], v[34:35], v[48:49], v[56:57]
	s_waitcnt lgkmcnt(0)
	v_pk_fma_f32 v[32:33], v[32:33], v[52:53], v[60:61]
	v_pk_fma_f32 v[36:37], v[36:37], v[54:55], v[62:63]
	v_pk_fma_f32 v[38:39], v[38:39], v[50:51], v[58:59]
	v_cvt_pk_bf16_f32 v32, v32, v33
	v_cvt_pk_bf16_f32 v33, v36, v37
	v_cvt_pk_bf16_f32 v34, v34, v35
	v_cvt_pk_bf16_f32 v35, v38, v39
	global_store_dwordx4 v[64:65], v[32:35], off offset:3072
	s_waitcnt vmcnt(34)
	v_cvt_f32_f16_sdwa v39, v25 dst_sel:DWORD dst_unused:UNUSED_PAD src0_sel:WORD_1
	v_cvt_f32_f16_e32 v38, v25
	v_cvt_f32_f16_sdwa v35, v29 dst_sel:DWORD dst_unused:UNUSED_PAD src0_sel:WORD_1
	v_cvt_f32_f16_e32 v34, v29
	v_cvt_f32_f16_sdwa v29, v28 dst_sel:DWORD dst_unused:UNUSED_PAD src0_sel:WORD_1
	v_cvt_f32_f16_e32 v28, v28
	v_cvt_f32_f16_sdwa v33, v31 dst_sel:DWORD dst_unused:UNUSED_PAD src0_sel:WORD_1
	v_cvt_f32_f16_e32 v32, v31
	v_cvt_f32_f16_sdwa v31, v30 dst_sel:DWORD dst_unused:UNUSED_PAD src0_sel:WORD_1
	v_cvt_f32_f16_e32 v30, v30
	v_add_f32_e32 v36, 0, v28
	v_add_f32_e32 v36, v36, v29
	v_add_f32_e32 v36, v36, v34
	v_add_f32_e32 v36, v36, v35
	v_add_f32_e32 v36, v36, v30
	v_cvt_f32_f16_sdwa v25, v24 dst_sel:DWORD dst_unused:UNUSED_PAD src0_sel:WORD_1
	v_cvt_f32_f16_e32 v24, v24
	v_add_f32_e32 v36, v36, v31
	v_add_f32_e32 v36, v36, v32
	v_add_f32_e32 v40, v36, v33
	v_cvt_f32_f16_sdwa v37, v27 dst_sel:DWORD dst_unused:UNUSED_PAD src0_sel:WORD_1
	v_cvt_f32_f16_e32 v36, v27
	v_cvt_f32_f16_sdwa v27, v26 dst_sel:DWORD dst_unused:UNUSED_PAD src0_sel:WORD_1
	v_cvt_f32_f16_e32 v26, v26
	v_add_f32_e32 v40, v40, v24
	v_add_f32_e32 v40, v40, v25
	v_add_f32_e32 v40, v40, v38
	v_add_f32_e32 v40, v40, v39
	v_add_f32_e32 v40, v40, v26
	v_cvt_f32_f16_sdwa v53, v21 dst_sel:DWORD dst_unused:UNUSED_PAD src0_sel:WORD_1
	v_cvt_f32_f16_e32 v52, v21
	v_cvt_f32_f16_sdwa v21, v20 dst_sel:DWORD dst_unused:UNUSED_PAD src0_sel:WORD_1
	v_cvt_f32_f16_e32 v20, v20
	v_add_f32_e32 v40, v40, v27
	v_add_f32_e32 v40, v40, v36
	v_add_f32_e32 v40, v40, v37
	v_cvt_f32_f16_sdwa v51, v23 dst_sel:DWORD dst_unused:UNUSED_PAD src0_sel:WORD_1
	v_cvt_f32_f16_e32 v50, v23
	v_cvt_f32_f16_sdwa v23, v22 dst_sel:DWORD dst_unused:UNUSED_PAD src0_sel:WORD_1
	v_cvt_f32_f16_e32 v22, v22
	v_add_f32_e32 v40, v40, v20
	v_add_f32_e32 v40, v40, v21
	v_add_f32_e32 v40, v40, v52
	v_add_f32_e32 v40, v40, v53
	v_add_f32_e32 v40, v40, v22
	v_cvt_f32_f16_sdwa v57, v18 dst_sel:DWORD dst_unused:UNUSED_PAD src0_sel:WORD_1
	v_cvt_f32_f16_e32 v56, v18
	v_cvt_f32_f16_e32 v18, v16
	v_add_f32_e32 v40, v40, v23
	v_cvt_f32_f16_sdwa v55, v19 dst_sel:DWORD dst_unused:UNUSED_PAD src0_sel:WORD_1
	v_cvt_f32_f16_e32 v54, v19
	v_cvt_f32_f16_sdwa v19, v16 dst_sel:DWORD dst_unused:UNUSED_PAD src0_sel:WORD_1
	v_add_f32_e32 v40, v40, v50
	v_cvt_f32_f16_e32 v58, v17
	v_add_f32_e32 v40, v40, v51
	v_cvt_f32_f16_sdwa v59, v17 dst_sel:DWORD dst_unused:UNUSED_PAD src0_sel:WORD_1
	v_add_f32_e32 v16, v40, v18
	v_add_f32_e32 v16, v16, v19
	v_add_f32_e32 v16, v16, v58
	v_add_f32_e32 v16, v16, v59
	v_add_f32_e32 v16, v16, v56
	v_add_f32_e32 v16, v16, v57
	v_add_f32_e32 v16, v16, v54
	v_add_f32_e32 v16, v16, v55
	s_nop 1
	v_add_f32_dpp v16, v16, v16 quad_perm:[1,0,3,2] row_mask:0xf bank_mask:0xf bound_ctrl:1
	s_nop 1
	v_add_f32_dpp v16, v16, v16 quad_perm:[2,3,0,1] row_mask:0xf bank_mask:0xf bound_ctrl:1
	s_nop 1
	v_add_f32_dpp v16, v16, v16 row_half_mirror row_mask:0xf bank_mask:0xf bound_ctrl:1
	s_nop 1
	v_add_f32_dpp v16, v16, v16 row_mirror row_mask:0xf bank_mask:0xf bound_ctrl:1
	s_nop 0
	v_readlane_b32 s0, v16, 16
	v_readlane_b32 s7, v16, 48
	v_readlane_b32 s2, v16, 0
	v_readlane_b32 s3, v16, 32
	v_mov_b32_e32 v16, s0
	v_mov_b32_e32 v17, s7
	v_pk_add_f32 v[16:17], s[2:3], v[16:17]
	s_nop 0
	v_add_f32_e32 v16, v16, v17
	v_mul_f32_e32 v48, 0x3a000000, v16
	v_pk_add_f32 v[42:43], v[28:29], v[48:49] op_sel_hi:[1,0] neg_lo:[0,1] neg_hi:[0,1]
	v_pk_add_f32 v[40:41], v[34:35], v[48:49] op_sel_hi:[1,0] neg_lo:[0,1] neg_hi:[0,1]
	v_pk_mul_f32 v[60:61], v[42:43], v[42:43]
	v_pk_mul_f32 v[62:63], v[40:41], v[40:41]
	v_pk_add_f32 v[46:47], v[30:31], v[48:49] op_sel_hi:[1,0] neg_lo:[0,1] neg_hi:[0,1]
	v_pk_add_f32 v[44:45], v[32:33], v[48:49] op_sel_hi:[1,0] neg_lo:[0,1] neg_hi:[0,1]
	v_pk_add_f32 v[34:35], v[24:25], v[48:49] op_sel_hi:[1,0] neg_lo:[0,1] neg_hi:[0,1]
	v_pk_add_f32 v[32:33], v[38:39], v[48:49] op_sel_hi:[1,0] neg_lo:[0,1] neg_hi:[0,1]
	v_pk_add_f32 v[38:39], v[26:27], v[48:49] op_sel_hi:[1,0] neg_lo:[0,1] neg_hi:[0,1]
	v_pk_add_f32 v[36:37], v[36:37], v[48:49] op_sel_hi:[1,0] neg_lo:[0,1] neg_hi:[0,1]
	v_pk_add_f32 v[20:21], v[20:21], v[48:49] op_sel_hi:[1,0] neg_lo:[0,1] neg_hi:[0,1]
	v_pk_add_f32 v[16:17], v[52:53], v[48:49] op_sel_hi:[1,0] neg_lo:[0,1] neg_hi:[0,1]
	v_pk_add_f32 v[28:29], v[22:23], v[48:49] op_sel_hi:[1,0] neg_lo:[0,1] neg_hi:[0,1]
	v_pk_add_f32 v[24:25], v[50:51], v[48:49] op_sel_hi:[1,0] neg_lo:[0,1] neg_hi:[0,1]
	v_pk_add_f32 v[18:19], v[18:19], v[48:49] op_sel_hi:[1,0] neg_lo:[0,1] neg_hi:[0,1]
	v_pk_add_f32 v[22:23], v[58:59], v[48:49] op_sel_hi:[1,0] neg_lo:[0,1] neg_hi:[0,1]
	v_pk_add_f32 v[26:27], v[56:57], v[48:49] op_sel_hi:[1,0] neg_lo:[0,1] neg_hi:[0,1]
	v_pk_add_f32 v[30:31], v[54:55], v[48:49] op_sel_hi:[1,0] neg_lo:[0,1] neg_hi:[0,1]
	v_add_f32_e32 v49, v60, v61
	v_add_f32_e32 v49, v62, v49
	v_pk_mul_f32 v[64:65], v[46:47], v[46:47]
	v_add_f32_e32 v49, v63, v49
	v_add_f32_e32 v49, v64, v49
	v_pk_mul_f32 v[66:67], v[44:45], v[44:45]
	v_add_f32_e32 v49, v65, v49
	v_add_f32_e32 v49, v66, v49
	v_pk_mul_f32 v[68:69], v[34:35], v[34:35]
	v_add_f32_e32 v49, v67, v49
	v_add_f32_e32 v49, v68, v49
	v_pk_mul_f32 v[70:71], v[32:33], v[32:33]
	v_add_f32_e32 v49, v69, v49
	v_add_f32_e32 v49, v70, v49
	v_pk_mul_f32 v[72:73], v[38:39], v[38:39]
	v_add_f32_e32 v49, v71, v49
	v_add_f32_e32 v49, v72, v49
	v_pk_mul_f32 v[74:75], v[36:37], v[36:37]
	v_add_f32_e32 v49, v73, v49
	v_add_f32_e32 v49, v74, v49
	v_pk_mul_f32 v[76:77], v[20:21], v[20:21]
	v_add_f32_e32 v49, v75, v49
	v_add_f32_e32 v49, v76, v49
	v_pk_mul_f32 v[52:53], v[16:17], v[16:17]
	v_add_f32_e32 v49, v77, v49
	v_add_f32_e32 v49, v52, v49
	v_pk_mul_f32 v[78:79], v[28:29], v[28:29]
	v_add_f32_e32 v49, v53, v49
	v_add_f32_e32 v49, v78, v49
	v_pk_mul_f32 v[50:51], v[24:25], v[24:25]
	v_add_f32_e32 v49, v79, v49
	v_add_f32_e32 v49, v50, v49
	v_pk_mul_f32 v[80:81], v[18:19], v[18:19]
	v_add_f32_e32 v49, v51, v49
	v_add_f32_e32 v49, v80, v49
	v_pk_mul_f32 v[58:59], v[22:23], v[22:23]
	v_add_f32_e32 v49, v81, v49
	v_add_f32_e32 v49, v58, v49
	v_pk_mul_f32 v[56:57], v[26:27], v[26:27]
	v_add_f32_e32 v49, v59, v49
	v_add_f32_e32 v49, v56, v49
	v_pk_mul_f32 v[54:55], v[30:31], v[30:31]
	v_add_f32_e32 v49, v57, v49
	v_add_f32_e32 v49, v54, v49
	v_add_f32_e32 v49, v55, v49
	s_nop 1
	v_add_f32_dpp v49, v49, v49 quad_perm:[1,0,3,2] row_mask:0xf bank_mask:0xf bound_ctrl:1
	s_nop 1
	v_add_f32_dpp v49, v49, v49 quad_perm:[2,3,0,1] row_mask:0xf bank_mask:0xf bound_ctrl:1
	s_nop 1
	v_add_f32_dpp v49, v49, v49 row_half_mirror row_mask:0xf bank_mask:0xf bound_ctrl:1
	s_nop 1
	v_add_f32_dpp v49, v49, v49 row_mirror row_mask:0xf bank_mask:0xf bound_ctrl:1
	s_nop 0
	v_readlane_b32 s2, v49, 16
	v_readlane_b32 s0, v49, 0
	s_nop 0
	v_mov_b32_e32 v50, s2
	v_readlane_b32 s2, v49, 48
	v_add_f32_e32 v50, s0, v50
	v_readlane_b32 s0, v49, 32
	v_mov_b32_e32 v49, s2
	s_nop 0
	v_add_f32_e32 v49, s0, v49
	v_add_f32_e32 v49, v50, v49
	v_fmamk_f32 v49, v49, 0x3a000000, v245
	v_cmp_gt_f32_e32 vcc, s87, v49
	v_mul_f32_e32 v50, 0x4f800000, v49
	s_nop 0
	v_cndmask_b32_e32 v49, v49, v50, vcc
	v_sqrt_f32_e32 v50, v49
	s_nop 0
	v_add_u32_e32 v51, -1, v50
	v_fma_f32 v52, -v51, v50, v49
	v_cmp_ge_f32_e64 s[42:43], 0, v52
	v_add_u32_e32 v52, 1, v50
	s_nop 0
	v_cndmask_b32_e64 v51, v50, v51, s[42:43]
	v_fma_f32 v50, -v52, v50, v49
	v_cmp_lt_f32_e64 s[42:43], 0, v50
	s_nop 1
	v_cndmask_b32_e64 v50, v51, v52, s[42:43]
	v_mul_f32_e32 v51, 0x37800000, v50
	v_cndmask_b32_e32 v50, v50, v51, vcc
	v_cmp_class_f32_e32 vcc, v49, v243
	s_nop 1
	v_cndmask_b32_e32 v49, v50, v49, vcc
	v_div_scale_f32 v50, s[2:3], v49, v49, 1.0
	v_rcp_f32_e32 v51, v50
	s_nop 0
	v_fma_f32 v52, -v50, v51, 1.0
	v_fmac_f32_e32 v51, v52, v51
	v_div_scale_f32 v52, vcc, 1.0, v49, 1.0
	v_mul_f32_e32 v53, v52, v51
	v_fma_f32 v54, -v50, v53, v52
	v_fmac_f32_e32 v53, v54, v51
	v_fma_f32 v50, -v50, v53, v52
	v_div_fmas_f32 v50, v50, v51, v53
	v_div_fixup_f32 v50, v50, v49, 1.0
	s_and_saveexec_b64 s[8:9], s[40:41]
	s_cbranch_execz .LBB0_2325
	s_ashr_i32 s45, s44, 31
	s_lshl_b64 s[2:3], s[44:45], 2
	s_add_u32 s2, s12, s2
	v_mov_b32_e32 v49, v50
	s_addc_u32 s3, s13, s3
	global_store_dwordx2 v225, v[48:49], s[2:3] offset:48
.LBB0_2325:
	s_or_b64 exec, exec, s[8:9]
	s_nop 0
	ds_read_b128 v[52:55], v195 offset:16
	ds_read_b128 v[56:59], v195 offset:0
	ds_read_b128 v[60:63], v195 offset:8208
	ds_read_b128 v[64:67], v195 offset:8192
	v_pk_mul_f32 v[40:41], v[40:41], v[50:51] op_sel_hi:[1,0]
	v_pk_mul_f32 v[42:43], v[42:43], v[50:51] op_sel_hi:[1,0]
	v_pk_mul_f32 v[46:47], v[46:47], v[50:51] op_sel_hi:[1,0]
	v_pk_mul_f32 v[44:45], v[44:45], v[50:51] op_sel_hi:[1,0]
	s_mov_b32 s0, 0x16b06000
	v_pk_mul_f32 v[34:35], v[34:35], v[50:51] op_sel_hi:[1,0]
	v_pk_mul_f32 v[38:39], v[38:39], v[50:51] op_sel_hi:[1,0]
	v_pk_mul_f32 v[32:33], v[32:33], v[50:51] op_sel_hi:[1,0]
	v_pk_mul_f32 v[36:37], v[36:37], v[50:51] op_sel_hi:[1,0]
	v_pk_mul_f32 v[20:21], v[20:21], v[50:51] op_sel_hi:[1,0]
	v_pk_mul_f32 v[28:29], v[28:29], v[50:51] op_sel_hi:[1,0]
	v_pk_mul_f32 v[16:17], v[16:17], v[50:51] op_sel_hi:[1,0]
	v_pk_mul_f32 v[24:25], v[24:25], v[50:51] op_sel_hi:[1,0]
	s_waitcnt lgkmcnt(1)
	v_pk_fma_f32 v[46:47], v[46:47], v[52:53], v[60:61]
	s_waitcnt lgkmcnt(0)
	v_pk_fma_f32 v[48:49], v[40:41], v[58:59], v[66:67]
	v_pk_fma_f32 v[42:43], v[42:43], v[56:57], v[64:65]
	v_pk_fma_f32 v[44:45], v[44:45], v[54:55], v[62:63]
	v_cvt_pk_bf16_f32 v41, v48, v49
	v_add_co_u32_e32 v48, vcc, s0, v112
	v_cvt_pk_bf16_f32 v40, v42, v43
	v_cvt_pk_bf16_f32 v42, v46, v47
	v_cvt_pk_bf16_f32 v43, v44, v45
	v_addc_co_u32_e32 v49, vcc, 0, v113, vcc
	global_store_dwordx4 v[48:49], v[40:43], off
	s_nop 0
	ds_read_b128 v[40:43], v195 offset:2064
	s_nop 0
	ds_read_b128 v[44:47], v195 offset:2048
	ds_read_b128 v[52:55], v195 offset:10256
	ds_read_b128 v[56:59], v195 offset:10240
	s_waitcnt lgkmcnt(1)
	v_pk_fma_f32 v[38:39], v[38:39], v[40:41], v[52:53]
	s_waitcnt lgkmcnt(0)
	v_pk_fma_f32 v[34:35], v[34:35], v[44:45], v[56:57]
	v_pk_fma_f32 v[40:41], v[32:33], v[46:47], v[58:59]
	v_pk_fma_f32 v[36:37], v[36:37], v[42:43], v[54:55]
	v_cvt_pk_bf16_f32 v32, v34, v35
	v_cvt_pk_bf16_f32 v33, v40, v41
	v_cvt_pk_bf16_f32 v34, v38, v39
	v_cvt_pk_bf16_f32 v35, v36, v37
	global_store_dwordx4 v[48:49], v[32:35], off offset:1024
	s_nop 0
	ds_read_b128 v[32:35], v195 offset:4112
	s_nop 0
	ds_read_b128 v[36:39], v195 offset:4096
	ds_read_b128 v[40:43], v195 offset:12304
	ds_read_b128 v[44:47], v195 offset:12288
	s_waitcnt lgkmcnt(1)
	v_pk_fma_f32 v[28:29], v[28:29], v[32:33], v[40:41]
	s_waitcnt lgkmcnt(0)
	v_pk_fma_f32 v[20:21], v[20:21], v[36:37], v[44:45]
	v_pk_fma_f32 v[16:17], v[16:17], v[38:39], v[46:47]
	v_pk_fma_f32 v[24:25], v[24:25], v[34:35], v[42:43]
	v_cvt_pk_bf16_f32 v32, v20, v21
	v_cvt_pk_bf16_f32 v33, v16, v17
	v_cvt_pk_bf16_f32 v34, v28, v29
	v_cvt_pk_bf16_f32 v35, v24, v25
	global_store_dwordx4 v[48:49], v[32:35], off offset:2048
	s_nop 0
	ds_read_b128 v[32:35], v195 offset:6160
	s_nop 0
	ds_read_b128 v[36:39], v195 offset:6144
	ds_read_b128 v[40:43], v195 offset:14352
	ds_read_b128 v[44:47], v195 offset:14336
	v_pk_mul_f32 v[16:17], v[18:19], v[50:51] op_sel_hi:[1,0]
	v_pk_mul_f32 v[18:19], v[26:27], v[50:51] op_sel_hi:[1,0]
	v_pk_mul_f32 v[20:21], v[22:23], v[50:51] op_sel_hi:[1,0]
	v_pk_mul_f32 v[22:23], v[30:31], v[50:51] op_sel_hi:[1,0]
	s_waitcnt lgkmcnt(1)
	v_pk_fma_f32 v[18:19], v[18:19], v[32:33], v[40:41]
	s_waitcnt lgkmcnt(0)
	v_pk_fma_f32 v[16:17], v[16:17], v[36:37], v[44:45]
	v_pk_fma_f32 v[20:21], v[20:21], v[38:39], v[46:47]
	v_pk_fma_f32 v[22:23], v[22:23], v[34:35], v[42:43]
	v_cvt_pk_bf16_f32 v16, v16, v17
	v_cvt_pk_bf16_f32 v17, v20, v21
	v_cvt_pk_bf16_f32 v18, v18, v19
	v_cvt_pk_bf16_f32 v19, v22, v23
	global_store_dwordx4 v[48:49], v[16:19], off offset:3072
	s_waitcnt vmcnt(35)
	v_cvt_f32_f16_sdwa v21, v9 dst_sel:DWORD dst_unused:UNUSED_PAD src0_sel:WORD_1
	v_cvt_f32_f16_sdwa v23, v11 dst_sel:DWORD dst_unused:UNUSED_PAD src0_sel:WORD_1
	v_cvt_f32_f16_sdwa v19, v13 dst_sel:DWORD dst_unused:UNUSED_PAD src0_sel:WORD_1
	v_cvt_f32_f16_e32 v18, v13
	v_cvt_f32_f16_sdwa v13, v12 dst_sel:DWORD dst_unused:UNUSED_PAD src0_sel:WORD_1
	v_cvt_f32_f16_e32 v12, v12
	v_cvt_f32_f16_sdwa v17, v15 dst_sel:DWORD dst_unused:UNUSED_PAD src0_sel:WORD_1
	v_cvt_f32_f16_e32 v16, v15
	v_cvt_f32_f16_sdwa v15, v14 dst_sel:DWORD dst_unused:UNUSED_PAD src0_sel:WORD_1
	v_cvt_f32_f16_e32 v14, v14
	v_add_f32_e32 v20, 0, v12
	v_add_f32_e32 v20, v20, v13
	v_add_f32_e32 v20, v20, v18
	v_add_f32_e32 v20, v20, v19
	v_add_f32_e32 v20, v20, v14
	v_add_f32_e32 v20, v20, v15
	v_add_f32_e32 v20, v20, v16
	v_add_f32_e32 v24, v20, v17
	v_cvt_f32_f16_e32 v20, v9
	v_cvt_f32_f16_sdwa v9, v8 dst_sel:DWORD dst_unused:UNUSED_PAD src0_sel:WORD_1
	v_cvt_f32_f16_e32 v8, v8
	v_cvt_f32_f16_e32 v22, v11
	v_cvt_f32_f16_sdwa v11, v10 dst_sel:DWORD dst_unused:UNUSED_PAD src0_sel:WORD_1
	v_cvt_f32_f16_e32 v10, v10
	v_add_f32_e32 v24, v24, v8
	v_add_f32_e32 v24, v24, v9
	v_add_f32_e32 v24, v24, v20
	v_add_f32_e32 v24, v24, v21
	v_add_f32_e32 v24, v24, v10
	v_cvt_f32_f16_sdwa v39, v5 dst_sel:DWORD dst_unused:UNUSED_PAD src0_sel:WORD_1
	v_cvt_f32_f16_e32 v38, v5
	v_cvt_f32_f16_sdwa v5, v4 dst_sel:DWORD dst_unused:UNUSED_PAD src0_sel:WORD_1
	v_cvt_f32_f16_e32 v4, v4
	v_add_f32_e32 v24, v24, v11
	v_add_f32_e32 v24, v24, v22
	v_add_f32_e32 v24, v24, v23
	v_cvt_f32_f16_sdwa v37, v6 dst_sel:DWORD dst_unused:UNUSED_PAD src0_sel:WORD_1
	v_cvt_f32_f16_e32 v36, v6
	v_add_f32_e32 v6, v24, v4
	v_add_f32_e32 v6, v6, v5
	v_cvt_f32_f16_e32 v34, v7
	v_add_f32_e32 v6, v6, v38
	v_cvt_f32_f16_sdwa v35, v7 dst_sel:DWORD dst_unused:UNUSED_PAD src0_sel:WORD_1
	v_add_f32_e32 v6, v6, v39
	v_add_f32_e32 v6, v6, v36
	v_cvt_f32_f16_sdwa v45, v1 dst_sel:DWORD dst_unused:UNUSED_PAD src0_sel:WORD_1
	v_cvt_f32_f16_e32 v44, v1
	v_cvt_f32_f16_sdwa v1, v0 dst_sel:DWORD dst_unused:UNUSED_PAD src0_sel:WORD_1
	v_cvt_f32_f16_e32 v0, v0
	v_add_f32_e32 v6, v6, v37
	v_add_f32_e32 v6, v6, v34
	v_add_f32_e32 v6, v6, v35
	v_cvt_f32_f16_sdwa v43, v2 dst_sel:DWORD dst_unused:UNUSED_PAD src0_sel:WORD_1
	v_cvt_f32_f16_e32 v42, v2
	v_add_f32_e32 v2, v6, v0
	v_add_f32_e32 v2, v2, v1
	v_cvt_f32_f16_e32 v40, v3
	v_add_f32_e32 v2, v2, v44
	v_cvt_f32_f16_sdwa v41, v3 dst_sel:DWORD dst_unused:UNUSED_PAD src0_sel:WORD_1
	v_add_f32_e32 v2, v2, v45
	v_add_f32_e32 v2, v2, v42
	v_add_f32_e32 v2, v2, v43
	v_add_f32_e32 v2, v2, v40
	v_add_f32_e32 v2, v2, v41
	s_nop 1
	v_add_f32_dpp v2, v2, v2 quad_perm:[1,0,3,2] row_mask:0xf bank_mask:0xf bound_ctrl:1
	s_nop 1
	v_add_f32_dpp v2, v2, v2 quad_perm:[2,3,0,1] row_mask:0xf bank_mask:0xf bound_ctrl:1
	s_nop 1
	v_add_f32_dpp v2, v2, v2 row_half_mirror row_mask:0xf bank_mask:0xf bound_ctrl:1
	s_nop 1
	v_add_f32_dpp v2, v2, v2 row_mirror row_mask:0xf bank_mask:0xf bound_ctrl:1
	s_nop 0
	v_readlane_b32 s0, v2, 16
	v_readlane_b32 s7, v2, 48
	v_readlane_b32 s2, v2, 0
	v_readlane_b32 s3, v2, 32
	v_mov_b32_e32 v2, s0
	v_mov_b32_e32 v3, s7
	v_pk_add_f32 v[2:3], s[2:3], v[2:3]
	s_nop 0
	v_add_f32_e32 v2, v2, v3
	v_mul_f32_e32 v28, 0x3a000000, v2
	v_pk_add_f32 v[24:25], v[12:13], v[28:29] op_sel_hi:[1,0] neg_lo:[0,1] neg_hi:[0,1]
	v_pk_add_f32 v[26:27], v[18:19], v[28:29] op_sel_hi:[1,0] neg_lo:[0,1] neg_hi:[0,1]
	v_pk_mul_f32 v[46:47], v[24:25], v[24:25]
	v_pk_mul_f32 v[48:49], v[26:27], v[26:27]
	v_pk_add_f32 v[30:31], v[14:15], v[28:29] op_sel_hi:[1,0] neg_lo:[0,1] neg_hi:[0,1]
	v_pk_add_f32 v[32:33], v[16:17], v[28:29] op_sel_hi:[1,0] neg_lo:[0,1] neg_hi:[0,1]
	v_pk_add_f32 v[12:13], v[8:9], v[28:29] op_sel_hi:[1,0] neg_lo:[0,1] neg_hi:[0,1]
	v_pk_add_f32 v[14:15], v[20:21], v[28:29] op_sel_hi:[1,0] neg_lo:[0,1] neg_hi:[0,1]
	v_pk_add_f32 v[20:21], v[10:11], v[28:29] op_sel_hi:[1,0] neg_lo:[0,1] neg_hi:[0,1]
	v_pk_add_f32 v[22:23], v[22:23], v[28:29] op_sel_hi:[1,0] neg_lo:[0,1] neg_hi:[0,1]
	v_pk_add_f32 v[4:5], v[4:5], v[28:29] op_sel_hi:[1,0] neg_lo:[0,1] neg_hi:[0,1]
	v_pk_add_f32 v[6:7], v[38:39], v[28:29] op_sel_hi:[1,0] neg_lo:[0,1] neg_hi:[0,1]
	v_pk_add_f32 v[16:17], v[36:37], v[28:29] op_sel_hi:[1,0] neg_lo:[0,1] neg_hi:[0,1]
	v_pk_add_f32 v[18:19], v[34:35], v[28:29] op_sel_hi:[1,0] neg_lo:[0,1] neg_hi:[0,1]
	v_pk_add_f32 v[0:1], v[0:1], v[28:29] op_sel_hi:[1,0] neg_lo:[0,1] neg_hi:[0,1]
	v_pk_add_f32 v[2:3], v[44:45], v[28:29] op_sel_hi:[1,0] neg_lo:[0,1] neg_hi:[0,1]
	v_pk_add_f32 v[8:9], v[42:43], v[28:29] op_sel_hi:[1,0] neg_lo:[0,1] neg_hi:[0,1]
	v_pk_add_f32 v[10:11], v[40:41], v[28:29] op_sel_hi:[1,0] neg_lo:[0,1] neg_hi:[0,1]
	v_add_f32_e32 v29, v46, v47
	v_add_f32_e32 v29, v48, v29
	v_pk_mul_f32 v[50:51], v[30:31], v[30:31]
	v_add_f32_e32 v29, v49, v29
	v_add_f32_e32 v29, v50, v29
	v_pk_mul_f32 v[52:53], v[32:33], v[32:33]
	v_add_f32_e32 v29, v51, v29
	v_add_f32_e32 v29, v52, v29
	v_pk_mul_f32 v[54:55], v[12:13], v[12:13]
	v_add_f32_e32 v29, v53, v29
	v_add_f32_e32 v29, v54, v29
	v_pk_mul_f32 v[56:57], v[14:15], v[14:15]
	v_add_f32_e32 v29, v55, v29
	v_add_f32_e32 v29, v56, v29
	v_pk_mul_f32 v[58:59], v[20:21], v[20:21]
	v_add_f32_e32 v29, v57, v29
	v_add_f32_e32 v29, v58, v29
	v_pk_mul_f32 v[60:61], v[22:23], v[22:23]
	v_add_f32_e32 v29, v59, v29
	v_add_f32_e32 v29, v60, v29
	v_pk_mul_f32 v[62:63], v[4:5], v[4:5]
	v_add_f32_e32 v29, v61, v29
	v_add_f32_e32 v29, v62, v29
	v_pk_mul_f32 v[38:39], v[6:7], v[6:7]
	v_add_f32_e32 v29, v63, v29
	v_add_f32_e32 v29, v38, v29
	v_pk_mul_f32 v[36:37], v[16:17], v[16:17]
	v_add_f32_e32 v29, v39, v29
	v_add_f32_e32 v29, v36, v29
	v_pk_mul_f32 v[34:35], v[18:19], v[18:19]
	v_add_f32_e32 v29, v37, v29
	v_add_f32_e32 v29, v34, v29
	v_pk_mul_f32 v[64:65], v[0:1], v[0:1]
	v_add_f32_e32 v29, v35, v29
	v_add_f32_e32 v29, v64, v29
	v_pk_mul_f32 v[44:45], v[2:3], v[2:3]
	v_add_f32_e32 v29, v65, v29
	v_add_f32_e32 v29, v44, v29
	v_pk_mul_f32 v[42:43], v[8:9], v[8:9]
	v_add_f32_e32 v29, v45, v29
	v_add_f32_e32 v29, v42, v29
	v_pk_mul_f32 v[40:41], v[10:11], v[10:11]
	v_add_f32_e32 v29, v43, v29
	v_add_f32_e32 v29, v40, v29
	v_add_f32_e32 v29, v41, v29
	s_nop 1
	v_add_f32_dpp v29, v29, v29 quad_perm:[1,0,3,2] row_mask:0xf bank_mask:0xf bound_ctrl:1
	s_nop 1
	v_add_f32_dpp v29, v29, v29 quad_perm:[2,3,0,1] row_mask:0xf bank_mask:0xf bound_ctrl:1
	s_nop 1
	v_add_f32_dpp v29, v29, v29 row_half_mirror row_mask:0xf bank_mask:0xf bound_ctrl:1
	s_nop 1
	v_add_f32_dpp v29, v29, v29 row_mirror row_mask:0xf bank_mask:0xf bound_ctrl:1
	s_nop 0
	v_readlane_b32 s2, v29, 16
	v_readlane_b32 s0, v29, 0
	s_nop 0
	v_mov_b32_e32 v34, s2
	v_readlane_b32 s2, v29, 48
	v_add_f32_e32 v34, s0, v34
	v_readlane_b32 s0, v29, 32
	v_mov_b32_e32 v29, s2
	s_nop 0
	v_add_f32_e32 v29, s0, v29
	v_add_f32_e32 v29, v34, v29
	v_fmamk_f32 v29, v29, 0x3a000000, v245
	v_cmp_gt_f32_e32 vcc, s87, v29
	v_mul_f32_e32 v34, 0x4f800000, v29
	s_nop 0
	v_cndmask_b32_e32 v29, v29, v34, vcc
	v_sqrt_f32_e32 v34, v29
	s_nop 0
	v_add_u32_e32 v35, -1, v34
	v_fma_f32 v36, -v35, v34, v29
	v_cmp_ge_f32_e64 s[42:43], 0, v36
	v_add_u32_e32 v36, 1, v34
	s_nop 0
	v_cndmask_b32_e64 v35, v34, v35, s[42:43]
	v_fma_f32 v34, -v36, v34, v29
	v_cmp_lt_f32_e64 s[42:43], 0, v34
	s_nop 1
	v_cndmask_b32_e64 v34, v35, v36, s[42:43]
	v_mul_f32_e32 v35, 0x37800000, v34
	v_cndmask_b32_e32 v34, v34, v35, vcc
	v_cmp_class_f32_e32 vcc, v29, v243
	s_nop 1
	v_cndmask_b32_e32 v29, v34, v29, vcc
	v_div_scale_f32 v34, s[2:3], v29, v29, 1.0
	v_rcp_f32_e32 v35, v34
	s_nop 0
	v_fma_f32 v36, -v34, v35, 1.0
	v_fmac_f32_e32 v35, v36, v35
	v_div_scale_f32 v36, vcc, 1.0, v29, 1.0
	v_mul_f32_e32 v37, v36, v35
	v_fma_f32 v38, -v34, v37, v36
	v_fmac_f32_e32 v37, v38, v35
	v_fma_f32 v34, -v34, v37, v36
	v_div_fmas_f32 v34, v34, v35, v37
	v_div_fixup_f32 v34, v34, v29, 1.0
	s_and_saveexec_b64 s[8:9], s[40:41]
	s_cbranch_execz .LBB0_2310
	s_ashr_i32 s45, s44, 31
	s_lshl_b64 s[2:3], s[44:45], 2
	s_add_u32 s2, s12, s2
	v_mov_b32_e32 v29, v34
	s_addc_u32 s3, s13, s3
	global_store_dwordx2 v225, v[28:29], s[2:3] offset:56
	s_branch .LBB0_2310

	.amdhsa_kernel _Z4mega4Args
		.amdhsa_group_segment_fixed_size 0
		.amdhsa_private_segment_fixed_size 0
		.amdhsa_kernarg_size 552
		.amdhsa_user_sgpr_count 2
		.amdhsa_user_sgpr_dispatch_ptr 0
		.amdhsa_user_sgpr_queue_ptr 0
		.amdhsa_user_sgpr_kernarg_segment_ptr 1
		.amdhsa_user_sgpr_dispatch_id 0
		.amdhsa_user_sgpr_kernarg_preload_length 0
		.amdhsa_user_sgpr_kernarg_preload_offset 0
		.amdhsa_user_sgpr_private_segment_size 0
		.amdhsa_uses_dynamic_stack 0
		.amdhsa_enable_private_segment 0
		.amdhsa_system_sgpr_workgroup_id_x 1
		.amdhsa_system_sgpr_workgroup_id_y 0
		.amdhsa_system_sgpr_workgroup_id_z 0
		.amdhsa_system_sgpr_workgroup_info 0
		.amdhsa_system_vgpr_workitem_id 0
		.amdhsa_next_free_vgpr 256
		.amdhsa_next_free_sgpr 102
		.amdhsa_accum_offset 256
		.amdhsa_reserve_vcc 1
		.amdhsa_float_round_mode_32 0
		.amdhsa_float_round_mode_16_64 0
		.amdhsa_float_denorm_mode_32 3
		.amdhsa_float_denorm_mode_16_64 3
		.amdhsa_dx10_clamp 1
		.amdhsa_ieee_mode 1
		.amdhsa_fp16_overflow 0
		.amdhsa_tg_split 0
		.amdhsa_exception_fp_ieee_invalid_op 0
		.amdhsa_exception_fp_denorm_src 0
		.amdhsa_exception_fp_ieee_div_zero 0
		.amdhsa_exception_fp_ieee_overflow 0
		.amdhsa_exception_fp_ieee_underflow 0
		.amdhsa_exception_fp_ieee_inexact 0
		.amdhsa_exception_int_div_zero 0
	.end_amdhsa_kernel

amdhsa.kernels:
  - .agpr_count:     0
    .args:
      - .offset:         0
        .size:           296
        .value_kind:     by_value
      - .offset:         296
        .size:           4
        .value_kind:     hidden_block_count_x
      - .offset:         300
        .size:           4
        .value_kind:     hidden_block_count_y
      - .offset:         304
        .size:           4
        .value_kind:     hidden_block_count_z
      - .offset:         308
        .size:           2
        .value_kind:     hidden_group_size_x
      - .offset:         310
        .size:           2
        .value_kind:     hidden_group_size_y
      - .offset:         312
        .size:           2
        .value_kind:     hidden_group_size_z
      - .offset:         314
        .size:           2
        .value_kind:     hidden_remainder_x
      - .offset:         316
        .size:           2
        .value_kind:     hidden_remainder_y
      - .offset:         318
        .size:           2
        .value_kind:     hidden_remainder_z
      - .offset:         336
        .size:           8
        .value_kind:     hidden_global_offset_x
      - .offset:         344
        .size:           8
        .value_kind:     hidden_global_offset_y
      - .offset:         352
        .size:           8
        .value_kind:     hidden_global_offset_z
      - .offset:         360
        .size:           2
        .value_kind:     hidden_grid_dims
      - .offset:         416
        .size:           4
        .value_kind:     hidden_dynamic_lds_size
    .group_segment_fixed_size: 0
    .kernarg_segment_align: 8
    .kernarg_segment_size: 552
    .language:       OpenCL C
    .language_version:
      - 2
      - 0
    .max_flat_workgroup_size: 512
    .name:           _Z4mega4Args
    .private_segment_fixed_size: 0
    .sgpr_count:     108
    .sgpr_spill_count: 359
    .symbol:         _Z4mega4Args.kd
    .uniform_work_group_size: 1
    .uses_dynamic_stack: false
    .vgpr_count:     256
    .vgpr_spill_count: 0
    .wavefront_size: 64
